# as v2 with the setprio 0/1 pair between the two MFMA blocks of each segment removed
# speedup vs baseline: 1.0077x; 1.0001x over previous
.LBB0_211:
	ds_read_b128 v[228:231], v153
	ds_read_b128 v[162:165], v153 offset:1024
	ds_read_b128 v[224:227], v153 offset:2048
	ds_read_b128 v[166:169], v153 offset:3072
	ds_read_b128 v[220:223], v157
	ds_read_b128 v[174:177], v157 offset:1024
	ds_read_b128 v[216:219], v157 offset:2048
	ds_read_b128 v[178:181], v157 offset:3072
	s_add_u32 s20, s52, 0xfff00080
	s_addc_u32 s21, s53, -1
	s_cmp_eq_u32 s77, 60
	s_cselect_b32 s57, s17, s21
	s_cselect_b32 s56, s41, s20
	s_cselect_b32 s55, s15, s76
	s_cselect_b32 s54, s74, s75
	v_lshl_add_u64 v[144:145], s[52:53], 0, v[140:141]
	s_add_i32 m0, s62, 0xc000
	ds_read_b128 v[182:185], v158
	ds_read_b128 v[186:189], v158 offset:1024
	ds_read_b128 v[190:193], v158 offset:2048
	ds_read_b128 v[194:197], v158 offset:3072
	ds_read_b128 v[198:201], v158 offset:4096
	ds_read_b128 v[202:205], v158 offset:5120
	ds_read_b128 v[206:209], v158 offset:6144
	ds_read_b128 v[210:213], v158 offset:7168
	global_load_lds_dwordx4 v[144:145], off
	v_lshl_add_u64 v[144:145], s[52:53], 0, v[142:143]
	s_add_i32 m0, s62, 0xe000
	s_nop 0
	global_load_lds_dwordx4 v[144:145], off
	s_waitcnt vmcnt(8)
	s_waitcnt lgkmcnt(0)
	s_barrier
	s_setprio 1
	s_waitcnt lgkmcnt(0)
	v_mfma_f32_16x16x32_bf16 v[126:129], v[228:231], v[182:185], v[126:129]
	v_mfma_f32_16x16x32_bf16 v[126:129], v[162:165], v[186:189], v[126:129]
	v_mfma_f32_16x16x32_bf16 v[118:121], v[224:227], v[182:185], v[118:121]
	v_mfma_f32_16x16x32_bf16 v[118:121], v[166:169], v[186:189], v[118:121]
	v_mfma_f32_16x16x32_bf16 v[106:109], v[224:227], v[190:193], v[106:109]
	v_mfma_f32_16x16x32_bf16 v[106:109], v[166:169], v[194:197], v[106:109]
	v_mfma_f32_16x16x32_bf16 v[110:113], v[228:231], v[190:193], v[110:113]
	v_mfma_f32_16x16x32_bf16 v[110:113], v[162:165], v[194:197], v[110:113]
	v_mfma_f32_16x16x32_bf16 v[94:97], v[228:231], v[198:201], v[94:97]
	v_mfma_f32_16x16x32_bf16 v[94:97], v[162:165], v[202:205], v[94:97]
	v_mfma_f32_16x16x32_bf16 v[90:93], v[224:227], v[198:201], v[90:93]
	v_mfma_f32_16x16x32_bf16 v[90:93], v[166:169], v[202:205], v[90:93]
	v_mfma_f32_16x16x32_bf16 v[74:77], v[224:227], v[206:209], v[74:77]
	v_mfma_f32_16x16x32_bf16 v[74:77], v[166:169], v[210:213], v[74:77]
	v_mfma_f32_16x16x32_bf16 v[78:81], v[228:231], v[206:209], v[78:81]
	v_mfma_f32_16x16x32_bf16 v[78:81], v[162:165], v[210:213], v[78:81]
	v_mfma_f32_16x16x32_bf16 v[122:125], v[220:223], v[182:185], v[122:125]
	v_mfma_f32_16x16x32_bf16 v[122:125], v[174:177], v[186:189], v[122:125]
	v_mfma_f32_16x16x32_bf16 v[114:117], v[216:219], v[182:185], v[114:117]
	v_mfma_f32_16x16x32_bf16 v[114:117], v[178:181], v[186:189], v[114:117]
	v_mfma_f32_16x16x32_bf16 v[98:101], v[216:219], v[190:193], v[98:101]
	v_mfma_f32_16x16x32_bf16 v[98:101], v[178:181], v[194:197], v[98:101]
	v_mfma_f32_16x16x32_bf16 v[102:105], v[220:223], v[190:193], v[102:105]
	v_mfma_f32_16x16x32_bf16 v[102:105], v[174:177], v[194:197], v[102:105]
	v_mfma_f32_16x16x32_bf16 v[86:89], v[220:223], v[198:201], v[86:89]
	v_mfma_f32_16x16x32_bf16 v[86:89], v[174:177], v[202:205], v[86:89]
	v_mfma_f32_16x16x32_bf16 v[82:85], v[216:219], v[198:201], v[82:85]
	v_mfma_f32_16x16x32_bf16 v[82:85], v[178:181], v[202:205], v[82:85]
	v_mfma_f32_16x16x32_bf16 v[66:69], v[216:219], v[206:209], v[66:69]
	v_mfma_f32_16x16x32_bf16 v[66:69], v[178:181], v[210:213], v[66:69]
	v_mfma_f32_16x16x32_bf16 v[70:73], v[220:223], v[206:209], v[70:73]
	v_mfma_f32_16x16x32_bf16 v[70:73], v[174:177], v[210:213], v[70:73]
	s_setprio 0
	s_barrier
	s_add_i32 s20, s72, s33
	v_lshl_add_u64 v[144:145], s[54:55], 0, v[132:133]
	s_mov_b32 m0, s20
	ds_read_b128 v[182:185], v158 offset:16384
	ds_read_b128 v[186:189], v158 offset:17408
	ds_read_b128 v[190:193], v158 offset:18432
	ds_read_b128 v[194:197], v158 offset:19456
	ds_read_b128 v[198:201], v158 offset:20480
	ds_read_b128 v[202:205], v158 offset:21504
	ds_read_b128 v[206:209], v158 offset:22528
	ds_read_b128 v[210:213], v158 offset:23552
	global_load_lds_dwordx4 v[144:145], off
	s_add_i32 m0, s20, 0x2000
	s_add_u32 s20, s54, 0x100000
	v_lshl_add_u64 v[160:161], s[54:55], 0, v[136:137]
	s_addc_u32 s21, s55, 0
	s_add_i32 s22, s73, s33
	global_load_lds_dwordx4 v[160:161], off
	v_lshl_add_u64 v[172:173], s[20:21], 0, v[132:133]
	s_mov_b32 m0, s22
	v_lshl_add_u64 v[214:215], s[56:57], 0, v[134:135]
	global_load_lds_dwordx4 v[172:173], off
	v_lshl_add_u64 v[172:173], s[20:21], 0, v[136:137]
	s_add_i32 m0, s22, 0x2000
	s_nop 0
	global_load_lds_dwordx4 v[172:173], off
	v_lshl_add_u64 v[172:173], s[56:57], 0, v[130:131]
	s_mov_b32 m0, s62
	s_nop 0
	global_load_lds_dwordx4 v[172:173], off
	s_mov_b32 m0, s63
	s_nop 0
	global_load_lds_dwordx4 v[214:215], off
	s_waitcnt vmcnt(8)
	s_waitcnt lgkmcnt(0)
	s_barrier
	s_setprio 1
	s_waitcnt lgkmcnt(0)
	v_mfma_f32_16x16x32_bf16 v[62:65], v[228:231], v[182:185], v[62:65]
	v_mfma_f32_16x16x32_bf16 v[62:65], v[162:165], v[186:189], v[62:65]
	v_mfma_f32_16x16x32_bf16 v[58:61], v[224:227], v[182:185], v[58:61]
	v_mfma_f32_16x16x32_bf16 v[58:61], v[166:169], v[186:189], v[58:61]
	v_mfma_f32_16x16x32_bf16 v[42:45], v[224:227], v[190:193], v[42:45]
	v_mfma_f32_16x16x32_bf16 v[42:45], v[166:169], v[194:197], v[42:45]
	v_mfma_f32_16x16x32_bf16 v[50:53], v[228:231], v[190:193], v[50:53]
	v_mfma_f32_16x16x32_bf16 v[50:53], v[162:165], v[194:197], v[50:53]
	v_mfma_f32_16x16x32_bf16 v[34:37], v[228:231], v[198:201], v[34:37]
	v_mfma_f32_16x16x32_bf16 v[34:37], v[162:165], v[202:205], v[34:37]
	v_mfma_f32_16x16x32_bf16 v[26:29], v[224:227], v[198:201], v[26:29]
	v_mfma_f32_16x16x32_bf16 v[26:29], v[166:169], v[202:205], v[26:29]
	v_mfma_f32_16x16x32_bf16 v[6:9], v[224:227], v[206:209], v[6:9]
	v_mfma_f32_16x16x32_bf16 v[6:9], v[166:169], v[210:213], v[6:9]
	v_mfma_f32_16x16x32_bf16 v[14:17], v[228:231], v[206:209], v[14:17]
	v_mfma_f32_16x16x32_bf16 v[14:17], v[162:165], v[210:213], v[14:17]
	v_mfma_f32_16x16x32_bf16 v[54:57], v[220:223], v[182:185], v[54:57]
	v_mfma_f32_16x16x32_bf16 v[54:57], v[174:177], v[186:189], v[54:57]
	v_mfma_f32_16x16x32_bf16 v[46:49], v[216:219], v[182:185], v[46:49]
	v_mfma_f32_16x16x32_bf16 v[46:49], v[178:181], v[186:189], v[46:49]
	v_mfma_f32_16x16x32_bf16 v[30:33], v[216:219], v[190:193], v[30:33]
	v_mfma_f32_16x16x32_bf16 v[30:33], v[178:181], v[194:197], v[30:33]
	v_mfma_f32_16x16x32_bf16 v[38:41], v[220:223], v[190:193], v[38:41]
	v_mfma_f32_16x16x32_bf16 v[38:41], v[174:177], v[194:197], v[38:41]
	v_mfma_f32_16x16x32_bf16 v[22:25], v[220:223], v[198:201], v[22:25]
	v_mfma_f32_16x16x32_bf16 v[22:25], v[174:177], v[202:205], v[22:25]
	v_mfma_f32_16x16x32_bf16 v[18:21], v[216:219], v[198:201], v[18:21]
	v_mfma_f32_16x16x32_bf16 v[18:21], v[178:181], v[202:205], v[18:21]
	v_mfma_f32_16x16x32_bf16 v[2:5], v[216:219], v[206:209], v[2:5]
	v_mfma_f32_16x16x32_bf16 v[2:5], v[178:181], v[210:213], v[2:5]
	v_mfma_f32_16x16x32_bf16 v[10:13], v[220:223], v[206:209], v[10:13]
	v_mfma_f32_16x16x32_bf16 v[10:13], v[174:177], v[210:213], v[10:13]
	s_setprio 0
	s_barrier
	s_add_i32 s22, 0, 0x18000
	v_add_u32_e32 v159, s22, v150
	s_add_i32 s23, 0, 0x1c000
	ds_read_b128 v[228:231], v159
	ds_read_b128 v[162:165], v159 offset:1024
	ds_read_b128 v[224:227], v159 offset:2048
	ds_read_b128 v[166:169], v159 offset:3072
	v_add_u32_e32 v159, s23, v150
	ds_read_b128 v[220:223], v159
	ds_read_b128 v[174:177], v159 offset:1024
	ds_read_b128 v[216:219], v159 offset:2048
	ds_read_b128 v[178:181], v159 offset:3072
	s_add_u32 s20, s56, 0x100000
	s_addc_u32 s21, s57, 0
	s_mov_b32 m0, s64
	v_lshl_add_u64 v[232:233], s[20:21], 0, v[130:131]
	ds_read_b128 v[182:185], v158 offset:32768
	ds_read_b128 v[186:189], v158 offset:33792
	ds_read_b128 v[190:193], v158 offset:34816
	ds_read_b128 v[194:197], v158 offset:35840
	ds_read_b128 v[198:201], v158 offset:36864
	ds_read_b128 v[202:205], v158 offset:37888
	ds_read_b128 v[206:209], v158 offset:38912
	ds_read_b128 v[210:213], v158 offset:39936
	global_load_lds_dwordx4 v[232:233], off
	v_lshl_add_u64 v[232:233], s[20:21], 0, v[134:135]
	s_mov_b32 m0, s65
	s_nop 0
	global_load_lds_dwordx4 v[232:233], off
	s_waitcnt vmcnt(8)
	s_waitcnt lgkmcnt(0)
	s_barrier
	s_setprio 1
	s_waitcnt lgkmcnt(0)
	v_mfma_f32_16x16x32_bf16 v[126:129], v[228:231], v[182:185], v[126:129]
	v_mfma_f32_16x16x32_bf16 v[126:129], v[162:165], v[186:189], v[126:129]
	v_mfma_f32_16x16x32_bf16 v[118:121], v[224:227], v[182:185], v[118:121]
	v_mfma_f32_16x16x32_bf16 v[118:121], v[166:169], v[186:189], v[118:121]
	v_mfma_f32_16x16x32_bf16 v[106:109], v[224:227], v[190:193], v[106:109]
	v_mfma_f32_16x16x32_bf16 v[106:109], v[166:169], v[194:197], v[106:109]
	v_mfma_f32_16x16x32_bf16 v[110:113], v[228:231], v[190:193], v[110:113]
	v_mfma_f32_16x16x32_bf16 v[110:113], v[162:165], v[194:197], v[110:113]
	v_mfma_f32_16x16x32_bf16 v[94:97], v[228:231], v[198:201], v[94:97]
	v_mfma_f32_16x16x32_bf16 v[94:97], v[162:165], v[202:205], v[94:97]
	v_mfma_f32_16x16x32_bf16 v[90:93], v[224:227], v[198:201], v[90:93]
	v_mfma_f32_16x16x32_bf16 v[90:93], v[166:169], v[202:205], v[90:93]
	v_mfma_f32_16x16x32_bf16 v[74:77], v[224:227], v[206:209], v[74:77]
	v_mfma_f32_16x16x32_bf16 v[74:77], v[166:169], v[210:213], v[74:77]
	v_mfma_f32_16x16x32_bf16 v[78:81], v[228:231], v[206:209], v[78:81]
	v_mfma_f32_16x16x32_bf16 v[78:81], v[162:165], v[210:213], v[78:81]
	v_mfma_f32_16x16x32_bf16 v[122:125], v[220:223], v[182:185], v[122:125]
	v_mfma_f32_16x16x32_bf16 v[122:125], v[174:177], v[186:189], v[122:125]
	v_mfma_f32_16x16x32_bf16 v[114:117], v[216:219], v[182:185], v[114:117]
	v_mfma_f32_16x16x32_bf16 v[114:117], v[178:181], v[186:189], v[114:117]
	v_mfma_f32_16x16x32_bf16 v[98:101], v[216:219], v[190:193], v[98:101]
	v_mfma_f32_16x16x32_bf16 v[98:101], v[178:181], v[194:197], v[98:101]
	v_mfma_f32_16x16x32_bf16 v[102:105], v[220:223], v[190:193], v[102:105]
	v_mfma_f32_16x16x32_bf16 v[102:105], v[174:177], v[194:197], v[102:105]
	v_mfma_f32_16x16x32_bf16 v[86:89], v[220:223], v[198:201], v[86:89]
	v_mfma_f32_16x16x32_bf16 v[86:89], v[174:177], v[202:205], v[86:89]
	v_mfma_f32_16x16x32_bf16 v[82:85], v[216:219], v[198:201], v[82:85]
	v_mfma_f32_16x16x32_bf16 v[82:85], v[178:181], v[202:205], v[82:85]
	v_mfma_f32_16x16x32_bf16 v[66:69], v[216:219], v[206:209], v[66:69]
	v_mfma_f32_16x16x32_bf16 v[66:69], v[178:181], v[210:213], v[66:69]
	v_mfma_f32_16x16x32_bf16 v[70:73], v[220:223], v[206:209], v[70:73]
	v_mfma_f32_16x16x32_bf16 v[70:73], v[174:177], v[210:213], v[70:73]
	s_setprio 0
	s_barrier
	s_add_i32 s20, s22, s33
	v_lshl_add_u64 v[144:145], v[144:145], 0, s[8:9]
	s_mov_b32 m0, s20
	ds_read_b128 v[182:185], v158 offset:49152
	ds_read_b128 v[186:189], v158 offset:50176
	ds_read_b128 v[190:193], v158 offset:51200
	ds_read_b128 v[194:197], v158 offset:52224
	ds_read_b128 v[198:201], v158 offset:53248
	ds_read_b128 v[202:205], v158 offset:54272
	ds_read_b128 v[206:209], v158 offset:55296
	ds_read_b128 v[210:213], v158 offset:56320
	global_load_lds_dwordx4 v[144:145], off
	s_add_i32 m0, s20, 0x2000
	s_add_u32 s20, s54, 0x100080
	v_lshl_add_u64 v[144:145], v[160:161], 0, s[8:9]
	s_addc_u32 s21, s55, 0
	s_add_i32 s22, s23, s33
	global_load_lds_dwordx4 v[144:145], off
	v_lshl_add_u64 v[144:145], s[20:21], 0, v[132:133]
	s_mov_b32 m0, s22
	s_nop 0
	global_load_lds_dwordx4 v[144:145], off
	v_lshl_add_u64 v[144:145], s[20:21], 0, v[136:137]
	s_add_i32 m0, s22, 0x2000
	s_nop 0
	global_load_lds_dwordx4 v[144:145], off
	v_lshl_add_u64 v[144:145], v[172:173], 0, s[8:9]
	s_mov_b32 m0, s66
	s_nop 0
	global_load_lds_dwordx4 v[144:145], off
	v_lshl_add_u64 v[144:145], v[214:215], 0, s[8:9]
	s_mov_b32 m0, s67
	s_nop 0
	global_load_lds_dwordx4 v[144:145], off
	s_waitcnt vmcnt(8)
	s_waitcnt lgkmcnt(0)
	s_barrier
	s_setprio 1
	s_waitcnt lgkmcnt(0)
	v_mfma_f32_16x16x32_bf16 v[62:65], v[228:231], v[182:185], v[62:65]
	v_mfma_f32_16x16x32_bf16 v[62:65], v[162:165], v[186:189], v[62:65]
	v_mfma_f32_16x16x32_bf16 v[58:61], v[224:227], v[182:185], v[58:61]
	v_mfma_f32_16x16x32_bf16 v[58:61], v[166:169], v[186:189], v[58:61]
	v_mfma_f32_16x16x32_bf16 v[42:45], v[224:227], v[190:193], v[42:45]
	v_mfma_f32_16x16x32_bf16 v[42:45], v[166:169], v[194:197], v[42:45]
	v_mfma_f32_16x16x32_bf16 v[50:53], v[228:231], v[190:193], v[50:53]
	v_mfma_f32_16x16x32_bf16 v[50:53], v[162:165], v[194:197], v[50:53]
	v_mfma_f32_16x16x32_bf16 v[34:37], v[228:231], v[198:201], v[34:37]
	v_mfma_f32_16x16x32_bf16 v[34:37], v[162:165], v[202:205], v[34:37]
	v_mfma_f32_16x16x32_bf16 v[26:29], v[224:227], v[198:201], v[26:29]
	v_mfma_f32_16x16x32_bf16 v[26:29], v[166:169], v[202:205], v[26:29]
	v_mfma_f32_16x16x32_bf16 v[6:9], v[224:227], v[206:209], v[6:9]
	v_mfma_f32_16x16x32_bf16 v[6:9], v[166:169], v[210:213], v[6:9]
	v_mfma_f32_16x16x32_bf16 v[14:17], v[228:231], v[206:209], v[14:17]
	v_mfma_f32_16x16x32_bf16 v[14:17], v[162:165], v[210:213], v[14:17]
	v_mfma_f32_16x16x32_bf16 v[54:57], v[220:223], v[182:185], v[54:57]
	v_mfma_f32_16x16x32_bf16 v[54:57], v[174:177], v[186:189], v[54:57]
	v_mfma_f32_16x16x32_bf16 v[46:49], v[216:219], v[182:185], v[46:49]
	v_mfma_f32_16x16x32_bf16 v[46:49], v[178:181], v[186:189], v[46:49]
	v_mfma_f32_16x16x32_bf16 v[30:33], v[216:219], v[190:193], v[30:33]
	v_mfma_f32_16x16x32_bf16 v[30:33], v[178:181], v[194:197], v[30:33]
	v_mfma_f32_16x16x32_bf16 v[38:41], v[220:223], v[190:193], v[38:41]
	v_mfma_f32_16x16x32_bf16 v[38:41], v[174:177], v[194:197], v[38:41]
	v_mfma_f32_16x16x32_bf16 v[22:25], v[220:223], v[198:201], v[22:25]
	v_mfma_f32_16x16x32_bf16 v[22:25], v[174:177], v[202:205], v[22:25]
	v_mfma_f32_16x16x32_bf16 v[18:21], v[216:219], v[198:201], v[18:21]
	v_mfma_f32_16x16x32_bf16 v[18:21], v[178:181], v[202:205], v[18:21]
	v_mfma_f32_16x16x32_bf16 v[2:5], v[216:219], v[206:209], v[2:5]
	v_mfma_f32_16x16x32_bf16 v[2:5], v[178:181], v[210:213], v[2:5]
	v_mfma_f32_16x16x32_bf16 v[10:13], v[220:223], v[206:209], v[10:13]
	v_mfma_f32_16x16x32_bf16 v[10:13], v[174:177], v[210:213], v[10:13]
	s_setprio 0
	s_barrier
	s_add_i32 s77, s77, 2
	s_add_u32 s52, s52, 0x100
	s_addc_u32 s53, s53, 0
	s_add_u32 s75, s75, 0x100
	s_addc_u32 s76, s76, 0
	s_cmp_gt_u32 s77, 61
	s_cbranch_scc0 .LBB0_211
	s_and_b64 vcc, exec, s[10:11]
	s_cbranch_vccz .LBB0_214
	s_barrier

.LBB0_232:
	s_add_u32 s20, s2, 0xfff00080
	s_addc_u32 s21, s3, -1
	s_add_i32 s22, 0, 0x10000
	v_add_u32_e32 v168, s22, v143
	ds_read_b128 v[156:159], v168
	ds_read_b128 v[160:163], v168 offset:1024
	ds_read_b128 v[164:167], v168 offset:2048
	ds_read_b128 v[174:177], v168 offset:3072
	ds_read_b128 v[178:181], v172
	ds_read_b128 v[182:185], v172 offset:1024
	ds_read_b128 v[186:189], v172 offset:2048
	ds_read_b128 v[190:193], v172 offset:3072
	s_cmp_eq_u32 s79, 60
	s_cselect_b32 s57, s39, s21
	s_cselect_b32 s56, s58, s20
	s_cselect_b32 s53, s31, s78
	s_cselect_b32 s52, s59, s77
	v_lshl_add_u64 v[168:169], s[2:3], 0, v[152:153]
	s_add_i32 m0, s64, 0xc000
	ds_read_b128 v[194:197], v173
	ds_read_b128 v[198:201], v173 offset:1024
	ds_read_b128 v[202:205], v173 offset:2048
	ds_read_b128 v[206:209], v173 offset:3072
	ds_read_b128 v[210:213], v173 offset:4096
	ds_read_b128 v[214:217], v173 offset:5120
	ds_read_b128 v[218:221], v173 offset:6144
	ds_read_b128 v[222:225], v173 offset:7168
	global_load_lds_dwordx4 v[168:169], off
	v_lshl_add_u64 v[168:169], s[2:3], 0, v[154:155]
	s_add_i32 m0, s64, 0xe000
	s_nop 0
	global_load_lds_dwordx4 v[168:169], off
	s_waitcnt vmcnt(8)
	s_waitcnt lgkmcnt(0)
	s_barrier
	s_setprio 1
	s_waitcnt lgkmcnt(0)
	v_mfma_f32_16x16x32_bf16 v[126:129], v[156:159], v[194:197], v[126:129]
	v_mfma_f32_16x16x32_bf16 v[126:129], v[160:163], v[198:201], v[126:129]
	v_mfma_f32_16x16x32_bf16 v[122:125], v[164:167], v[194:197], v[122:125]
	v_mfma_f32_16x16x32_bf16 v[122:125], v[174:177], v[198:201], v[122:125]
	v_mfma_f32_16x16x32_bf16 v[106:109], v[164:167], v[202:205], v[106:109]
	v_mfma_f32_16x16x32_bf16 v[106:109], v[174:177], v[206:209], v[106:109]
	v_mfma_f32_16x16x32_bf16 v[110:113], v[156:159], v[202:205], v[110:113]
	v_mfma_f32_16x16x32_bf16 v[110:113], v[160:163], v[206:209], v[110:113]
	v_mfma_f32_16x16x32_bf16 v[94:97], v[156:159], v[210:213], v[94:97]
	v_mfma_f32_16x16x32_bf16 v[94:97], v[160:163], v[214:217], v[94:97]
	v_mfma_f32_16x16x32_bf16 v[90:93], v[164:167], v[210:213], v[90:93]
	v_mfma_f32_16x16x32_bf16 v[90:93], v[174:177], v[214:217], v[90:93]
	v_mfma_f32_16x16x32_bf16 v[74:77], v[164:167], v[218:221], v[74:77]
	v_mfma_f32_16x16x32_bf16 v[74:77], v[174:177], v[222:225], v[74:77]
	v_mfma_f32_16x16x32_bf16 v[78:81], v[156:159], v[218:221], v[78:81]
	v_mfma_f32_16x16x32_bf16 v[78:81], v[160:163], v[222:225], v[78:81]
	v_mfma_f32_16x16x32_bf16 v[118:121], v[178:181], v[194:197], v[118:121]
	v_mfma_f32_16x16x32_bf16 v[118:121], v[182:185], v[198:201], v[118:121]
	v_mfma_f32_16x16x32_bf16 v[114:117], v[186:189], v[194:197], v[114:117]
	v_mfma_f32_16x16x32_bf16 v[114:117], v[190:193], v[198:201], v[114:117]
	v_mfma_f32_16x16x32_bf16 v[98:101], v[186:189], v[202:205], v[98:101]
	v_mfma_f32_16x16x32_bf16 v[98:101], v[190:193], v[206:209], v[98:101]
	v_mfma_f32_16x16x32_bf16 v[102:105], v[178:181], v[202:205], v[102:105]
	v_mfma_f32_16x16x32_bf16 v[102:105], v[182:185], v[206:209], v[102:105]
	v_mfma_f32_16x16x32_bf16 v[86:89], v[178:181], v[210:213], v[86:89]
	v_mfma_f32_16x16x32_bf16 v[86:89], v[182:185], v[214:217], v[86:89]
	v_mfma_f32_16x16x32_bf16 v[82:85], v[186:189], v[210:213], v[82:85]
	v_mfma_f32_16x16x32_bf16 v[82:85], v[190:193], v[214:217], v[82:85]
	v_mfma_f32_16x16x32_bf16 v[66:69], v[186:189], v[218:221], v[66:69]
	v_mfma_f32_16x16x32_bf16 v[66:69], v[190:193], v[222:225], v[66:69]
	v_mfma_f32_16x16x32_bf16 v[70:73], v[178:181], v[218:221], v[70:73]
	v_mfma_f32_16x16x32_bf16 v[70:73], v[182:185], v[222:225], v[70:73]
	s_setprio 0
	s_barrier
	s_add_i32 s20, s22, s63
	v_lshl_add_u64 v[168:169], s[52:53], 0, v[132:133]
	s_mov_b32 m0, s20
	ds_read_b128 v[194:197], v173 offset:16384
	ds_read_b128 v[198:201], v173 offset:17408
	ds_read_b128 v[202:205], v173 offset:18432
	ds_read_b128 v[206:209], v173 offset:19456
	ds_read_b128 v[210:213], v173 offset:20480
	ds_read_b128 v[214:217], v173 offset:21504
	ds_read_b128 v[218:221], v173 offset:22528
	ds_read_b128 v[222:225], v173 offset:23552
	global_load_lds_dwordx4 v[168:169], off
	s_add_i32 m0, s20, 0x2000
	s_add_u32 s20, s52, 0x100000
	v_lshl_add_u64 v[226:227], s[52:53], 0, v[136:137]
	s_addc_u32 s21, s53, 0
	s_add_i32 s22, s73, s63
	global_load_lds_dwordx4 v[226:227], off
	v_lshl_add_u64 v[228:229], s[20:21], 0, v[132:133]
	s_mov_b32 m0, s22
	v_lshl_add_u64 v[230:231], s[56:57], 0, v[134:135]
	global_load_lds_dwordx4 v[228:229], off
	v_lshl_add_u64 v[228:229], s[20:21], 0, v[136:137]
	s_add_i32 m0, s22, 0x2000
	s_nop 0
	global_load_lds_dwordx4 v[228:229], off
	v_lshl_add_u64 v[228:229], s[56:57], 0, v[130:131]
	s_mov_b32 m0, s64
	s_nop 0
	global_load_lds_dwordx4 v[228:229], off
	s_mov_b32 m0, s65
	s_nop 0
	global_load_lds_dwordx4 v[230:231], off
	s_waitcnt vmcnt(8)
	s_waitcnt lgkmcnt(0)
	s_barrier
	s_setprio 1
	s_waitcnt lgkmcnt(0)
	v_mfma_f32_16x16x32_bf16 v[62:65], v[156:159], v[194:197], v[62:65]
	v_mfma_f32_16x16x32_bf16 v[62:65], v[160:163], v[198:201], v[62:65]
	v_mfma_f32_16x16x32_bf16 v[58:61], v[164:167], v[194:197], v[58:61]
	v_mfma_f32_16x16x32_bf16 v[58:61], v[174:177], v[198:201], v[58:61]
	v_mfma_f32_16x16x32_bf16 v[42:45], v[164:167], v[202:205], v[42:45]
	v_mfma_f32_16x16x32_bf16 v[42:45], v[174:177], v[206:209], v[42:45]
	v_mfma_f32_16x16x32_bf16 v[46:49], v[156:159], v[202:205], v[46:49]
	v_mfma_f32_16x16x32_bf16 v[46:49], v[160:163], v[206:209], v[46:49]
	v_mfma_f32_16x16x32_bf16 v[30:33], v[156:159], v[210:213], v[30:33]
	v_mfma_f32_16x16x32_bf16 v[30:33], v[160:163], v[214:217], v[30:33]
	v_mfma_f32_16x16x32_bf16 v[26:29], v[164:167], v[210:213], v[26:29]
	v_mfma_f32_16x16x32_bf16 v[26:29], v[174:177], v[214:217], v[26:29]
	v_mfma_f32_16x16x32_bf16 v[10:13], v[164:167], v[218:221], v[10:13]
	v_mfma_f32_16x16x32_bf16 v[10:13], v[174:177], v[222:225], v[10:13]
	v_mfma_f32_16x16x32_bf16 v[14:17], v[156:159], v[218:221], v[14:17]
	v_mfma_f32_16x16x32_bf16 v[14:17], v[160:163], v[222:225], v[14:17]
	v_mfma_f32_16x16x32_bf16 v[54:57], v[178:181], v[194:197], v[54:57]
	v_mfma_f32_16x16x32_bf16 v[54:57], v[182:185], v[198:201], v[54:57]
	v_mfma_f32_16x16x32_bf16 v[50:53], v[186:189], v[194:197], v[50:53]
	v_mfma_f32_16x16x32_bf16 v[50:53], v[190:193], v[198:201], v[50:53]
	v_mfma_f32_16x16x32_bf16 v[34:37], v[186:189], v[202:205], v[34:37]
	v_mfma_f32_16x16x32_bf16 v[34:37], v[190:193], v[206:209], v[34:37]
	v_mfma_f32_16x16x32_bf16 v[38:41], v[178:181], v[202:205], v[38:41]
	v_mfma_f32_16x16x32_bf16 v[38:41], v[182:185], v[206:209], v[38:41]
	v_mfma_f32_16x16x32_bf16 v[22:25], v[178:181], v[210:213], v[22:25]
	v_mfma_f32_16x16x32_bf16 v[22:25], v[182:185], v[214:217], v[22:25]
	v_mfma_f32_16x16x32_bf16 v[18:21], v[186:189], v[210:213], v[18:21]
	v_mfma_f32_16x16x32_bf16 v[18:21], v[190:193], v[214:217], v[18:21]
	v_mfma_f32_16x16x32_bf16 v[2:5], v[186:189], v[218:221], v[2:5]
	v_mfma_f32_16x16x32_bf16 v[2:5], v[190:193], v[222:225], v[2:5]
	v_mfma_f32_16x16x32_bf16 v[6:9], v[178:181], v[218:221], v[6:9]
	v_mfma_f32_16x16x32_bf16 v[6:9], v[182:185], v[222:225], v[6:9]
	s_setprio 0
	s_barrier
	s_add_i32 s22, 0, 0x18000
	s_add_i32 s23, 0, 0x1c000
	v_add_u32_e32 v174, s22, v143
	v_add_u32_e32 v190, s23, v143
	ds_read_b128 v[156:159], v174
	ds_read_b128 v[160:163], v174 offset:1024
	ds_read_b128 v[164:167], v174 offset:2048
	ds_read_b128 v[174:177], v174 offset:3072
	ds_read_b128 v[178:181], v190
	ds_read_b128 v[182:185], v190 offset:1024
	ds_read_b128 v[186:189], v190 offset:2048
	ds_read_b128 v[190:193], v190 offset:3072
	s_add_u32 s20, s56, 0x100000
	s_addc_u32 s21, s57, 0
	s_mov_b32 m0, s66
	v_lshl_add_u64 v[232:233], s[20:21], 0, v[130:131]
	ds_read_b128 v[194:197], v173 offset:32768
	ds_read_b128 v[198:201], v173 offset:33792
	ds_read_b128 v[202:205], v173 offset:34816
	ds_read_b128 v[206:209], v173 offset:35840
	ds_read_b128 v[210:213], v173 offset:36864
	ds_read_b128 v[214:217], v173 offset:37888
	ds_read_b128 v[218:221], v173 offset:38912
	ds_read_b128 v[222:225], v173 offset:39936
	global_load_lds_dwordx4 v[232:233], off
	v_lshl_add_u64 v[232:233], s[20:21], 0, v[134:135]
	s_mov_b32 m0, s67
	s_nop 0
	global_load_lds_dwordx4 v[232:233], off
	s_waitcnt vmcnt(8)
	s_waitcnt lgkmcnt(0)
	s_barrier
	s_setprio 1
	s_waitcnt lgkmcnt(0)
	v_mfma_f32_16x16x32_bf16 v[126:129], v[156:159], v[194:197], v[126:129]
	v_mfma_f32_16x16x32_bf16 v[126:129], v[160:163], v[198:201], v[126:129]
	v_mfma_f32_16x16x32_bf16 v[122:125], v[164:167], v[194:197], v[122:125]
	v_mfma_f32_16x16x32_bf16 v[122:125], v[174:177], v[198:201], v[122:125]
	v_mfma_f32_16x16x32_bf16 v[106:109], v[164:167], v[202:205], v[106:109]
	v_mfma_f32_16x16x32_bf16 v[106:109], v[174:177], v[206:209], v[106:109]
	v_mfma_f32_16x16x32_bf16 v[110:113], v[156:159], v[202:205], v[110:113]
	v_mfma_f32_16x16x32_bf16 v[110:113], v[160:163], v[206:209], v[110:113]
	v_mfma_f32_16x16x32_bf16 v[94:97], v[156:159], v[210:213], v[94:97]
	v_mfma_f32_16x16x32_bf16 v[94:97], v[160:163], v[214:217], v[94:97]
	v_mfma_f32_16x16x32_bf16 v[90:93], v[164:167], v[210:213], v[90:93]
	v_mfma_f32_16x16x32_bf16 v[90:93], v[174:177], v[214:217], v[90:93]
	v_mfma_f32_16x16x32_bf16 v[74:77], v[164:167], v[218:221], v[74:77]
	v_mfma_f32_16x16x32_bf16 v[74:77], v[174:177], v[222:225], v[74:77]
	v_mfma_f32_16x16x32_bf16 v[78:81], v[156:159], v[218:221], v[78:81]
	v_mfma_f32_16x16x32_bf16 v[78:81], v[160:163], v[222:225], v[78:81]
	v_mfma_f32_16x16x32_bf16 v[118:121], v[178:181], v[194:197], v[118:121]
	v_mfma_f32_16x16x32_bf16 v[118:121], v[182:185], v[198:201], v[118:121]
	v_mfma_f32_16x16x32_bf16 v[114:117], v[186:189], v[194:197], v[114:117]
	v_mfma_f32_16x16x32_bf16 v[114:117], v[190:193], v[198:201], v[114:117]
	v_mfma_f32_16x16x32_bf16 v[98:101], v[186:189], v[202:205], v[98:101]
	v_mfma_f32_16x16x32_bf16 v[98:101], v[190:193], v[206:209], v[98:101]
	v_mfma_f32_16x16x32_bf16 v[102:105], v[178:181], v[202:205], v[102:105]
	v_mfma_f32_16x16x32_bf16 v[102:105], v[182:185], v[206:209], v[102:105]
	v_mfma_f32_16x16x32_bf16 v[86:89], v[178:181], v[210:213], v[86:89]
	v_mfma_f32_16x16x32_bf16 v[86:89], v[182:185], v[214:217], v[86:89]
	v_mfma_f32_16x16x32_bf16 v[82:85], v[186:189], v[210:213], v[82:85]
	v_mfma_f32_16x16x32_bf16 v[82:85], v[190:193], v[214:217], v[82:85]
	v_mfma_f32_16x16x32_bf16 v[66:69], v[186:189], v[218:221], v[66:69]
	v_mfma_f32_16x16x32_bf16 v[66:69], v[190:193], v[222:225], v[66:69]
	v_mfma_f32_16x16x32_bf16 v[70:73], v[178:181], v[218:221], v[70:73]
	v_mfma_f32_16x16x32_bf16 v[70:73], v[182:185], v[222:225], v[70:73]
	s_setprio 0
	s_barrier
	s_add_i32 s20, s22, s63
	v_lshl_add_u64 v[168:169], v[168:169], 0, s[14:15]
	s_mov_b32 m0, s20
	ds_read_b128 v[194:197], v173 offset:49152
	ds_read_b128 v[198:201], v173 offset:50176
	ds_read_b128 v[202:205], v173 offset:51200
	ds_read_b128 v[206:209], v173 offset:52224
	ds_read_b128 v[210:213], v173 offset:53248
	ds_read_b128 v[214:217], v173 offset:54272
	ds_read_b128 v[218:221], v173 offset:55296
	ds_read_b128 v[222:225], v173 offset:56320
	global_load_lds_dwordx4 v[168:169], off
	s_add_i32 m0, s20, 0x2000
	s_add_u32 s20, s52, 0x100080
	v_lshl_add_u64 v[168:169], v[226:227], 0, s[14:15]
	s_addc_u32 s21, s53, 0
	s_add_i32 s22, s23, s63
	global_load_lds_dwordx4 v[168:169], off
	v_lshl_add_u64 v[168:169], s[20:21], 0, v[132:133]
	s_mov_b32 m0, s22
	s_nop 0
	global_load_lds_dwordx4 v[168:169], off
	v_lshl_add_u64 v[168:169], s[20:21], 0, v[136:137]
	s_add_i32 m0, s22, 0x2000
	s_nop 0
	global_load_lds_dwordx4 v[168:169], off
	v_lshl_add_u64 v[168:169], v[228:229], 0, s[14:15]
	s_mov_b32 m0, s70
	s_nop 0
	global_load_lds_dwordx4 v[168:169], off
	v_lshl_add_u64 v[168:169], v[230:231], 0, s[14:15]
	s_mov_b32 m0, s71
	s_nop 0
	global_load_lds_dwordx4 v[168:169], off
	s_waitcnt vmcnt(8)
	s_waitcnt lgkmcnt(0)
	s_barrier
	s_setprio 1
	s_waitcnt lgkmcnt(0)
	v_mfma_f32_16x16x32_bf16 v[62:65], v[156:159], v[194:197], v[62:65]
	v_mfma_f32_16x16x32_bf16 v[62:65], v[160:163], v[198:201], v[62:65]
	v_mfma_f32_16x16x32_bf16 v[58:61], v[164:167], v[194:197], v[58:61]
	v_mfma_f32_16x16x32_bf16 v[58:61], v[174:177], v[198:201], v[58:61]
	v_mfma_f32_16x16x32_bf16 v[42:45], v[164:167], v[202:205], v[42:45]
	v_mfma_f32_16x16x32_bf16 v[42:45], v[174:177], v[206:209], v[42:45]
	v_mfma_f32_16x16x32_bf16 v[46:49], v[156:159], v[202:205], v[46:49]
	v_mfma_f32_16x16x32_bf16 v[46:49], v[160:163], v[206:209], v[46:49]
	v_mfma_f32_16x16x32_bf16 v[30:33], v[156:159], v[210:213], v[30:33]
	v_mfma_f32_16x16x32_bf16 v[30:33], v[160:163], v[214:217], v[30:33]
	v_mfma_f32_16x16x32_bf16 v[26:29], v[164:167], v[210:213], v[26:29]
	v_mfma_f32_16x16x32_bf16 v[26:29], v[174:177], v[214:217], v[26:29]
	v_mfma_f32_16x16x32_bf16 v[10:13], v[164:167], v[218:221], v[10:13]
	v_mfma_f32_16x16x32_bf16 v[10:13], v[174:177], v[222:225], v[10:13]
	v_mfma_f32_16x16x32_bf16 v[14:17], v[156:159], v[218:221], v[14:17]
	v_mfma_f32_16x16x32_bf16 v[14:17], v[160:163], v[222:225], v[14:17]
	v_mfma_f32_16x16x32_bf16 v[54:57], v[178:181], v[194:197], v[54:57]
	v_mfma_f32_16x16x32_bf16 v[54:57], v[182:185], v[198:201], v[54:57]
	v_mfma_f32_16x16x32_bf16 v[50:53], v[186:189], v[194:197], v[50:53]
	v_mfma_f32_16x16x32_bf16 v[50:53], v[190:193], v[198:201], v[50:53]
	v_mfma_f32_16x16x32_bf16 v[34:37], v[186:189], v[202:205], v[34:37]
	v_mfma_f32_16x16x32_bf16 v[34:37], v[190:193], v[206:209], v[34:37]
	v_mfma_f32_16x16x32_bf16 v[38:41], v[178:181], v[202:205], v[38:41]
	v_mfma_f32_16x16x32_bf16 v[38:41], v[182:185], v[206:209], v[38:41]
	v_mfma_f32_16x16x32_bf16 v[22:25], v[178:181], v[210:213], v[22:25]
	v_mfma_f32_16x16x32_bf16 v[22:25], v[182:185], v[214:217], v[22:25]
	v_mfma_f32_16x16x32_bf16 v[18:21], v[186:189], v[210:213], v[18:21]
	v_mfma_f32_16x16x32_bf16 v[18:21], v[190:193], v[214:217], v[18:21]
	v_mfma_f32_16x16x32_bf16 v[2:5], v[186:189], v[218:221], v[2:5]
	v_mfma_f32_16x16x32_bf16 v[2:5], v[190:193], v[222:225], v[2:5]
	v_mfma_f32_16x16x32_bf16 v[6:9], v[178:181], v[218:221], v[6:9]
	v_mfma_f32_16x16x32_bf16 v[6:9], v[182:185], v[222:225], v[6:9]
	s_setprio 0
	s_barrier
	s_add_i32 s79, s79, 2
	s_add_u32 s2, s2, 0x100
	s_addc_u32 s3, s3, 0
	s_add_u32 s77, s77, 0x100
	s_addc_u32 s78, s78, 0
	s_cmp_gt_u32 s79, 61
	s_cbranch_scc0 .LBB0_232
	s_and_b64 vcc, exec, s[16:17]
	s_cbranch_vccz .LBB0_235
	s_barrier

.LBB0_402:
	ds_read_b128 v[146:149], v156
	ds_read_b128 v[160:163], v156 offset:1024
	ds_read_b128 v[164:167], v156 offset:2048
	ds_read_b128 v[172:175], v156 offset:3072
	ds_read_b128 v[176:179], v157
	ds_read_b128 v[180:183], v157 offset:1024
	ds_read_b128 v[184:187], v157 offset:2048
	ds_read_b128 v[188:191], v157 offset:3072
	s_add_i32 s79, s58, 2
	s_add_u32 s22, s52, 0xffd50080
	s_addc_u32 s23, s53, -1
	s_cmp_eq_u32 s73, s58
	s_cselect_b32 s58, s68, s77
	s_cselect_b32 s61, s1, s23
	s_cselect_b32 s60, s0, s22
	s_cselect_b32 s59, s69, s78
	v_lshl_add_u64 v[150:151], s[52:53], 0, v[142:143]
	s_add_i32 m0, s87, 0xc000
	ds_read_b128 v[192:195], v158
	ds_read_b128 v[196:199], v158 offset:1024
	ds_read_b128 v[200:203], v158 offset:2048
	ds_read_b128 v[204:207], v158 offset:3072
	ds_read_b128 v[208:211], v158 offset:4096
	ds_read_b128 v[212:215], v158 offset:5120
	ds_read_b128 v[216:219], v158 offset:6144
	ds_read_b128 v[220:223], v158 offset:7168
	global_load_lds_dwordx4 v[150:151], off
	v_lshl_add_u64 v[150:151], s[52:53], 0, v[144:145]
	s_add_i32 m0, s87, 0xe000
	s_nop 0
	global_load_lds_dwordx4 v[150:151], off
	s_waitcnt vmcnt(8)
	s_waitcnt lgkmcnt(0)
	s_barrier
	s_setprio 1
	s_waitcnt lgkmcnt(0)
	v_mfma_f32_16x16x32_bf16 v[126:129], v[146:149], v[192:195], v[126:129]
	v_mfma_f32_16x16x32_bf16 v[126:129], v[160:163], v[196:199], v[126:129]
	v_mfma_f32_16x16x32_bf16 v[122:125], v[164:167], v[192:195], v[122:125]
	v_mfma_f32_16x16x32_bf16 v[122:125], v[172:175], v[196:199], v[122:125]
	v_mfma_f32_16x16x32_bf16 v[114:117], v[164:167], v[200:203], v[114:117]
	v_mfma_f32_16x16x32_bf16 v[114:117], v[172:175], v[204:207], v[114:117]
	v_mfma_f32_16x16x32_bf16 v[118:121], v[146:149], v[200:203], v[118:121]
	v_mfma_f32_16x16x32_bf16 v[118:121], v[160:163], v[204:207], v[118:121]
	v_mfma_f32_16x16x32_bf16 v[110:113], v[146:149], v[208:211], v[110:113]
	v_mfma_f32_16x16x32_bf16 v[110:113], v[160:163], v[212:215], v[110:113]
	v_mfma_f32_16x16x32_bf16 v[106:109], v[164:167], v[208:211], v[106:109]
	v_mfma_f32_16x16x32_bf16 v[106:109], v[172:175], v[212:215], v[106:109]
	v_mfma_f32_16x16x32_bf16 v[98:101], v[164:167], v[216:219], v[98:101]
	v_mfma_f32_16x16x32_bf16 v[98:101], v[172:175], v[220:223], v[98:101]
	v_mfma_f32_16x16x32_bf16 v[102:105], v[146:149], v[216:219], v[102:105]
	v_mfma_f32_16x16x32_bf16 v[102:105], v[160:163], v[220:223], v[102:105]
	v_mfma_f32_16x16x32_bf16 v[94:97], v[176:179], v[192:195], v[94:97]
	v_mfma_f32_16x16x32_bf16 v[94:97], v[180:183], v[196:199], v[94:97]
	v_mfma_f32_16x16x32_bf16 v[90:93], v[184:187], v[192:195], v[90:93]
	v_mfma_f32_16x16x32_bf16 v[90:93], v[188:191], v[196:199], v[90:93]
	v_mfma_f32_16x16x32_bf16 v[82:85], v[184:187], v[200:203], v[82:85]
	v_mfma_f32_16x16x32_bf16 v[82:85], v[188:191], v[204:207], v[82:85]
	v_mfma_f32_16x16x32_bf16 v[86:89], v[176:179], v[200:203], v[86:89]
	v_mfma_f32_16x16x32_bf16 v[86:89], v[180:183], v[204:207], v[86:89]
	v_mfma_f32_16x16x32_bf16 v[78:81], v[176:179], v[208:211], v[78:81]
	v_mfma_f32_16x16x32_bf16 v[78:81], v[180:183], v[212:215], v[78:81]
	v_mfma_f32_16x16x32_bf16 v[74:77], v[184:187], v[208:211], v[74:77]
	v_mfma_f32_16x16x32_bf16 v[74:77], v[188:191], v[212:215], v[74:77]
	v_mfma_f32_16x16x32_bf16 v[66:69], v[184:187], v[216:219], v[66:69]
	v_mfma_f32_16x16x32_bf16 v[66:69], v[188:191], v[220:223], v[66:69]
	v_mfma_f32_16x16x32_bf16 v[70:73], v[176:179], v[216:219], v[70:73]
	v_mfma_f32_16x16x32_bf16 v[70:73], v[180:183], v[220:223], v[70:73]
	s_setprio 0
	s_barrier
	s_add_i32 s22, s17, s66
	v_lshl_add_u64 v[150:151], s[58:59], 0, v[132:133]
	s_mov_b32 m0, s22
	ds_read_b128 v[192:195], v158 offset:16384
	ds_read_b128 v[196:199], v158 offset:17408
	ds_read_b128 v[200:203], v158 offset:18432
	ds_read_b128 v[204:207], v158 offset:19456
	ds_read_b128 v[208:211], v158 offset:20480
	ds_read_b128 v[212:215], v158 offset:21504
	ds_read_b128 v[216:219], v158 offset:22528
	ds_read_b128 v[220:223], v158 offset:23552
	global_load_lds_dwordx4 v[150:151], off
	s_add_i32 m0, s22, 0x2000
	s_add_u32 s22, s58, 0x2b0000
	v_lshl_add_u64 v[168:169], s[58:59], 0, v[136:137]
	s_addc_u32 s23, s59, 0
	s_add_i32 s24, s63, s66
	global_load_lds_dwordx4 v[168:169], off
	v_lshl_add_u64 v[224:225], s[22:23], 0, v[132:133]
	s_mov_b32 m0, s24
	v_lshl_add_u64 v[226:227], s[60:61], 0, v[134:135]
	global_load_lds_dwordx4 v[224:225], off
	v_lshl_add_u64 v[224:225], s[22:23], 0, v[136:137]
	s_add_i32 m0, s24, 0x2000
	s_nop 0
	global_load_lds_dwordx4 v[224:225], off
	v_lshl_add_u64 v[224:225], s[60:61], 0, v[130:131]
	s_mov_b32 m0, s87
	s_nop 0
	global_load_lds_dwordx4 v[224:225], off
	s_mov_b32 m0, s89
	s_nop 0
	global_load_lds_dwordx4 v[226:227], off
	s_waitcnt vmcnt(8)
	s_waitcnt lgkmcnt(0)
	s_barrier
	s_setprio 1
	s_waitcnt lgkmcnt(0)
	v_mfma_f32_16x16x32_bf16 v[62:65], v[146:149], v[192:195], v[62:65]
	v_mfma_f32_16x16x32_bf16 v[62:65], v[160:163], v[196:199], v[62:65]
	v_mfma_f32_16x16x32_bf16 v[58:61], v[164:167], v[192:195], v[58:61]
	v_mfma_f32_16x16x32_bf16 v[58:61], v[172:175], v[196:199], v[58:61]
	v_mfma_f32_16x16x32_bf16 v[50:53], v[164:167], v[200:203], v[50:53]
	v_mfma_f32_16x16x32_bf16 v[50:53], v[172:175], v[204:207], v[50:53]
	v_mfma_f32_16x16x32_bf16 v[54:57], v[146:149], v[200:203], v[54:57]
	v_mfma_f32_16x16x32_bf16 v[54:57], v[160:163], v[204:207], v[54:57]
	v_mfma_f32_16x16x32_bf16 v[46:49], v[146:149], v[208:211], v[46:49]
	v_mfma_f32_16x16x32_bf16 v[46:49], v[160:163], v[212:215], v[46:49]
	v_mfma_f32_16x16x32_bf16 v[42:45], v[164:167], v[208:211], v[42:45]
	v_mfma_f32_16x16x32_bf16 v[42:45], v[172:175], v[212:215], v[42:45]
	v_mfma_f32_16x16x32_bf16 v[34:37], v[164:167], v[216:219], v[34:37]
	v_mfma_f32_16x16x32_bf16 v[34:37], v[172:175], v[220:223], v[34:37]
	v_mfma_f32_16x16x32_bf16 v[38:41], v[146:149], v[216:219], v[38:41]
	v_mfma_f32_16x16x32_bf16 v[38:41], v[160:163], v[220:223], v[38:41]
	v_mfma_f32_16x16x32_bf16 v[30:33], v[176:179], v[192:195], v[30:33]
	v_mfma_f32_16x16x32_bf16 v[30:33], v[180:183], v[196:199], v[30:33]
	v_mfma_f32_16x16x32_bf16 v[26:29], v[184:187], v[192:195], v[26:29]
	v_mfma_f32_16x16x32_bf16 v[26:29], v[188:191], v[196:199], v[26:29]
	v_mfma_f32_16x16x32_bf16 v[18:21], v[184:187], v[200:203], v[18:21]
	v_mfma_f32_16x16x32_bf16 v[18:21], v[188:191], v[204:207], v[18:21]
	v_mfma_f32_16x16x32_bf16 v[22:25], v[176:179], v[200:203], v[22:25]
	v_mfma_f32_16x16x32_bf16 v[22:25], v[180:183], v[204:207], v[22:25]
	v_mfma_f32_16x16x32_bf16 v[14:17], v[176:179], v[208:211], v[14:17]
	v_mfma_f32_16x16x32_bf16 v[14:17], v[180:183], v[212:215], v[14:17]
	v_mfma_f32_16x16x32_bf16 v[10:13], v[184:187], v[208:211], v[10:13]
	v_mfma_f32_16x16x32_bf16 v[10:13], v[188:191], v[212:215], v[10:13]
	v_mfma_f32_16x16x32_bf16 v[2:5], v[184:187], v[216:219], v[2:5]
	v_mfma_f32_16x16x32_bf16 v[2:5], v[188:191], v[220:223], v[2:5]
	v_mfma_f32_16x16x32_bf16 v[6:9], v[176:179], v[216:219], v[6:9]
	v_mfma_f32_16x16x32_bf16 v[6:9], v[180:183], v[220:223], v[6:9]
	s_setprio 0
	s_barrier
	s_add_i32 s24, 0, 0x18000
	v_add_u32_e32 v171, s24, v154
	s_add_i32 s25, 0, 0x1c000
	ds_read_b128 v[146:149], v171
	ds_read_b128 v[160:163], v171 offset:1024
	ds_read_b128 v[164:167], v171 offset:2048
	ds_read_b128 v[172:175], v171 offset:3072
	v_add_u32_e32 v171, s25, v154
	ds_read_b128 v[176:179], v171
	ds_read_b128 v[180:183], v171 offset:1024
	ds_read_b128 v[184:187], v171 offset:2048
	ds_read_b128 v[188:191], v171 offset:3072
	s_add_u32 s22, s60, 0x2b0000
	s_addc_u32 s23, s61, 0
	s_mov_b32 m0, s90
	v_lshl_add_u64 v[228:229], s[22:23], 0, v[130:131]
	ds_read_b128 v[192:195], v158 offset:32768
	ds_read_b128 v[196:199], v158 offset:33792
	ds_read_b128 v[200:203], v158 offset:34816
	ds_read_b128 v[204:207], v158 offset:35840
	ds_read_b128 v[208:211], v158 offset:36864
	ds_read_b128 v[212:215], v158 offset:37888
	ds_read_b128 v[216:219], v158 offset:38912
	ds_read_b128 v[220:223], v158 offset:39936
	global_load_lds_dwordx4 v[228:229], off
	v_lshl_add_u64 v[228:229], s[22:23], 0, v[134:135]
	s_mov_b32 m0, s91
	s_nop 0
	global_load_lds_dwordx4 v[228:229], off
	s_waitcnt vmcnt(8)
	s_waitcnt lgkmcnt(0)
	s_barrier
	s_setprio 1
	s_waitcnt lgkmcnt(0)
	v_mfma_f32_16x16x32_bf16 v[126:129], v[146:149], v[192:195], v[126:129]
	v_mfma_f32_16x16x32_bf16 v[126:129], v[160:163], v[196:199], v[126:129]
	v_mfma_f32_16x16x32_bf16 v[122:125], v[164:167], v[192:195], v[122:125]
	v_mfma_f32_16x16x32_bf16 v[122:125], v[172:175], v[196:199], v[122:125]
	v_mfma_f32_16x16x32_bf16 v[114:117], v[164:167], v[200:203], v[114:117]
	v_mfma_f32_16x16x32_bf16 v[114:117], v[172:175], v[204:207], v[114:117]
	v_mfma_f32_16x16x32_bf16 v[118:121], v[146:149], v[200:203], v[118:121]
	v_mfma_f32_16x16x32_bf16 v[118:121], v[160:163], v[204:207], v[118:121]
	v_mfma_f32_16x16x32_bf16 v[110:113], v[146:149], v[208:211], v[110:113]
	v_mfma_f32_16x16x32_bf16 v[110:113], v[160:163], v[212:215], v[110:113]
	v_mfma_f32_16x16x32_bf16 v[106:109], v[164:167], v[208:211], v[106:109]
	v_mfma_f32_16x16x32_bf16 v[106:109], v[172:175], v[212:215], v[106:109]
	v_mfma_f32_16x16x32_bf16 v[98:101], v[164:167], v[216:219], v[98:101]
	v_mfma_f32_16x16x32_bf16 v[98:101], v[172:175], v[220:223], v[98:101]
	v_mfma_f32_16x16x32_bf16 v[102:105], v[146:149], v[216:219], v[102:105]
	v_mfma_f32_16x16x32_bf16 v[102:105], v[160:163], v[220:223], v[102:105]
	v_mfma_f32_16x16x32_bf16 v[94:97], v[176:179], v[192:195], v[94:97]
	v_mfma_f32_16x16x32_bf16 v[94:97], v[180:183], v[196:199], v[94:97]
	v_mfma_f32_16x16x32_bf16 v[90:93], v[184:187], v[192:195], v[90:93]
	v_mfma_f32_16x16x32_bf16 v[90:93], v[188:191], v[196:199], v[90:93]
	v_mfma_f32_16x16x32_bf16 v[82:85], v[184:187], v[200:203], v[82:85]
	v_mfma_f32_16x16x32_bf16 v[82:85], v[188:191], v[204:207], v[82:85]
	v_mfma_f32_16x16x32_bf16 v[86:89], v[176:179], v[200:203], v[86:89]
	v_mfma_f32_16x16x32_bf16 v[86:89], v[180:183], v[204:207], v[86:89]
	v_mfma_f32_16x16x32_bf16 v[78:81], v[176:179], v[208:211], v[78:81]
	v_mfma_f32_16x16x32_bf16 v[78:81], v[180:183], v[212:215], v[78:81]
	v_mfma_f32_16x16x32_bf16 v[74:77], v[184:187], v[208:211], v[74:77]
	v_mfma_f32_16x16x32_bf16 v[74:77], v[188:191], v[212:215], v[74:77]
	v_mfma_f32_16x16x32_bf16 v[66:69], v[184:187], v[216:219], v[66:69]
	v_mfma_f32_16x16x32_bf16 v[66:69], v[188:191], v[220:223], v[66:69]
	v_mfma_f32_16x16x32_bf16 v[70:73], v[176:179], v[216:219], v[70:73]
	v_mfma_f32_16x16x32_bf16 v[70:73], v[180:183], v[220:223], v[70:73]
	s_setprio 0
	s_barrier
	s_add_i32 s22, s24, s66
	v_lshl_add_u64 v[150:151], v[150:151], 0, s[38:39]
	s_mov_b32 m0, s22
	ds_read_b128 v[192:195], v158 offset:49152
	ds_read_b128 v[196:199], v158 offset:50176
	ds_read_b128 v[200:203], v158 offset:51200
	ds_read_b128 v[204:207], v158 offset:52224
	ds_read_b128 v[208:211], v158 offset:53248
	ds_read_b128 v[212:215], v158 offset:54272
	ds_read_b128 v[216:219], v158 offset:55296
	ds_read_b128 v[220:223], v158 offset:56320
	global_load_lds_dwordx4 v[150:151], off
	s_add_i32 m0, s22, 0x2000
	s_add_u32 s22, s58, 0x2b0080
	v_lshl_add_u64 v[150:151], v[168:169], 0, s[38:39]
	s_addc_u32 s23, s59, 0
	s_add_i32 s24, s25, s66
	global_load_lds_dwordx4 v[150:151], off
	v_lshl_add_u64 v[150:151], s[22:23], 0, v[132:133]
	s_mov_b32 m0, s24
	s_nop 0
	global_load_lds_dwordx4 v[150:151], off
	v_lshl_add_u64 v[150:151], s[22:23], 0, v[136:137]
	s_add_i32 m0, s24, 0x2000
	s_nop 0
	global_load_lds_dwordx4 v[150:151], off
	v_lshl_add_u64 v[150:151], v[224:225], 0, s[38:39]
	s_mov_b32 m0, s14
	s_nop 0
	global_load_lds_dwordx4 v[150:151], off
	v_lshl_add_u64 v[150:151], v[226:227], 0, s[38:39]
	s_mov_b32 m0, s15
	s_nop 0
	global_load_lds_dwordx4 v[150:151], off
	s_waitcnt vmcnt(8)
	s_waitcnt lgkmcnt(0)
	s_barrier
	s_setprio 1
	s_waitcnt lgkmcnt(0)
	v_mfma_f32_16x16x32_bf16 v[62:65], v[146:149], v[192:195], v[62:65]
	v_mfma_f32_16x16x32_bf16 v[62:65], v[160:163], v[196:199], v[62:65]
	v_mfma_f32_16x16x32_bf16 v[58:61], v[164:167], v[192:195], v[58:61]
	v_mfma_f32_16x16x32_bf16 v[58:61], v[172:175], v[196:199], v[58:61]
	v_mfma_f32_16x16x32_bf16 v[50:53], v[164:167], v[200:203], v[50:53]
	v_mfma_f32_16x16x32_bf16 v[50:53], v[172:175], v[204:207], v[50:53]
	v_mfma_f32_16x16x32_bf16 v[54:57], v[146:149], v[200:203], v[54:57]
	v_mfma_f32_16x16x32_bf16 v[54:57], v[160:163], v[204:207], v[54:57]
	v_mfma_f32_16x16x32_bf16 v[46:49], v[146:149], v[208:211], v[46:49]
	v_mfma_f32_16x16x32_bf16 v[46:49], v[160:163], v[212:215], v[46:49]
	v_mfma_f32_16x16x32_bf16 v[42:45], v[164:167], v[208:211], v[42:45]
	v_mfma_f32_16x16x32_bf16 v[42:45], v[172:175], v[212:215], v[42:45]
	v_mfma_f32_16x16x32_bf16 v[34:37], v[164:167], v[216:219], v[34:37]
	v_mfma_f32_16x16x32_bf16 v[34:37], v[172:175], v[220:223], v[34:37]
	v_mfma_f32_16x16x32_bf16 v[38:41], v[146:149], v[216:219], v[38:41]
	v_mfma_f32_16x16x32_bf16 v[38:41], v[160:163], v[220:223], v[38:41]
	v_mfma_f32_16x16x32_bf16 v[30:33], v[176:179], v[192:195], v[30:33]
	v_mfma_f32_16x16x32_bf16 v[30:33], v[180:183], v[196:199], v[30:33]
	v_mfma_f32_16x16x32_bf16 v[26:29], v[184:187], v[192:195], v[26:29]
	v_mfma_f32_16x16x32_bf16 v[26:29], v[188:191], v[196:199], v[26:29]
	v_mfma_f32_16x16x32_bf16 v[18:21], v[184:187], v[200:203], v[18:21]
	v_mfma_f32_16x16x32_bf16 v[18:21], v[188:191], v[204:207], v[18:21]
	v_mfma_f32_16x16x32_bf16 v[22:25], v[176:179], v[200:203], v[22:25]
	v_mfma_f32_16x16x32_bf16 v[22:25], v[180:183], v[204:207], v[22:25]
	v_mfma_f32_16x16x32_bf16 v[14:17], v[176:179], v[208:211], v[14:17]
	v_mfma_f32_16x16x32_bf16 v[14:17], v[180:183], v[212:215], v[14:17]
	v_mfma_f32_16x16x32_bf16 v[10:13], v[184:187], v[208:211], v[10:13]
	v_mfma_f32_16x16x32_bf16 v[10:13], v[188:191], v[212:215], v[10:13]
	v_mfma_f32_16x16x32_bf16 v[2:5], v[184:187], v[216:219], v[2:5]
	v_mfma_f32_16x16x32_bf16 v[2:5], v[188:191], v[220:223], v[2:5]
	v_mfma_f32_16x16x32_bf16 v[6:9], v[176:179], v[216:219], v[6:9]
	v_mfma_f32_16x16x32_bf16 v[6:9], v[180:183], v[220:223], v[6:9]
	s_setprio 0
	s_barrier
	s_add_u32 s52, s52, 0x100
	s_addc_u32 s53, s53, 0
	s_add_u32 s77, s77, 0x100
	s_addc_u32 s78, s78, 0
	s_cmp_ge_i32 s79, s76
	s_mov_b32 s58, s79
	s_cbranch_scc0 .LBB0_402
	s_and_b64 vcc, exec, s[40:41]
	s_cbranch_vccz .LBB0_405

.LBB0_649:
	ds_read_b128 v[146:149], v161
	ds_read_b128 v[150:153], v161 offset:1024
	ds_read_b128 v[164:167], v161 offset:2048
	ds_read_b128 v[168:171], v161 offset:3072
	ds_read_b128 v[172:175], v162
	ds_read_b128 v[176:179], v162 offset:1024
	ds_read_b128 v[180:183], v162 offset:2048
	ds_read_b128 v[184:187], v162 offset:3072
	s_add_u32 s8, s4, 0xfff00080
	s_addc_u32 s9, s5, -1
	s_cmp_eq_u32 s57, 60
	s_cselect_b32 s53, s1, s9
	s_cselect_b32 s52, s7, s8
	s_cselect_b32 s9, s11, s55
	s_cselect_b32 s8, s12, s33
	v_lshl_add_u64 v[154:155], s[4:5], 0, v[142:143]
	s_add_i32 m0, s64, 0xc000
	ds_read_b128 v[188:191], v163
	ds_read_b128 v[192:195], v163 offset:1024
	ds_read_b128 v[196:199], v163 offset:2048
	ds_read_b128 v[200:203], v163 offset:3072
	ds_read_b128 v[206:209], v163 offset:4096
	ds_read_b128 v[210:213], v163 offset:5120
	ds_read_b128 v[214:217], v163 offset:6144
	ds_read_b128 v[218:221], v163 offset:7168
	global_load_lds_dwordx4 v[154:155], off
	v_lshl_add_u64 v[154:155], s[4:5], 0, v[144:145]
	s_add_i32 m0, s64, 0xe000
	s_nop 0
	global_load_lds_dwordx4 v[154:155], off
	s_waitcnt vmcnt(8)
	s_waitcnt lgkmcnt(0)
	s_barrier
	s_setprio 1
	s_waitcnt lgkmcnt(0)
	v_mfma_f32_16x16x32_bf16 v[126:129], v[146:149], v[188:191], v[126:129]
	v_mfma_f32_16x16x32_bf16 v[126:129], v[150:153], v[192:195], v[126:129]
	v_mfma_f32_16x16x32_bf16 v[122:125], v[164:167], v[188:191], v[122:125]
	v_mfma_f32_16x16x32_bf16 v[122:125], v[168:171], v[192:195], v[122:125]
	v_mfma_f32_16x16x32_bf16 v[106:109], v[164:167], v[196:199], v[106:109]
	v_mfma_f32_16x16x32_bf16 v[106:109], v[168:171], v[200:203], v[106:109]
	v_mfma_f32_16x16x32_bf16 v[110:113], v[146:149], v[196:199], v[110:113]
	v_mfma_f32_16x16x32_bf16 v[110:113], v[150:153], v[200:203], v[110:113]
	v_mfma_f32_16x16x32_bf16 v[94:97], v[146:149], v[206:209], v[94:97]
	v_mfma_f32_16x16x32_bf16 v[94:97], v[150:153], v[210:213], v[94:97]
	v_mfma_f32_16x16x32_bf16 v[90:93], v[164:167], v[206:209], v[90:93]
	v_mfma_f32_16x16x32_bf16 v[90:93], v[168:171], v[210:213], v[90:93]
	v_mfma_f32_16x16x32_bf16 v[74:77], v[164:167], v[214:217], v[74:77]
	v_mfma_f32_16x16x32_bf16 v[74:77], v[168:171], v[218:221], v[74:77]
	v_mfma_f32_16x16x32_bf16 v[78:81], v[146:149], v[214:217], v[78:81]
	v_mfma_f32_16x16x32_bf16 v[78:81], v[150:153], v[218:221], v[78:81]
	v_mfma_f32_16x16x32_bf16 v[118:121], v[172:175], v[188:191], v[118:121]
	v_mfma_f32_16x16x32_bf16 v[118:121], v[176:179], v[192:195], v[118:121]
	v_mfma_f32_16x16x32_bf16 v[114:117], v[180:183], v[188:191], v[114:117]
	v_mfma_f32_16x16x32_bf16 v[114:117], v[184:187], v[192:195], v[114:117]
	v_mfma_f32_16x16x32_bf16 v[98:101], v[180:183], v[196:199], v[98:101]
	v_mfma_f32_16x16x32_bf16 v[98:101], v[184:187], v[200:203], v[98:101]
	v_mfma_f32_16x16x32_bf16 v[102:105], v[172:175], v[196:199], v[102:105]
	v_mfma_f32_16x16x32_bf16 v[102:105], v[176:179], v[200:203], v[102:105]
	v_mfma_f32_16x16x32_bf16 v[86:89], v[172:175], v[206:209], v[86:89]
	v_mfma_f32_16x16x32_bf16 v[86:89], v[176:179], v[210:213], v[86:89]
	v_mfma_f32_16x16x32_bf16 v[82:85], v[180:183], v[206:209], v[82:85]
	v_mfma_f32_16x16x32_bf16 v[82:85], v[184:187], v[210:213], v[82:85]
	v_mfma_f32_16x16x32_bf16 v[66:69], v[180:183], v[214:217], v[66:69]
	v_mfma_f32_16x16x32_bf16 v[66:69], v[184:187], v[218:221], v[66:69]
	v_mfma_f32_16x16x32_bf16 v[70:73], v[172:175], v[214:217], v[70:73]
	v_mfma_f32_16x16x32_bf16 v[70:73], v[176:179], v[218:221], v[70:73]
	s_setprio 0
	s_barrier
	s_add_i32 s26, s86, s59
	v_lshl_add_u64 v[154:155], s[8:9], 0, v[132:133]
	s_mov_b32 m0, s26
	ds_read_b128 v[188:191], v163 offset:16384
	ds_read_b128 v[192:195], v163 offset:17408
	ds_read_b128 v[196:199], v163 offset:18432
	ds_read_b128 v[200:203], v163 offset:19456
	ds_read_b128 v[206:209], v163 offset:20480
	ds_read_b128 v[210:213], v163 offset:21504
	ds_read_b128 v[214:217], v163 offset:22528
	ds_read_b128 v[218:221], v163 offset:23552
	global_load_lds_dwordx4 v[154:155], off
	s_add_i32 m0, s26, 0x2000
	s_add_u32 s26, s8, 0x100000
	v_lshl_add_u64 v[222:223], s[8:9], 0, v[136:137]
	s_addc_u32 s27, s9, 0
	s_add_i32 s28, s87, s59
	global_load_lds_dwordx4 v[222:223], off
	v_lshl_add_u64 v[224:225], s[26:27], 0, v[132:133]
	s_mov_b32 m0, s28
	v_lshl_add_u64 v[226:227], s[52:53], 0, v[134:135]
	global_load_lds_dwordx4 v[224:225], off
	v_lshl_add_u64 v[224:225], s[26:27], 0, v[136:137]
	s_add_i32 m0, s28, 0x2000
	s_nop 0
	global_load_lds_dwordx4 v[224:225], off
	v_lshl_add_u64 v[224:225], s[52:53], 0, v[130:131]
	s_mov_b32 m0, s64
	s_nop 0
	global_load_lds_dwordx4 v[224:225], off
	s_mov_b32 m0, s65
	s_nop 0
	global_load_lds_dwordx4 v[226:227], off
	s_waitcnt vmcnt(8)
	s_waitcnt lgkmcnt(0)
	s_barrier
	s_setprio 1
	s_waitcnt lgkmcnt(0)
	v_mfma_f32_16x16x32_bf16 v[62:65], v[146:149], v[188:191], v[62:65]
	v_mfma_f32_16x16x32_bf16 v[62:65], v[150:153], v[192:195], v[62:65]
	v_mfma_f32_16x16x32_bf16 v[58:61], v[164:167], v[188:191], v[58:61]
	v_mfma_f32_16x16x32_bf16 v[58:61], v[168:171], v[192:195], v[58:61]
	v_mfma_f32_16x16x32_bf16 v[42:45], v[164:167], v[196:199], v[42:45]
	v_mfma_f32_16x16x32_bf16 v[42:45], v[168:171], v[200:203], v[42:45]
	v_mfma_f32_16x16x32_bf16 v[46:49], v[146:149], v[196:199], v[46:49]
	v_mfma_f32_16x16x32_bf16 v[46:49], v[150:153], v[200:203], v[46:49]
	v_mfma_f32_16x16x32_bf16 v[30:33], v[146:149], v[206:209], v[30:33]
	v_mfma_f32_16x16x32_bf16 v[30:33], v[150:153], v[210:213], v[30:33]
	v_mfma_f32_16x16x32_bf16 v[26:29], v[164:167], v[206:209], v[26:29]
	v_mfma_f32_16x16x32_bf16 v[26:29], v[168:171], v[210:213], v[26:29]
	v_mfma_f32_16x16x32_bf16 v[10:13], v[164:167], v[214:217], v[10:13]
	v_mfma_f32_16x16x32_bf16 v[10:13], v[168:171], v[218:221], v[10:13]
	v_mfma_f32_16x16x32_bf16 v[14:17], v[146:149], v[214:217], v[14:17]
	v_mfma_f32_16x16x32_bf16 v[14:17], v[150:153], v[218:221], v[14:17]
	v_mfma_f32_16x16x32_bf16 v[54:57], v[172:175], v[188:191], v[54:57]
	v_mfma_f32_16x16x32_bf16 v[54:57], v[176:179], v[192:195], v[54:57]
	v_mfma_f32_16x16x32_bf16 v[50:53], v[180:183], v[188:191], v[50:53]
	v_mfma_f32_16x16x32_bf16 v[50:53], v[184:187], v[192:195], v[50:53]
	v_mfma_f32_16x16x32_bf16 v[34:37], v[180:183], v[196:199], v[34:37]
	v_mfma_f32_16x16x32_bf16 v[34:37], v[184:187], v[200:203], v[34:37]
	v_mfma_f32_16x16x32_bf16 v[38:41], v[172:175], v[196:199], v[38:41]
	v_mfma_f32_16x16x32_bf16 v[38:41], v[176:179], v[200:203], v[38:41]
	v_mfma_f32_16x16x32_bf16 v[22:25], v[172:175], v[206:209], v[22:25]
	v_mfma_f32_16x16x32_bf16 v[22:25], v[176:179], v[210:213], v[22:25]
	v_mfma_f32_16x16x32_bf16 v[18:21], v[180:183], v[206:209], v[18:21]
	v_mfma_f32_16x16x32_bf16 v[18:21], v[184:187], v[210:213], v[18:21]
	v_mfma_f32_16x16x32_bf16 v[2:5], v[180:183], v[214:217], v[2:5]
	v_mfma_f32_16x16x32_bf16 v[2:5], v[184:187], v[218:221], v[2:5]
	v_mfma_f32_16x16x32_bf16 v[6:9], v[172:175], v[214:217], v[6:9]
	v_mfma_f32_16x16x32_bf16 v[6:9], v[176:179], v[218:221], v[6:9]
	s_setprio 0
	s_barrier
	s_add_i32 s28, 0, 0x18000
	v_add_u32_e32 v140, s28, v156
	s_add_i32 s29, 0, 0x1c000
	ds_read_b128 v[146:149], v140
	ds_read_b128 v[150:153], v140 offset:1024
	ds_read_b128 v[164:167], v140 offset:2048
	ds_read_b128 v[168:171], v140 offset:3072
	v_add_u32_e32 v140, s29, v156
	ds_read_b128 v[172:175], v140
	ds_read_b128 v[176:179], v140 offset:1024
	ds_read_b128 v[180:183], v140 offset:2048
	ds_read_b128 v[184:187], v140 offset:3072
	s_add_u32 s26, s52, 0x100000
	s_addc_u32 s27, s53, 0
	s_mov_b32 m0, s66
	v_lshl_add_u64 v[228:229], s[26:27], 0, v[130:131]
	ds_read_b128 v[188:191], v163 offset:32768
	ds_read_b128 v[192:195], v163 offset:33792
	ds_read_b128 v[196:199], v163 offset:34816
	ds_read_b128 v[200:203], v163 offset:35840
	ds_read_b128 v[206:209], v163 offset:36864
	ds_read_b128 v[210:213], v163 offset:37888
	ds_read_b128 v[214:217], v163 offset:38912
	ds_read_b128 v[218:221], v163 offset:39936
	global_load_lds_dwordx4 v[228:229], off
	v_lshl_add_u64 v[228:229], s[26:27], 0, v[134:135]
	s_mov_b32 m0, s67
	s_nop 0
	global_load_lds_dwordx4 v[228:229], off
	s_waitcnt vmcnt(8)
	s_waitcnt lgkmcnt(0)
	s_barrier
	s_setprio 1
	s_waitcnt lgkmcnt(0)
	v_mfma_f32_16x16x32_bf16 v[126:129], v[146:149], v[188:191], v[126:129]
	v_mfma_f32_16x16x32_bf16 v[126:129], v[150:153], v[192:195], v[126:129]
	v_mfma_f32_16x16x32_bf16 v[122:125], v[164:167], v[188:191], v[122:125]
	v_mfma_f32_16x16x32_bf16 v[122:125], v[168:171], v[192:195], v[122:125]
	v_mfma_f32_16x16x32_bf16 v[106:109], v[164:167], v[196:199], v[106:109]
	v_mfma_f32_16x16x32_bf16 v[106:109], v[168:171], v[200:203], v[106:109]
	v_mfma_f32_16x16x32_bf16 v[110:113], v[146:149], v[196:199], v[110:113]
	v_mfma_f32_16x16x32_bf16 v[110:113], v[150:153], v[200:203], v[110:113]
	v_mfma_f32_16x16x32_bf16 v[94:97], v[146:149], v[206:209], v[94:97]
	v_mfma_f32_16x16x32_bf16 v[94:97], v[150:153], v[210:213], v[94:97]
	v_mfma_f32_16x16x32_bf16 v[90:93], v[164:167], v[206:209], v[90:93]
	v_mfma_f32_16x16x32_bf16 v[90:93], v[168:171], v[210:213], v[90:93]
	v_mfma_f32_16x16x32_bf16 v[74:77], v[164:167], v[214:217], v[74:77]
	v_mfma_f32_16x16x32_bf16 v[74:77], v[168:171], v[218:221], v[74:77]
	v_mfma_f32_16x16x32_bf16 v[78:81], v[146:149], v[214:217], v[78:81]
	v_mfma_f32_16x16x32_bf16 v[78:81], v[150:153], v[218:221], v[78:81]
	v_mfma_f32_16x16x32_bf16 v[118:121], v[172:175], v[188:191], v[118:121]
	v_mfma_f32_16x16x32_bf16 v[118:121], v[176:179], v[192:195], v[118:121]
	v_mfma_f32_16x16x32_bf16 v[114:117], v[180:183], v[188:191], v[114:117]
	v_mfma_f32_16x16x32_bf16 v[114:117], v[184:187], v[192:195], v[114:117]
	v_mfma_f32_16x16x32_bf16 v[98:101], v[180:183], v[196:199], v[98:101]
	v_mfma_f32_16x16x32_bf16 v[98:101], v[184:187], v[200:203], v[98:101]
	v_mfma_f32_16x16x32_bf16 v[102:105], v[172:175], v[196:199], v[102:105]
	v_mfma_f32_16x16x32_bf16 v[102:105], v[176:179], v[200:203], v[102:105]
	v_mfma_f32_16x16x32_bf16 v[86:89], v[172:175], v[206:209], v[86:89]
	v_mfma_f32_16x16x32_bf16 v[86:89], v[176:179], v[210:213], v[86:89]
	v_mfma_f32_16x16x32_bf16 v[82:85], v[180:183], v[206:209], v[82:85]
	v_mfma_f32_16x16x32_bf16 v[82:85], v[184:187], v[210:213], v[82:85]
	v_mfma_f32_16x16x32_bf16 v[66:69], v[180:183], v[214:217], v[66:69]
	v_mfma_f32_16x16x32_bf16 v[66:69], v[184:187], v[218:221], v[66:69]
	v_mfma_f32_16x16x32_bf16 v[70:73], v[172:175], v[214:217], v[70:73]
	v_mfma_f32_16x16x32_bf16 v[70:73], v[176:179], v[218:221], v[70:73]
	s_setprio 0
	s_barrier
	s_add_i32 s26, s28, s59
	v_lshl_add_u64 v[154:155], v[154:155], 0, s[38:39]
	s_mov_b32 m0, s26
	ds_read_b128 v[188:191], v163 offset:49152
	ds_read_b128 v[192:195], v163 offset:50176
	ds_read_b128 v[196:199], v163 offset:51200
	ds_read_b128 v[200:203], v163 offset:52224
	ds_read_b128 v[206:209], v163 offset:53248
	ds_read_b128 v[210:213], v163 offset:54272
	ds_read_b128 v[214:217], v163 offset:55296
	ds_read_b128 v[218:221], v163 offset:56320
	global_load_lds_dwordx4 v[154:155], off
	s_add_i32 m0, s26, 0x2000
	s_add_u32 s8, s8, 0x100080
	v_lshl_add_u64 v[154:155], v[222:223], 0, s[38:39]
	s_addc_u32 s9, s9, 0
	s_add_i32 s26, s29, s59
	global_load_lds_dwordx4 v[154:155], off
	v_lshl_add_u64 v[154:155], s[8:9], 0, v[132:133]
	s_mov_b32 m0, s26
	s_nop 0
	global_load_lds_dwordx4 v[154:155], off
	v_lshl_add_u64 v[154:155], s[8:9], 0, v[136:137]
	s_add_i32 m0, s26, 0x2000
	s_nop 0
	global_load_lds_dwordx4 v[154:155], off
	v_lshl_add_u64 v[154:155], v[224:225], 0, s[38:39]
	s_mov_b32 m0, s22
	s_nop 0
	global_load_lds_dwordx4 v[154:155], off
	v_lshl_add_u64 v[154:155], v[226:227], 0, s[38:39]
	s_mov_b32 m0, s23
	s_nop 0
	global_load_lds_dwordx4 v[154:155], off
	s_waitcnt vmcnt(8)
	s_waitcnt lgkmcnt(0)
	s_barrier
	s_setprio 1
	s_waitcnt lgkmcnt(0)
	v_mfma_f32_16x16x32_bf16 v[62:65], v[146:149], v[188:191], v[62:65]
	v_mfma_f32_16x16x32_bf16 v[62:65], v[150:153], v[192:195], v[62:65]
	v_mfma_f32_16x16x32_bf16 v[58:61], v[164:167], v[188:191], v[58:61]
	v_mfma_f32_16x16x32_bf16 v[58:61], v[168:171], v[192:195], v[58:61]
	v_mfma_f32_16x16x32_bf16 v[42:45], v[164:167], v[196:199], v[42:45]
	v_mfma_f32_16x16x32_bf16 v[42:45], v[168:171], v[200:203], v[42:45]
	v_mfma_f32_16x16x32_bf16 v[46:49], v[146:149], v[196:199], v[46:49]
	v_mfma_f32_16x16x32_bf16 v[46:49], v[150:153], v[200:203], v[46:49]
	v_mfma_f32_16x16x32_bf16 v[30:33], v[146:149], v[206:209], v[30:33]
	v_mfma_f32_16x16x32_bf16 v[30:33], v[150:153], v[210:213], v[30:33]
	v_mfma_f32_16x16x32_bf16 v[26:29], v[164:167], v[206:209], v[26:29]
	v_mfma_f32_16x16x32_bf16 v[26:29], v[168:171], v[210:213], v[26:29]
	v_mfma_f32_16x16x32_bf16 v[10:13], v[164:167], v[214:217], v[10:13]
	v_mfma_f32_16x16x32_bf16 v[10:13], v[168:171], v[218:221], v[10:13]
	v_mfma_f32_16x16x32_bf16 v[14:17], v[146:149], v[214:217], v[14:17]
	v_mfma_f32_16x16x32_bf16 v[14:17], v[150:153], v[218:221], v[14:17]
	v_mfma_f32_16x16x32_bf16 v[54:57], v[172:175], v[188:191], v[54:57]
	v_mfma_f32_16x16x32_bf16 v[54:57], v[176:179], v[192:195], v[54:57]
	v_mfma_f32_16x16x32_bf16 v[50:53], v[180:183], v[188:191], v[50:53]
	v_mfma_f32_16x16x32_bf16 v[50:53], v[184:187], v[192:195], v[50:53]
	v_mfma_f32_16x16x32_bf16 v[34:37], v[180:183], v[196:199], v[34:37]
	v_mfma_f32_16x16x32_bf16 v[34:37], v[184:187], v[200:203], v[34:37]
	v_mfma_f32_16x16x32_bf16 v[38:41], v[172:175], v[196:199], v[38:41]
	v_mfma_f32_16x16x32_bf16 v[38:41], v[176:179], v[200:203], v[38:41]
	v_mfma_f32_16x16x32_bf16 v[22:25], v[172:175], v[206:209], v[22:25]
	v_mfma_f32_16x16x32_bf16 v[22:25], v[176:179], v[210:213], v[22:25]
	v_mfma_f32_16x16x32_bf16 v[18:21], v[180:183], v[206:209], v[18:21]
	v_mfma_f32_16x16x32_bf16 v[18:21], v[184:187], v[210:213], v[18:21]
	v_mfma_f32_16x16x32_bf16 v[2:5], v[180:183], v[214:217], v[2:5]
	v_mfma_f32_16x16x32_bf16 v[2:5], v[184:187], v[218:221], v[2:5]
	v_mfma_f32_16x16x32_bf16 v[6:9], v[172:175], v[214:217], v[6:9]
	v_mfma_f32_16x16x32_bf16 v[6:9], v[176:179], v[218:221], v[6:9]
	s_setprio 0
	s_barrier
	s_add_i32 s57, s57, 2
	s_add_u32 s4, s4, 0x100
	s_addc_u32 s5, s5, 0
	s_add_u32 s33, s33, 0x100
	s_addc_u32 s55, s55, 0
	s_cmp_gt_u32 s57, 61
	s_cbranch_scc0 .LBB0_649
	s_and_b64 vcc, exec, s[40:41]
	s_cbranch_vccz .LBB0_652
	s_barrier

.LBB0_955:
	s_add_u32 s28, s72, s60
	s_addc_u32 s29, s73, 0
	s_add_u32 s36, s28, 0x100
	s_addc_u32 s37, s29, 0
	s_and_b64 s[26:27], s[58:59], exec
	s_cselect_b32 s63, s39, s37
	s_cselect_b32 s62, s78, s36
	s_add_u32 s26, s70, s60
	s_addc_u32 s27, s71, 0
	s_add_u32 s36, s26, 0x100
	s_addc_u32 s37, s27, 0
	s_and_b64 s[26:27], s[58:59], exec
	s_cselect_b32 s65, s31, s37
	s_cselect_b32 s64, s79, s36
	s_add_u32 vcc_lo, s28, 0x20080
	ds_read_b128 v[130:133], v181
	ds_read_b128 v[134:137], v181 offset:1024
	ds_read_b128 v[150:153], v181 offset:2048
	ds_read_b128 v[154:157], v181 offset:3072
	ds_read_b128 v[158:161], v182
	ds_read_b128 v[162:165], v182 offset:1024
	ds_read_b128 v[166:169], v182 offset:2048
	ds_read_b128 v[170:173], v182 offset:3072
	s_addc_u32 vcc_hi, s29, 0
	s_add_i32 s27, s4, s86
	s_add_i32 m0, s69, 0xc000
	s_add_i32 s37, s69, 0xe000
	s_add_i32 s36, s27, 0x2000
	s_add_u32 s66, s64, 0x10000
	s_addc_u32 s67, s65, 0
	s_add_i32 s29, s5, s86
	s_add_i32 s28, s29, 0x2000
	s_add_i32 s83, 0, 0x18000
	s_add_i32 s82, 0, 0x1c000
	s_add_u32 s60, s62, 0x20000
	s_addc_u32 s61, s63, 0
	s_add_i32 s81, s83, s86
	s_add_i32 s26, s81, 0x2000
	s_add_u32 s58, s64, 0x10080
	s_addc_u32 s59, s65, 0
	s_add_i32 s80, s82, s86
	s_add_i32 s93, s80, 0x2000
	v_lshl_add_u64 v[218:219], vcc, 0, v[140:141]
	ds_read_b128 v[184:187], v183
	ds_read_b128 v[188:191], v183 offset:1024
	ds_read_b128 v[192:195], v183 offset:2048
	ds_read_b128 v[196:199], v183 offset:3072
	ds_read_b128 v[200:203], v183 offset:4096
	ds_read_b128 v[206:209], v183 offset:5120
	ds_read_b128 v[210:213], v183 offset:6144
	ds_read_b128 v[214:217], v183 offset:7168
	global_load_lds_dwordx4 v[218:219], off
	v_lshl_add_u64 v[218:219], vcc, 0, v[144:145]
	s_mov_b32 m0, s37
	s_nop 0
	global_load_lds_dwordx4 v[218:219], off
	s_waitcnt vmcnt(8)
	s_waitcnt lgkmcnt(0)
	s_barrier
	s_setprio 1
	s_waitcnt lgkmcnt(0)
	v_mfma_f32_16x16x32_bf16 v[126:129], v[130:133], v[184:187], v[126:129]
	v_mfma_f32_16x16x32_bf16 v[126:129], v[134:137], v[188:191], v[126:129]
	v_mfma_f32_16x16x32_bf16 v[122:125], v[150:153], v[184:187], v[122:125]
	v_mfma_f32_16x16x32_bf16 v[122:125], v[154:157], v[188:191], v[122:125]
	v_mfma_f32_16x16x32_bf16 v[114:117], v[150:153], v[192:195], v[114:117]
	v_mfma_f32_16x16x32_bf16 v[114:117], v[154:157], v[196:199], v[114:117]
	v_mfma_f32_16x16x32_bf16 v[118:121], v[130:133], v[192:195], v[118:121]
	v_mfma_f32_16x16x32_bf16 v[118:121], v[134:137], v[196:199], v[118:121]
	v_mfma_f32_16x16x32_bf16 v[110:113], v[130:133], v[200:203], v[110:113]
	v_mfma_f32_16x16x32_bf16 v[110:113], v[134:137], v[206:209], v[110:113]
	v_mfma_f32_16x16x32_bf16 v[106:109], v[150:153], v[200:203], v[106:109]
	v_mfma_f32_16x16x32_bf16 v[106:109], v[154:157], v[206:209], v[106:109]
	v_mfma_f32_16x16x32_bf16 v[98:101], v[150:153], v[210:213], v[98:101]
	v_mfma_f32_16x16x32_bf16 v[98:101], v[154:157], v[214:217], v[98:101]
	v_mfma_f32_16x16x32_bf16 v[102:105], v[130:133], v[210:213], v[102:105]
	v_mfma_f32_16x16x32_bf16 v[102:105], v[134:137], v[214:217], v[102:105]
	v_mfma_f32_16x16x32_bf16 v[62:65], v[158:161], v[184:187], v[62:65]
	v_mfma_f32_16x16x32_bf16 v[62:65], v[162:165], v[188:191], v[62:65]
	v_mfma_f32_16x16x32_bf16 v[58:61], v[166:169], v[184:187], v[58:61]
	v_mfma_f32_16x16x32_bf16 v[58:61], v[170:173], v[188:191], v[58:61]
	v_mfma_f32_16x16x32_bf16 v[50:53], v[166:169], v[192:195], v[50:53]
	v_mfma_f32_16x16x32_bf16 v[50:53], v[170:173], v[196:199], v[50:53]
	v_mfma_f32_16x16x32_bf16 v[54:57], v[158:161], v[192:195], v[54:57]
	v_mfma_f32_16x16x32_bf16 v[54:57], v[162:165], v[196:199], v[54:57]
	v_mfma_f32_16x16x32_bf16 v[46:49], v[158:161], v[200:203], v[46:49]
	v_mfma_f32_16x16x32_bf16 v[46:49], v[162:165], v[206:209], v[46:49]
	v_mfma_f32_16x16x32_bf16 v[42:45], v[166:169], v[200:203], v[42:45]
	v_mfma_f32_16x16x32_bf16 v[42:45], v[170:173], v[206:209], v[42:45]
	v_mfma_f32_16x16x32_bf16 v[34:37], v[166:169], v[210:213], v[34:37]
	v_mfma_f32_16x16x32_bf16 v[34:37], v[170:173], v[214:217], v[34:37]
	v_mfma_f32_16x16x32_bf16 v[38:41], v[158:161], v[210:213], v[38:41]
	v_mfma_f32_16x16x32_bf16 v[38:41], v[162:165], v[214:217], v[38:41]
	s_setprio 0
	s_barrier
	s_mov_b32 m0, s27
	v_lshl_add_u64 v[218:219], s[64:65], 0, v[142:143]
	ds_read_b128 v[184:187], v183 offset:16384
	ds_read_b128 v[188:191], v183 offset:17408
	ds_read_b128 v[192:195], v183 offset:18432
	ds_read_b128 v[196:199], v183 offset:19456
	ds_read_b128 v[200:203], v183 offset:20480
	ds_read_b128 v[206:209], v183 offset:21504
	ds_read_b128 v[210:213], v183 offset:22528
	ds_read_b128 v[214:217], v183 offset:23552
	global_load_lds_dwordx4 v[218:219], off
	v_lshl_add_u64 v[220:221], s[64:65], 0, v[146:147]
	s_mov_b32 m0, s36
	v_lshl_add_u64 v[222:223], s[66:67], 0, v[142:143]
	global_load_lds_dwordx4 v[220:221], off
	s_mov_b32 m0, s29
	v_lshl_add_u64 v[224:225], s[62:63], 0, v[144:145]
	global_load_lds_dwordx4 v[222:223], off
	v_lshl_add_u64 v[222:223], s[66:67], 0, v[146:147]
	s_mov_b32 m0, s28
	s_nop 0
	global_load_lds_dwordx4 v[222:223], off
	v_lshl_add_u64 v[222:223], s[62:63], 0, v[140:141]
	s_mov_b32 m0, s69
	s_nop 0
	global_load_lds_dwordx4 v[222:223], off
	s_mov_b32 m0, s87
	s_nop 0
	global_load_lds_dwordx4 v[224:225], off
	s_waitcnt vmcnt(8)
	s_waitcnt lgkmcnt(0)
	s_barrier
	s_setprio 1
	s_waitcnt lgkmcnt(0)
	v_mfma_f32_16x16x32_bf16 v[94:97], v[130:133], v[184:187], v[94:97]
	v_mfma_f32_16x16x32_bf16 v[94:97], v[134:137], v[188:191], v[94:97]
	v_mfma_f32_16x16x32_bf16 v[90:93], v[150:153], v[184:187], v[90:93]
	v_mfma_f32_16x16x32_bf16 v[90:93], v[154:157], v[188:191], v[90:93]
	v_mfma_f32_16x16x32_bf16 v[82:85], v[150:153], v[192:195], v[82:85]
	v_mfma_f32_16x16x32_bf16 v[82:85], v[154:157], v[196:199], v[82:85]
	v_mfma_f32_16x16x32_bf16 v[86:89], v[130:133], v[192:195], v[86:89]
	v_mfma_f32_16x16x32_bf16 v[86:89], v[134:137], v[196:199], v[86:89]
	v_mfma_f32_16x16x32_bf16 v[78:81], v[130:133], v[200:203], v[78:81]
	v_mfma_f32_16x16x32_bf16 v[78:81], v[134:137], v[206:209], v[78:81]
	v_mfma_f32_16x16x32_bf16 v[74:77], v[150:153], v[200:203], v[74:77]
	v_mfma_f32_16x16x32_bf16 v[74:77], v[154:157], v[206:209], v[74:77]
	v_mfma_f32_16x16x32_bf16 v[66:69], v[150:153], v[210:213], v[66:69]
	v_mfma_f32_16x16x32_bf16 v[66:69], v[154:157], v[214:217], v[66:69]
	v_mfma_f32_16x16x32_bf16 v[70:73], v[130:133], v[210:213], v[70:73]
	v_mfma_f32_16x16x32_bf16 v[70:73], v[134:137], v[214:217], v[70:73]
	v_mfma_f32_16x16x32_bf16 v[30:33], v[158:161], v[184:187], v[30:33]
	v_mfma_f32_16x16x32_bf16 v[30:33], v[162:165], v[188:191], v[30:33]
	v_mfma_f32_16x16x32_bf16 v[26:29], v[166:169], v[184:187], v[26:29]
	v_mfma_f32_16x16x32_bf16 v[26:29], v[170:173], v[188:191], v[26:29]
	v_mfma_f32_16x16x32_bf16 v[18:21], v[166:169], v[192:195], v[18:21]
	v_mfma_f32_16x16x32_bf16 v[18:21], v[170:173], v[196:199], v[18:21]
	v_mfma_f32_16x16x32_bf16 v[22:25], v[158:161], v[192:195], v[22:25]
	v_mfma_f32_16x16x32_bf16 v[22:25], v[162:165], v[196:199], v[22:25]
	v_mfma_f32_16x16x32_bf16 v[14:17], v[158:161], v[200:203], v[14:17]
	v_mfma_f32_16x16x32_bf16 v[14:17], v[162:165], v[206:209], v[14:17]
	v_mfma_f32_16x16x32_bf16 v[10:13], v[166:169], v[200:203], v[10:13]
	v_mfma_f32_16x16x32_bf16 v[10:13], v[170:173], v[206:209], v[10:13]
	v_mfma_f32_16x16x32_bf16 v[2:5], v[166:169], v[210:213], v[2:5]
	v_mfma_f32_16x16x32_bf16 v[2:5], v[170:173], v[214:217], v[2:5]
	v_mfma_f32_16x16x32_bf16 v[6:9], v[158:161], v[210:213], v[6:9]
	v_mfma_f32_16x16x32_bf16 v[6:9], v[162:165], v[214:217], v[6:9]
	s_setprio 0
	s_barrier
	v_add_u32_e32 v148, s83, v179
	ds_read_b128 v[130:133], v148
	ds_read_b128 v[134:137], v148 offset:1024
	ds_read_b128 v[150:153], v148 offset:2048
	ds_read_b128 v[154:157], v148 offset:3072
	v_add_u32_e32 v148, s82, v179
	ds_read_b128 v[158:161], v148
	ds_read_b128 v[162:165], v148 offset:1024
	ds_read_b128 v[166:169], v148 offset:2048
	ds_read_b128 v[170:173], v148 offset:3072
	s_mov_b32 m0, s88
	v_lshl_add_u64 v[226:227], s[60:61], 0, v[140:141]
	ds_read_b128 v[184:187], v183 offset:32768
	ds_read_b128 v[188:191], v183 offset:33792
	ds_read_b128 v[192:195], v183 offset:34816
	ds_read_b128 v[196:199], v183 offset:35840
	ds_read_b128 v[200:203], v183 offset:36864
	ds_read_b128 v[206:209], v183 offset:37888
	ds_read_b128 v[210:213], v183 offset:38912
	ds_read_b128 v[214:217], v183 offset:39936
	global_load_lds_dwordx4 v[226:227], off
	v_lshl_add_u64 v[226:227], s[60:61], 0, v[144:145]
	s_mov_b32 m0, s89
	s_nop 0
	global_load_lds_dwordx4 v[226:227], off
	s_waitcnt vmcnt(8)
	s_waitcnt lgkmcnt(0)
	s_barrier
	s_setprio 1
	s_waitcnt lgkmcnt(0)
	v_mfma_f32_16x16x32_bf16 v[126:129], v[130:133], v[184:187], v[126:129]
	v_mfma_f32_16x16x32_bf16 v[126:129], v[134:137], v[188:191], v[126:129]
	v_mfma_f32_16x16x32_bf16 v[122:125], v[150:153], v[184:187], v[122:125]
	v_mfma_f32_16x16x32_bf16 v[122:125], v[154:157], v[188:191], v[122:125]
	v_mfma_f32_16x16x32_bf16 v[114:117], v[150:153], v[192:195], v[114:117]
	v_mfma_f32_16x16x32_bf16 v[114:117], v[154:157], v[196:199], v[114:117]
	v_mfma_f32_16x16x32_bf16 v[118:121], v[130:133], v[192:195], v[118:121]
	v_mfma_f32_16x16x32_bf16 v[118:121], v[134:137], v[196:199], v[118:121]
	v_mfma_f32_16x16x32_bf16 v[110:113], v[130:133], v[200:203], v[110:113]
	v_mfma_f32_16x16x32_bf16 v[110:113], v[134:137], v[206:209], v[110:113]
	v_mfma_f32_16x16x32_bf16 v[106:109], v[150:153], v[200:203], v[106:109]
	v_mfma_f32_16x16x32_bf16 v[106:109], v[154:157], v[206:209], v[106:109]
	v_mfma_f32_16x16x32_bf16 v[98:101], v[150:153], v[210:213], v[98:101]
	v_mfma_f32_16x16x32_bf16 v[98:101], v[154:157], v[214:217], v[98:101]
	v_mfma_f32_16x16x32_bf16 v[102:105], v[130:133], v[210:213], v[102:105]
	v_mfma_f32_16x16x32_bf16 v[102:105], v[134:137], v[214:217], v[102:105]
	v_mfma_f32_16x16x32_bf16 v[62:65], v[158:161], v[184:187], v[62:65]
	v_mfma_f32_16x16x32_bf16 v[62:65], v[162:165], v[188:191], v[62:65]
	v_mfma_f32_16x16x32_bf16 v[58:61], v[166:169], v[184:187], v[58:61]
	v_mfma_f32_16x16x32_bf16 v[58:61], v[170:173], v[188:191], v[58:61]
	v_mfma_f32_16x16x32_bf16 v[50:53], v[166:169], v[192:195], v[50:53]
	v_mfma_f32_16x16x32_bf16 v[50:53], v[170:173], v[196:199], v[50:53]
	v_mfma_f32_16x16x32_bf16 v[54:57], v[158:161], v[192:195], v[54:57]
	v_mfma_f32_16x16x32_bf16 v[54:57], v[162:165], v[196:199], v[54:57]
	v_mfma_f32_16x16x32_bf16 v[46:49], v[158:161], v[200:203], v[46:49]
	v_mfma_f32_16x16x32_bf16 v[46:49], v[162:165], v[206:209], v[46:49]
	v_mfma_f32_16x16x32_bf16 v[42:45], v[166:169], v[200:203], v[42:45]
	v_mfma_f32_16x16x32_bf16 v[42:45], v[170:173], v[206:209], v[42:45]
	v_mfma_f32_16x16x32_bf16 v[34:37], v[166:169], v[210:213], v[34:37]
	v_mfma_f32_16x16x32_bf16 v[34:37], v[170:173], v[214:217], v[34:37]
	v_mfma_f32_16x16x32_bf16 v[38:41], v[158:161], v[210:213], v[38:41]
	v_mfma_f32_16x16x32_bf16 v[38:41], v[162:165], v[214:217], v[38:41]
	s_setprio 0
	s_barrier
	s_mov_b32 m0, s81
	v_lshl_add_u64 v[218:219], v[218:219], 0, s[10:11]
	ds_read_b128 v[184:187], v183 offset:49152
	ds_read_b128 v[188:191], v183 offset:50176
	ds_read_b128 v[192:195], v183 offset:51200
	ds_read_b128 v[196:199], v183 offset:52224
	ds_read_b128 v[200:203], v183 offset:53248
	ds_read_b128 v[206:209], v183 offset:54272
	ds_read_b128 v[210:213], v183 offset:55296
	ds_read_b128 v[214:217], v183 offset:56320
	global_load_lds_dwordx4 v[218:219], off
	v_lshl_add_u64 v[218:219], v[220:221], 0, s[10:11]
	s_mov_b32 m0, s26
	s_nop 0
	global_load_lds_dwordx4 v[218:219], off
	v_lshl_add_u64 v[218:219], s[58:59], 0, v[142:143]
	s_mov_b32 m0, s80
	s_nop 0
	global_load_lds_dwordx4 v[218:219], off
	v_lshl_add_u64 v[218:219], s[58:59], 0, v[146:147]
	s_mov_b32 m0, s93
	s_nop 0
	global_load_lds_dwordx4 v[218:219], off
	v_lshl_add_u64 v[218:219], v[222:223], 0, s[10:11]
	s_mov_b32 m0, s90
	s_nop 0
	global_load_lds_dwordx4 v[218:219], off
	v_lshl_add_u64 v[218:219], v[224:225], 0, s[10:11]
	s_mov_b32 m0, s91
	s_nop 0
	global_load_lds_dwordx4 v[218:219], off
	s_waitcnt vmcnt(8)
	s_waitcnt lgkmcnt(0)
	s_barrier
	s_setprio 1
	s_waitcnt lgkmcnt(0)
	v_mfma_f32_16x16x32_bf16 v[94:97], v[130:133], v[184:187], v[94:97]
	v_mfma_f32_16x16x32_bf16 v[94:97], v[134:137], v[188:191], v[94:97]
	v_mfma_f32_16x16x32_bf16 v[90:93], v[150:153], v[184:187], v[90:93]
	v_mfma_f32_16x16x32_bf16 v[90:93], v[154:157], v[188:191], v[90:93]
	v_mfma_f32_16x16x32_bf16 v[82:85], v[150:153], v[192:195], v[82:85]
	v_mfma_f32_16x16x32_bf16 v[82:85], v[154:157], v[196:199], v[82:85]
	v_mfma_f32_16x16x32_bf16 v[86:89], v[130:133], v[192:195], v[86:89]
	v_mfma_f32_16x16x32_bf16 v[86:89], v[134:137], v[196:199], v[86:89]
	v_mfma_f32_16x16x32_bf16 v[78:81], v[130:133], v[200:203], v[78:81]
	v_mfma_f32_16x16x32_bf16 v[78:81], v[134:137], v[206:209], v[78:81]
	v_mfma_f32_16x16x32_bf16 v[74:77], v[150:153], v[200:203], v[74:77]
	v_mfma_f32_16x16x32_bf16 v[74:77], v[154:157], v[206:209], v[74:77]
	v_mfma_f32_16x16x32_bf16 v[66:69], v[150:153], v[210:213], v[66:69]
	v_mfma_f32_16x16x32_bf16 v[66:69], v[154:157], v[214:217], v[66:69]
	v_mfma_f32_16x16x32_bf16 v[70:73], v[130:133], v[210:213], v[70:73]
	v_mfma_f32_16x16x32_bf16 v[70:73], v[134:137], v[214:217], v[70:73]
	v_mfma_f32_16x16x32_bf16 v[30:33], v[158:161], v[184:187], v[30:33]
	v_mfma_f32_16x16x32_bf16 v[30:33], v[162:165], v[188:191], v[30:33]
	v_mfma_f32_16x16x32_bf16 v[26:29], v[166:169], v[184:187], v[26:29]
	v_mfma_f32_16x16x32_bf16 v[26:29], v[170:173], v[188:191], v[26:29]
	v_mfma_f32_16x16x32_bf16 v[18:21], v[166:169], v[192:195], v[18:21]
	v_mfma_f32_16x16x32_bf16 v[18:21], v[170:173], v[196:199], v[18:21]
	v_mfma_f32_16x16x32_bf16 v[22:25], v[158:161], v[192:195], v[22:25]
	v_mfma_f32_16x16x32_bf16 v[22:25], v[162:165], v[196:199], v[22:25]
	v_mfma_f32_16x16x32_bf16 v[14:17], v[158:161], v[200:203], v[14:17]
	v_mfma_f32_16x16x32_bf16 v[14:17], v[162:165], v[206:209], v[14:17]
	v_mfma_f32_16x16x32_bf16 v[10:13], v[166:169], v[200:203], v[10:13]
	v_mfma_f32_16x16x32_bf16 v[10:13], v[170:173], v[206:209], v[10:13]
	v_mfma_f32_16x16x32_bf16 v[2:5], v[166:169], v[210:213], v[2:5]
	v_mfma_f32_16x16x32_bf16 v[2:5], v[170:173], v[214:217], v[2:5]
	v_mfma_f32_16x16x32_bf16 v[6:9], v[158:161], v[210:213], v[6:9]
	v_mfma_f32_16x16x32_bf16 v[6:9], v[162:165], v[214:217], v[6:9]
	s_setprio 0
	s_barrier
	s_movk_i32 s60, 0x100
	s_andn2_b64 vcc, exec, s[52:53]
	s_mov_b64 s[58:59], -1
	s_mov_b64 s[52:53], 0
	s_cbranch_vccz .LBB0_955
	s_and_b64 vcc, exec, s[14:15]
	s_cbranch_vccz .LBB0_958
	s_barrier

.LBB0_985:
	s_add_u32 s41, s30, s40
	s_addc_u32 s42, s31, 0
	s_add_u32 s43, s41, 0x100
	s_addc_u32 s44, s42, 0
	s_and_b64 s[26:27], s[38:39], exec
	s_cselect_b32 s53, s17, s44
	s_cselect_b32 s52, s19, s43
	s_add_u32 s26, s28, s40
	s_addc_u32 s27, s29, 0
	s_add_u32 s40, s26, 0x100
	s_addc_u32 s43, s27, 0
	s_and_b64 s[26:27], s[38:39], exec
	s_cselect_b32 s55, s15, s43
	s_cselect_b32 s54, s73, s40
	s_add_u32 s58, s41, 0x20080
	ds_read_b128 v[148:151], v133
	ds_read_b128 v[152:155], v133 offset:1024
	ds_read_b128 v[156:159], v133 offset:2048
	ds_read_b128 v[160:163], v133 offset:3072
	ds_read_b128 v[164:167], v134
	ds_read_b128 v[168:171], v134 offset:1024
	ds_read_b128 v[172:175], v134 offset:2048
	ds_read_b128 v[176:179], v134 offset:3072
	s_addc_u32 s59, s42, 0
	s_add_i32 s81, s71, s60
	s_add_i32 m0, s61, 0xc000
	s_add_i32 s42, s61, 0xe000
	s_add_i32 s26, s81, 0x2000
	s_add_u32 s56, s54, 0x10000
	s_addc_u32 s57, s55, 0
	s_add_i32 s80, s72, s60
	s_add_i32 s27, s80, 0x2000
	s_add_i32 s79, 0, 0x18000
	s_add_i32 s78, 0, 0x1c000
	s_add_u32 s40, s52, 0x20000
	s_addc_u32 s41, s53, 0
	s_add_i32 s77, s79, s60
	s_add_i32 s75, s77, 0x2000
	s_add_u32 s38, s54, 0x10080
	s_addc_u32 s39, s55, 0
	s_add_i32 s76, s78, s60
	s_add_i32 s74, s76, 0x2000
	v_lshl_add_u64 v[136:137], s[58:59], 0, v[140:141]
	ds_read_b128 v[180:183], v135
	ds_read_b128 v[184:187], v135 offset:1024
	ds_read_b128 v[188:191], v135 offset:2048
	ds_read_b128 v[192:195], v135 offset:3072
	ds_read_b128 v[196:199], v135 offset:4096
	ds_read_b128 v[200:203], v135 offset:5120
	ds_read_b128 v[206:209], v135 offset:6144
	ds_read_b128 v[210:213], v135 offset:7168
	global_load_lds_dwordx4 v[136:137], off
	v_lshl_add_u64 v[136:137], s[58:59], 0, v[144:145]
	s_mov_b32 m0, s42
	s_nop 0
	global_load_lds_dwordx4 v[136:137], off
	s_waitcnt vmcnt(8)
	s_waitcnt lgkmcnt(0)
	s_barrier
	s_setprio 1
	s_waitcnt lgkmcnt(0)
	v_mfma_f32_16x16x32_bf16 v[126:129], v[148:151], v[180:183], v[126:129]
	v_mfma_f32_16x16x32_bf16 v[126:129], v[152:155], v[184:187], v[126:129]
	v_mfma_f32_16x16x32_bf16 v[122:125], v[156:159], v[180:183], v[122:125]
	v_mfma_f32_16x16x32_bf16 v[122:125], v[160:163], v[184:187], v[122:125]
	v_mfma_f32_16x16x32_bf16 v[114:117], v[156:159], v[188:191], v[114:117]
	v_mfma_f32_16x16x32_bf16 v[114:117], v[160:163], v[192:195], v[114:117]
	v_mfma_f32_16x16x32_bf16 v[118:121], v[148:151], v[188:191], v[118:121]
	v_mfma_f32_16x16x32_bf16 v[118:121], v[152:155], v[192:195], v[118:121]
	v_mfma_f32_16x16x32_bf16 v[102:105], v[148:151], v[196:199], v[102:105]
	v_mfma_f32_16x16x32_bf16 v[102:105], v[152:155], v[200:203], v[102:105]
	v_mfma_f32_16x16x32_bf16 v[98:101], v[156:159], v[196:199], v[98:101]
	v_mfma_f32_16x16x32_bf16 v[98:101], v[160:163], v[200:203], v[98:101]
	v_mfma_f32_16x16x32_bf16 v[82:85], v[156:159], v[206:209], v[82:85]
	v_mfma_f32_16x16x32_bf16 v[82:85], v[160:163], v[210:213], v[82:85]
	v_mfma_f32_16x16x32_bf16 v[86:89], v[148:151], v[206:209], v[86:89]
	v_mfma_f32_16x16x32_bf16 v[86:89], v[152:155], v[210:213], v[86:89]
	v_mfma_f32_16x16x32_bf16 v[110:113], v[164:167], v[180:183], v[110:113]
	v_mfma_f32_16x16x32_bf16 v[110:113], v[168:171], v[184:187], v[110:113]
	v_mfma_f32_16x16x32_bf16 v[106:109], v[172:175], v[180:183], v[106:109]
	v_mfma_f32_16x16x32_bf16 v[106:109], v[176:179], v[184:187], v[106:109]
	v_mfma_f32_16x16x32_bf16 v[90:93], v[172:175], v[188:191], v[90:93]
	v_mfma_f32_16x16x32_bf16 v[90:93], v[176:179], v[192:195], v[90:93]
	v_mfma_f32_16x16x32_bf16 v[94:97], v[164:167], v[188:191], v[94:97]
	v_mfma_f32_16x16x32_bf16 v[94:97], v[168:171], v[192:195], v[94:97]
	v_mfma_f32_16x16x32_bf16 v[78:81], v[164:167], v[196:199], v[78:81]
	v_mfma_f32_16x16x32_bf16 v[78:81], v[168:171], v[200:203], v[78:81]
	v_mfma_f32_16x16x32_bf16 v[74:77], v[172:175], v[196:199], v[74:77]
	v_mfma_f32_16x16x32_bf16 v[74:77], v[176:179], v[200:203], v[74:77]
	v_mfma_f32_16x16x32_bf16 v[66:69], v[172:175], v[206:209], v[66:69]
	v_mfma_f32_16x16x32_bf16 v[66:69], v[176:179], v[210:213], v[66:69]
	v_mfma_f32_16x16x32_bf16 v[70:73], v[164:167], v[206:209], v[70:73]
	v_mfma_f32_16x16x32_bf16 v[70:73], v[168:171], v[210:213], v[70:73]
	s_setprio 0
	s_barrier
	s_mov_b32 m0, s81
	v_lshl_add_u64 v[136:137], s[54:55], 0, v[142:143]
	ds_read_b128 v[180:183], v135 offset:16384
	ds_read_b128 v[184:187], v135 offset:17408
	ds_read_b128 v[188:191], v135 offset:18432
	ds_read_b128 v[192:195], v135 offset:19456
	ds_read_b128 v[196:199], v135 offset:20480
	ds_read_b128 v[200:203], v135 offset:21504
	ds_read_b128 v[206:209], v135 offset:22528
	ds_read_b128 v[210:213], v135 offset:23552
	global_load_lds_dwordx4 v[136:137], off
	v_lshl_add_u64 v[214:215], s[54:55], 0, v[146:147]
	s_mov_b32 m0, s26
	v_lshl_add_u64 v[216:217], s[56:57], 0, v[142:143]
	global_load_lds_dwordx4 v[214:215], off
	s_mov_b32 m0, s80
	v_lshl_add_u64 v[218:219], s[52:53], 0, v[144:145]
	global_load_lds_dwordx4 v[216:217], off
	v_lshl_add_u64 v[216:217], s[56:57], 0, v[146:147]
	s_mov_b32 m0, s27
	s_nop 0
	global_load_lds_dwordx4 v[216:217], off
	v_lshl_add_u64 v[216:217], s[52:53], 0, v[140:141]
	s_mov_b32 m0, s61
	s_nop 0
	global_load_lds_dwordx4 v[216:217], off
	s_mov_b32 m0, s62
	s_nop 0
	global_load_lds_dwordx4 v[218:219], off
	s_waitcnt vmcnt(8)
	s_waitcnt lgkmcnt(0)
	s_barrier
	s_setprio 1
	s_waitcnt lgkmcnt(0)
	v_mfma_f32_16x16x32_bf16 v[62:65], v[148:151], v[180:183], v[62:65]
	v_mfma_f32_16x16x32_bf16 v[62:65], v[152:155], v[184:187], v[62:65]
	v_mfma_f32_16x16x32_bf16 v[58:61], v[156:159], v[180:183], v[58:61]
	v_mfma_f32_16x16x32_bf16 v[58:61], v[160:163], v[184:187], v[58:61]
	v_mfma_f32_16x16x32_bf16 v[50:53], v[156:159], v[188:191], v[50:53]
	v_mfma_f32_16x16x32_bf16 v[50:53], v[160:163], v[192:195], v[50:53]
	v_mfma_f32_16x16x32_bf16 v[54:57], v[148:151], v[188:191], v[54:57]
	v_mfma_f32_16x16x32_bf16 v[54:57], v[152:155], v[192:195], v[54:57]
	v_mfma_f32_16x16x32_bf16 v[38:41], v[148:151], v[196:199], v[38:41]
	v_mfma_f32_16x16x32_bf16 v[38:41], v[152:155], v[200:203], v[38:41]
	v_mfma_f32_16x16x32_bf16 v[34:37], v[156:159], v[196:199], v[34:37]
	v_mfma_f32_16x16x32_bf16 v[34:37], v[160:163], v[200:203], v[34:37]
	v_mfma_f32_16x16x32_bf16 v[18:21], v[156:159], v[206:209], v[18:21]
	v_mfma_f32_16x16x32_bf16 v[18:21], v[160:163], v[210:213], v[18:21]
	v_mfma_f32_16x16x32_bf16 v[22:25], v[148:151], v[206:209], v[22:25]
	v_mfma_f32_16x16x32_bf16 v[22:25], v[152:155], v[210:213], v[22:25]
	v_mfma_f32_16x16x32_bf16 v[46:49], v[164:167], v[180:183], v[46:49]
	v_mfma_f32_16x16x32_bf16 v[46:49], v[168:171], v[184:187], v[46:49]
	v_mfma_f32_16x16x32_bf16 v[42:45], v[172:175], v[180:183], v[42:45]
	v_mfma_f32_16x16x32_bf16 v[42:45], v[176:179], v[184:187], v[42:45]
	v_mfma_f32_16x16x32_bf16 v[26:29], v[172:175], v[188:191], v[26:29]
	v_mfma_f32_16x16x32_bf16 v[26:29], v[176:179], v[192:195], v[26:29]
	v_mfma_f32_16x16x32_bf16 v[30:33], v[164:167], v[188:191], v[30:33]
	v_mfma_f32_16x16x32_bf16 v[30:33], v[168:171], v[192:195], v[30:33]
	v_mfma_f32_16x16x32_bf16 v[14:17], v[164:167], v[196:199], v[14:17]
	v_mfma_f32_16x16x32_bf16 v[14:17], v[168:171], v[200:203], v[14:17]
	v_mfma_f32_16x16x32_bf16 v[10:13], v[172:175], v[196:199], v[10:13]
	v_mfma_f32_16x16x32_bf16 v[10:13], v[176:179], v[200:203], v[10:13]
	v_mfma_f32_16x16x32_bf16 v[2:5], v[172:175], v[206:209], v[2:5]
	v_mfma_f32_16x16x32_bf16 v[2:5], v[176:179], v[210:213], v[2:5]
	v_mfma_f32_16x16x32_bf16 v[6:9], v[164:167], v[206:209], v[6:9]
	v_mfma_f32_16x16x32_bf16 v[6:9], v[168:171], v[210:213], v[6:9]
	s_setprio 0
	s_barrier
	v_add_u32_e32 v160, s79, v131
	v_add_u32_e32 v176, s78, v131
	ds_read_b128 v[148:151], v160
	ds_read_b128 v[152:155], v160 offset:1024
	ds_read_b128 v[156:159], v160 offset:2048
	ds_read_b128 v[160:163], v160 offset:3072
	ds_read_b128 v[164:167], v176
	ds_read_b128 v[168:171], v176 offset:1024
	ds_read_b128 v[172:175], v176 offset:2048
	ds_read_b128 v[176:179], v176 offset:3072
	s_mov_b32 m0, s63
	v_lshl_add_u64 v[220:221], s[40:41], 0, v[140:141]
	ds_read_b128 v[180:183], v135 offset:32768
	ds_read_b128 v[184:187], v135 offset:33792
	ds_read_b128 v[188:191], v135 offset:34816
	ds_read_b128 v[192:195], v135 offset:35840
	ds_read_b128 v[196:199], v135 offset:36864
	ds_read_b128 v[200:203], v135 offset:37888
	ds_read_b128 v[206:209], v135 offset:38912
	ds_read_b128 v[210:213], v135 offset:39936
	global_load_lds_dwordx4 v[220:221], off
	v_lshl_add_u64 v[220:221], s[40:41], 0, v[144:145]
	s_mov_b32 m0, s64
	s_nop 0
	global_load_lds_dwordx4 v[220:221], off
	s_waitcnt vmcnt(8)
	s_waitcnt lgkmcnt(0)
	s_barrier
	s_setprio 1
	s_waitcnt lgkmcnt(0)
	v_mfma_f32_16x16x32_bf16 v[126:129], v[148:151], v[180:183], v[126:129]
	v_mfma_f32_16x16x32_bf16 v[126:129], v[152:155], v[184:187], v[126:129]
	v_mfma_f32_16x16x32_bf16 v[122:125], v[156:159], v[180:183], v[122:125]
	v_mfma_f32_16x16x32_bf16 v[122:125], v[160:163], v[184:187], v[122:125]
	v_mfma_f32_16x16x32_bf16 v[114:117], v[156:159], v[188:191], v[114:117]
	v_mfma_f32_16x16x32_bf16 v[114:117], v[160:163], v[192:195], v[114:117]
	v_mfma_f32_16x16x32_bf16 v[118:121], v[148:151], v[188:191], v[118:121]
	v_mfma_f32_16x16x32_bf16 v[118:121], v[152:155], v[192:195], v[118:121]
	v_mfma_f32_16x16x32_bf16 v[102:105], v[148:151], v[196:199], v[102:105]
	v_mfma_f32_16x16x32_bf16 v[102:105], v[152:155], v[200:203], v[102:105]
	v_mfma_f32_16x16x32_bf16 v[98:101], v[156:159], v[196:199], v[98:101]
	v_mfma_f32_16x16x32_bf16 v[98:101], v[160:163], v[200:203], v[98:101]
	v_mfma_f32_16x16x32_bf16 v[82:85], v[156:159], v[206:209], v[82:85]
	v_mfma_f32_16x16x32_bf16 v[82:85], v[160:163], v[210:213], v[82:85]
	v_mfma_f32_16x16x32_bf16 v[86:89], v[148:151], v[206:209], v[86:89]
	v_mfma_f32_16x16x32_bf16 v[86:89], v[152:155], v[210:213], v[86:89]
	v_mfma_f32_16x16x32_bf16 v[110:113], v[164:167], v[180:183], v[110:113]
	v_mfma_f32_16x16x32_bf16 v[110:113], v[168:171], v[184:187], v[110:113]
	v_mfma_f32_16x16x32_bf16 v[106:109], v[172:175], v[180:183], v[106:109]
	v_mfma_f32_16x16x32_bf16 v[106:109], v[176:179], v[184:187], v[106:109]
	v_mfma_f32_16x16x32_bf16 v[90:93], v[172:175], v[188:191], v[90:93]
	v_mfma_f32_16x16x32_bf16 v[90:93], v[176:179], v[192:195], v[90:93]
	v_mfma_f32_16x16x32_bf16 v[94:97], v[164:167], v[188:191], v[94:97]
	v_mfma_f32_16x16x32_bf16 v[94:97], v[168:171], v[192:195], v[94:97]
	v_mfma_f32_16x16x32_bf16 v[78:81], v[164:167], v[196:199], v[78:81]
	v_mfma_f32_16x16x32_bf16 v[78:81], v[168:171], v[200:203], v[78:81]
	v_mfma_f32_16x16x32_bf16 v[74:77], v[172:175], v[196:199], v[74:77]
	v_mfma_f32_16x16x32_bf16 v[74:77], v[176:179], v[200:203], v[74:77]
	v_mfma_f32_16x16x32_bf16 v[66:69], v[172:175], v[206:209], v[66:69]
	v_mfma_f32_16x16x32_bf16 v[66:69], v[176:179], v[210:213], v[66:69]
	v_mfma_f32_16x16x32_bf16 v[70:73], v[164:167], v[206:209], v[70:73]
	v_mfma_f32_16x16x32_bf16 v[70:73], v[168:171], v[210:213], v[70:73]
	s_setprio 0
	s_barrier
	s_mov_b32 m0, s77
	v_lshl_add_u64 v[136:137], v[136:137], 0, s[8:9]
	ds_read_b128 v[180:183], v135 offset:49152
	ds_read_b128 v[184:187], v135 offset:50176
	ds_read_b128 v[188:191], v135 offset:51200
	ds_read_b128 v[192:195], v135 offset:52224
	ds_read_b128 v[196:199], v135 offset:53248
	ds_read_b128 v[200:203], v135 offset:54272
	ds_read_b128 v[206:209], v135 offset:55296
	ds_read_b128 v[210:213], v135 offset:56320
	global_load_lds_dwordx4 v[136:137], off
	v_lshl_add_u64 v[136:137], v[214:215], 0, s[8:9]
	s_mov_b32 m0, s75
	s_nop 0
	global_load_lds_dwordx4 v[136:137], off
	v_lshl_add_u64 v[136:137], s[38:39], 0, v[142:143]
	s_mov_b32 m0, s76
	s_nop 0
	global_load_lds_dwordx4 v[136:137], off
	v_lshl_add_u64 v[136:137], s[38:39], 0, v[146:147]
	s_mov_b32 m0, s74
	s_nop 0
	global_load_lds_dwordx4 v[136:137], off
	v_lshl_add_u64 v[136:137], v[216:217], 0, s[8:9]
	s_mov_b32 m0, s65
	s_nop 0
	global_load_lds_dwordx4 v[136:137], off
	v_lshl_add_u64 v[136:137], v[218:219], 0, s[8:9]
	s_mov_b32 m0, s66
	s_nop 0
	global_load_lds_dwordx4 v[136:137], off
	s_waitcnt vmcnt(8)
	s_waitcnt lgkmcnt(0)
	s_barrier
	s_setprio 1
	s_waitcnt lgkmcnt(0)
	v_mfma_f32_16x16x32_bf16 v[62:65], v[148:151], v[180:183], v[62:65]
	v_mfma_f32_16x16x32_bf16 v[62:65], v[152:155], v[184:187], v[62:65]
	v_mfma_f32_16x16x32_bf16 v[58:61], v[156:159], v[180:183], v[58:61]
	v_mfma_f32_16x16x32_bf16 v[58:61], v[160:163], v[184:187], v[58:61]
	v_mfma_f32_16x16x32_bf16 v[50:53], v[156:159], v[188:191], v[50:53]
	v_mfma_f32_16x16x32_bf16 v[50:53], v[160:163], v[192:195], v[50:53]
	v_mfma_f32_16x16x32_bf16 v[54:57], v[148:151], v[188:191], v[54:57]
	v_mfma_f32_16x16x32_bf16 v[54:57], v[152:155], v[192:195], v[54:57]
	v_mfma_f32_16x16x32_bf16 v[38:41], v[148:151], v[196:199], v[38:41]
	v_mfma_f32_16x16x32_bf16 v[38:41], v[152:155], v[200:203], v[38:41]
	v_mfma_f32_16x16x32_bf16 v[34:37], v[156:159], v[196:199], v[34:37]
	v_mfma_f32_16x16x32_bf16 v[34:37], v[160:163], v[200:203], v[34:37]
	v_mfma_f32_16x16x32_bf16 v[18:21], v[156:159], v[206:209], v[18:21]
	v_mfma_f32_16x16x32_bf16 v[18:21], v[160:163], v[210:213], v[18:21]
	v_mfma_f32_16x16x32_bf16 v[22:25], v[148:151], v[206:209], v[22:25]
	v_mfma_f32_16x16x32_bf16 v[22:25], v[152:155], v[210:213], v[22:25]
	v_mfma_f32_16x16x32_bf16 v[46:49], v[164:167], v[180:183], v[46:49]
	v_mfma_f32_16x16x32_bf16 v[46:49], v[168:171], v[184:187], v[46:49]
	v_mfma_f32_16x16x32_bf16 v[42:45], v[172:175], v[180:183], v[42:45]
	v_mfma_f32_16x16x32_bf16 v[42:45], v[176:179], v[184:187], v[42:45]
	v_mfma_f32_16x16x32_bf16 v[26:29], v[172:175], v[188:191], v[26:29]
	v_mfma_f32_16x16x32_bf16 v[26:29], v[176:179], v[192:195], v[26:29]
	v_mfma_f32_16x16x32_bf16 v[30:33], v[164:167], v[188:191], v[30:33]
	v_mfma_f32_16x16x32_bf16 v[30:33], v[168:171], v[192:195], v[30:33]
	v_mfma_f32_16x16x32_bf16 v[14:17], v[164:167], v[196:199], v[14:17]
	v_mfma_f32_16x16x32_bf16 v[14:17], v[168:171], v[200:203], v[14:17]
	v_mfma_f32_16x16x32_bf16 v[10:13], v[172:175], v[196:199], v[10:13]
	v_mfma_f32_16x16x32_bf16 v[10:13], v[176:179], v[200:203], v[10:13]
	v_mfma_f32_16x16x32_bf16 v[2:5], v[172:175], v[206:209], v[2:5]
	v_mfma_f32_16x16x32_bf16 v[2:5], v[176:179], v[210:213], v[2:5]
	v_mfma_f32_16x16x32_bf16 v[6:9], v[164:167], v[206:209], v[6:9]
	v_mfma_f32_16x16x32_bf16 v[6:9], v[168:171], v[210:213], v[6:9]
	s_setprio 0
	s_barrier
	s_movk_i32 s40, 0x100
	s_andn2_b64 vcc, exec, s[36:37]
	s_mov_b64 s[38:39], -1
	s_mov_b64 s[36:37], 0
	s_cbranch_vccz .LBB0_985
	s_and_b64 vcc, exec, s[10:11]
	s_cbranch_vccz .LBB0_988
	s_barrier

.LBB0_1285:
	v_add_u32_e32 v3, s90, v206
	ds_read_b128 v[176:179], v3
	ds_read_b128 v[180:183], v3 offset:1024
	ds_read_b128 v[184:187], v3 offset:2048
	ds_read_b128 v[188:191], v3 offset:3072
	v_add_u32_e32 v3, s91, v206
	ds_read_b128 v[192:195], v3
	ds_read_b128 v[196:199], v3 offset:1024
	ds_read_b128 v[200:203], v3 offset:2048
	ds_read_b128 v[210:213], v3 offset:3072
	s_add_i32 s14, s58, 2
	s_add_u32 s59, s56, 0xfff00080
	s_addc_u32 s60, s57, -1
	s_cmp_eq_u32 s92, s58
	s_cselect_b32 s61, s1, s60
	s_cselect_b32 s60, s45, s59
	s_cselect_b32 s59, s47, s82
	s_cselect_b32 s58, s49, s93
	v_lshl_add_u64 v[4:5], s[56:57], 0, v[148:149]
	s_add_i32 m0, s55, 0xc000
	ds_read_b128 v[214:217], v208
	ds_read_b128 v[218:221], v208 offset:1024
	ds_read_b128 v[222:225], v208 offset:2048
	ds_read_b128 v[226:229], v208 offset:3072
	ds_read_b128 v[230:233], v208 offset:4096
	ds_read_b128 v[234:237], v208 offset:5120
	ds_read_b128 v[238:241], v208 offset:6144
	ds_read_b128 v[242:245], v208 offset:7168
	global_load_lds_dwordx4 v[4:5], off
	v_lshl_add_u64 v[4:5], s[56:57], 0, v[150:151]
	s_add_i32 m0, s55, 0xe000
	s_nop 0
	global_load_lds_dwordx4 v[4:5], off
	s_waitcnt vmcnt(8)
	s_waitcnt lgkmcnt(0)
	s_barrier
	s_setprio 1
	s_waitcnt lgkmcnt(0)
	v_mfma_f32_16x16x32_bf16 v[106:109], v[176:179], v[214:217], v[106:109]
	v_mfma_f32_16x16x32_bf16 v[106:109], v[180:183], v[218:221], v[106:109]
	v_mfma_f32_16x16x32_bf16 v[114:117], v[184:187], v[214:217], v[114:117]
	v_mfma_f32_16x16x32_bf16 v[114:117], v[188:191], v[218:221], v[114:117]
	v_mfma_f32_16x16x32_bf16 v[110:113], v[184:187], v[222:225], v[110:113]
	v_mfma_f32_16x16x32_bf16 v[110:113], v[188:191], v[226:229], v[110:113]
	v_mfma_f32_16x16x32_bf16 v[102:105], v[176:179], v[222:225], v[102:105]
	v_mfma_f32_16x16x32_bf16 v[102:105], v[180:183], v[226:229], v[102:105]
	v_mfma_f32_16x16x32_bf16 v[90:93], v[176:179], v[230:233], v[90:93]
	v_mfma_f32_16x16x32_bf16 v[90:93], v[180:183], v[234:237], v[90:93]
	v_mfma_f32_16x16x32_bf16 v[86:89], v[184:187], v[230:233], v[86:89]
	v_mfma_f32_16x16x32_bf16 v[86:89], v[188:191], v[234:237], v[86:89]
	v_mfma_f32_16x16x32_bf16 v[70:73], v[184:187], v[238:241], v[70:73]
	v_mfma_f32_16x16x32_bf16 v[70:73], v[188:191], v[242:245], v[70:73]
	v_mfma_f32_16x16x32_bf16 v[74:77], v[176:179], v[238:241], v[74:77]
	v_mfma_f32_16x16x32_bf16 v[74:77], v[180:183], v[242:245], v[74:77]
	v_mfma_f32_16x16x32_bf16 v[126:129], v[192:195], v[214:217], v[126:129]
	v_mfma_f32_16x16x32_bf16 v[126:129], v[196:199], v[218:221], v[126:129]
	v_mfma_f32_16x16x32_bf16 v[130:133], v[200:203], v[214:217], v[130:133]
	v_mfma_f32_16x16x32_bf16 v[130:133], v[210:213], v[218:221], v[130:133]
	v_mfma_f32_16x16x32_bf16 v[118:121], v[200:203], v[222:225], v[118:121]
	v_mfma_f32_16x16x32_bf16 v[118:121], v[210:213], v[226:229], v[118:121]
	v_mfma_f32_16x16x32_bf16 v[122:125], v[192:195], v[222:225], v[122:125]
	v_mfma_f32_16x16x32_bf16 v[122:125], v[196:199], v[226:229], v[122:125]
	v_mfma_f32_16x16x32_bf16 v[98:101], v[192:195], v[230:233], v[98:101]
	v_mfma_f32_16x16x32_bf16 v[98:101], v[196:199], v[234:237], v[98:101]
	v_mfma_f32_16x16x32_bf16 v[94:97], v[200:203], v[230:233], v[94:97]
	v_mfma_f32_16x16x32_bf16 v[94:97], v[210:213], v[234:237], v[94:97]
	v_mfma_f32_16x16x32_bf16 v[78:81], v[200:203], v[238:241], v[78:81]
	v_mfma_f32_16x16x32_bf16 v[78:81], v[210:213], v[242:245], v[78:81]
	v_mfma_f32_16x16x32_bf16 v[82:85], v[192:195], v[238:241], v[82:85]
	v_mfma_f32_16x16x32_bf16 v[82:85], v[196:199], v[242:245], v[82:85]
	s_setprio 0
	s_barrier
	s_add_i32 vcc_lo, s90, s66
	v_lshl_add_u64 v[246:247], s[58:59], 0, v[140:141]
	s_mov_b32 m0, vcc_lo
	ds_read_b128 v[214:217], v208 offset:16384
	ds_read_b128 v[218:221], v208 offset:17408
	ds_read_b128 v[222:225], v208 offset:18432
	ds_read_b128 v[226:229], v208 offset:19456
	ds_read_b128 v[230:233], v208 offset:20480
	ds_read_b128 v[234:237], v208 offset:21504
	ds_read_b128 v[238:241], v208 offset:22528
	ds_read_b128 v[242:245], v208 offset:23552
	global_load_lds_dwordx4 v[246:247], off
	s_add_i32 m0, vcc_lo, 0x2000
	s_add_u32 vcc_lo, s58, 0x100000
	v_lshl_add_u64 v[248:249], s[58:59], 0, v[144:145]
	s_addc_u32 vcc_hi, s59, 0
	s_add_i32 s83, s91, s66
	global_load_lds_dwordx4 v[248:249], off
	v_lshl_add_u64 v[4:5], vcc, 0, v[140:141]
	s_mov_b32 m0, s83
	v_lshl_add_u64 v[250:251], s[60:61], 0, v[136:137]
	global_load_lds_dwordx4 v[4:5], off
	v_lshl_add_u64 v[4:5], vcc, 0, v[144:145]
	s_add_i32 m0, s83, 0x2000
	v_lshl_add_u64 v[252:253], s[60:61], 0, v[142:143]
	global_load_lds_dwordx4 v[4:5], off
	s_mov_b32 m0, s55
	s_nop 0
	global_load_lds_dwordx4 v[250:251], off
	s_mov_b32 m0, s72
	s_nop 0
	global_load_lds_dwordx4 v[252:253], off
	s_waitcnt vmcnt(8)
	s_waitcnt lgkmcnt(0)
	s_barrier
	s_setprio 1
	s_waitcnt lgkmcnt(0)
	v_mfma_f32_16x16x32_bf16 v[66:69], v[176:179], v[214:217], v[66:69]
	v_mfma_f32_16x16x32_bf16 v[66:69], v[180:183], v[218:221], v[66:69]
	v_mfma_f32_16x16x32_bf16 v[58:61], v[184:187], v[214:217], v[58:61]
	v_mfma_f32_16x16x32_bf16 v[58:61], v[188:191], v[218:221], v[58:61]
	v_mfma_f32_16x16x32_bf16 v[42:45], v[184:187], v[222:225], v[42:45]
	v_mfma_f32_16x16x32_bf16 v[42:45], v[188:191], v[226:229], v[42:45]
	v_mfma_f32_16x16x32_bf16 v[50:53], v[176:179], v[222:225], v[50:53]
	v_mfma_f32_16x16x32_bf16 v[50:53], v[180:183], v[226:229], v[50:53]
	v_mfma_f32_16x16x32_bf16 v[34:37], v[176:179], v[230:233], v[34:37]
	v_mfma_f32_16x16x32_bf16 v[34:37], v[180:183], v[234:237], v[34:37]
	v_mfma_f32_16x16x32_bf16 v[26:29], v[184:187], v[230:233], v[26:29]
	v_mfma_f32_16x16x32_bf16 v[26:29], v[188:191], v[234:237], v[26:29]
	v_mfma_f32_16x16x32_bf16 v[10:13], v[184:187], v[238:241], v[10:13]
	v_mfma_f32_16x16x32_bf16 v[10:13], v[188:191], v[242:245], v[10:13]
	v_mfma_f32_16x16x32_bf16 v[18:21], v[176:179], v[238:241], v[18:21]
	v_mfma_f32_16x16x32_bf16 v[18:21], v[180:183], v[242:245], v[18:21]
	v_mfma_f32_16x16x32_bf16 v[62:65], v[192:195], v[214:217], v[62:65]
	v_mfma_f32_16x16x32_bf16 v[62:65], v[196:199], v[218:221], v[62:65]
	v_mfma_f32_16x16x32_bf16 v[54:57], v[200:203], v[214:217], v[54:57]
	v_mfma_f32_16x16x32_bf16 v[54:57], v[210:213], v[218:221], v[54:57]
	v_mfma_f32_16x16x32_bf16 v[38:41], v[200:203], v[222:225], v[38:41]
	v_mfma_f32_16x16x32_bf16 v[38:41], v[210:213], v[226:229], v[38:41]
	v_mfma_f32_16x16x32_bf16 v[46:49], v[192:195], v[222:225], v[46:49]
	v_mfma_f32_16x16x32_bf16 v[46:49], v[196:199], v[226:229], v[46:49]
	v_mfma_f32_16x16x32_bf16 v[30:33], v[192:195], v[230:233], v[30:33]
	v_mfma_f32_16x16x32_bf16 v[30:33], v[196:199], v[234:237], v[30:33]
	v_mfma_f32_16x16x32_bf16 v[22:25], v[200:203], v[230:233], v[22:25]
	v_mfma_f32_16x16x32_bf16 v[22:25], v[210:213], v[234:237], v[22:25]
	v_mfma_f32_16x16x32_bf16 v[4:7], v[200:203], v[238:241], v[6:9]
	v_mfma_f32_16x16x32_bf16 v[4:7], v[210:213], v[242:245], v[4:7]
	v_mfma_f32_16x16x32_bf16 v[14:17], v[192:195], v[238:241], v[14:17]
	v_mfma_f32_16x16x32_bf16 v[14:17], v[196:199], v[242:245], v[14:17]
	s_setprio 0
	s_barrier
	s_add_i32 s83, 0, 0x18000
	v_add_u32_e32 v3, s83, v206
	s_add_i32 vcc_lo, 0, 0x1c000
	ds_read_b128 v[176:179], v3
	ds_read_b128 v[180:183], v3 offset:1024
	ds_read_b128 v[184:187], v3 offset:2048
	ds_read_b128 v[188:191], v3 offset:3072
	v_add_u32_e32 v3, vcc_lo, v206
	ds_read_b128 v[192:195], v3
	ds_read_b128 v[196:199], v3 offset:1024
	ds_read_b128 v[200:203], v3 offset:2048
	ds_read_b128 v[210:213], v3 offset:3072
	s_add_u32 s60, s60, 0x100000
	s_addc_u32 s61, s61, 0
	s_mov_b32 m0, s73
	v_lshl_add_u64 v[8:9], s[60:61], 0, v[136:137]
	ds_read_b128 v[214:217], v208 offset:32768
	ds_read_b128 v[218:221], v208 offset:33792
	ds_read_b128 v[222:225], v208 offset:34816
	ds_read_b128 v[226:229], v208 offset:35840
	ds_read_b128 v[230:233], v208 offset:36864
	ds_read_b128 v[234:237], v208 offset:37888
	ds_read_b128 v[238:241], v208 offset:38912
	ds_read_b128 v[242:245], v208 offset:39936
	global_load_lds_dwordx4 v[8:9], off
	v_lshl_add_u64 v[8:9], s[60:61], 0, v[142:143]
	s_mov_b32 m0, s74
	s_nop 0
	global_load_lds_dwordx4 v[8:9], off
	s_waitcnt vmcnt(8)
	s_waitcnt lgkmcnt(0)
	s_barrier
	s_setprio 1
	s_waitcnt lgkmcnt(0)
	v_mfma_f32_16x16x32_bf16 v[106:109], v[176:179], v[214:217], v[106:109]
	v_mfma_f32_16x16x32_bf16 v[106:109], v[180:183], v[218:221], v[106:109]
	v_mfma_f32_16x16x32_bf16 v[114:117], v[184:187], v[214:217], v[114:117]
	v_mfma_f32_16x16x32_bf16 v[114:117], v[188:191], v[218:221], v[114:117]
	v_mfma_f32_16x16x32_bf16 v[110:113], v[184:187], v[222:225], v[110:113]
	v_mfma_f32_16x16x32_bf16 v[110:113], v[188:191], v[226:229], v[110:113]
	v_mfma_f32_16x16x32_bf16 v[102:105], v[176:179], v[222:225], v[102:105]
	v_mfma_f32_16x16x32_bf16 v[102:105], v[180:183], v[226:229], v[102:105]
	v_mfma_f32_16x16x32_bf16 v[90:93], v[176:179], v[230:233], v[90:93]
	v_mfma_f32_16x16x32_bf16 v[90:93], v[180:183], v[234:237], v[90:93]
	v_mfma_f32_16x16x32_bf16 v[86:89], v[184:187], v[230:233], v[86:89]
	v_mfma_f32_16x16x32_bf16 v[86:89], v[188:191], v[234:237], v[86:89]
	v_mfma_f32_16x16x32_bf16 v[70:73], v[184:187], v[238:241], v[70:73]
	v_mfma_f32_16x16x32_bf16 v[70:73], v[188:191], v[242:245], v[70:73]
	v_mfma_f32_16x16x32_bf16 v[74:77], v[176:179], v[238:241], v[74:77]
	v_mfma_f32_16x16x32_bf16 v[74:77], v[180:183], v[242:245], v[74:77]
	v_mfma_f32_16x16x32_bf16 v[126:129], v[192:195], v[214:217], v[126:129]
	v_mfma_f32_16x16x32_bf16 v[126:129], v[196:199], v[218:221], v[126:129]
	v_mfma_f32_16x16x32_bf16 v[130:133], v[200:203], v[214:217], v[130:133]
	v_mfma_f32_16x16x32_bf16 v[130:133], v[210:213], v[218:221], v[130:133]
	v_mfma_f32_16x16x32_bf16 v[118:121], v[200:203], v[222:225], v[118:121]
	v_mfma_f32_16x16x32_bf16 v[118:121], v[210:213], v[226:229], v[118:121]
	v_mfma_f32_16x16x32_bf16 v[122:125], v[192:195], v[222:225], v[122:125]
	v_mfma_f32_16x16x32_bf16 v[122:125], v[196:199], v[226:229], v[122:125]
	v_mfma_f32_16x16x32_bf16 v[98:101], v[192:195], v[230:233], v[98:101]
	v_mfma_f32_16x16x32_bf16 v[98:101], v[196:199], v[234:237], v[98:101]
	v_mfma_f32_16x16x32_bf16 v[94:97], v[200:203], v[230:233], v[94:97]
	v_mfma_f32_16x16x32_bf16 v[94:97], v[210:213], v[234:237], v[94:97]
	v_mfma_f32_16x16x32_bf16 v[78:81], v[200:203], v[238:241], v[78:81]
	v_mfma_f32_16x16x32_bf16 v[78:81], v[210:213], v[242:245], v[78:81]
	v_mfma_f32_16x16x32_bf16 v[82:85], v[192:195], v[238:241], v[82:85]
	v_mfma_f32_16x16x32_bf16 v[82:85], v[196:199], v[242:245], v[82:85]
	s_setprio 0
	s_barrier
	s_add_i32 s60, s83, s66
	v_lshl_add_u64 v[8:9], v[246:247], 0, s[20:21]
	s_mov_b32 m0, s60
	ds_read_b128 v[214:217], v208 offset:49152
	ds_read_b128 v[218:221], v208 offset:50176
	ds_read_b128 v[222:225], v208 offset:51200
	ds_read_b128 v[226:229], v208 offset:52224
	ds_read_b128 v[230:233], v208 offset:53248
	ds_read_b128 v[234:237], v208 offset:54272
	ds_read_b128 v[238:241], v208 offset:55296
	ds_read_b128 v[242:245], v208 offset:56320
	global_load_lds_dwordx4 v[8:9], off
	s_add_i32 m0, s60, 0x2000
	s_add_u32 s58, s58, 0x100080
	v_lshl_add_u64 v[8:9], v[248:249], 0, s[20:21]
	s_addc_u32 s59, s59, 0
	s_add_i32 s60, vcc_lo, s66
	global_load_lds_dwordx4 v[8:9], off
	v_lshl_add_u64 v[8:9], s[58:59], 0, v[140:141]
	s_mov_b32 m0, s60
	s_nop 0
	global_load_lds_dwordx4 v[8:9], off
	v_lshl_add_u64 v[8:9], s[58:59], 0, v[144:145]
	s_add_i32 m0, s60, 0x2000
	s_nop 0
	global_load_lds_dwordx4 v[8:9], off
	v_lshl_add_u64 v[8:9], v[250:251], 0, s[20:21]
	s_mov_b32 m0, s76
	s_nop 0
	global_load_lds_dwordx4 v[8:9], off
	v_lshl_add_u64 v[8:9], v[252:253], 0, s[20:21]
	s_mov_b32 m0, s77
	s_nop 0
	global_load_lds_dwordx4 v[8:9], off
	s_waitcnt vmcnt(8)
	s_waitcnt lgkmcnt(0)
	s_barrier
	s_setprio 1
	s_waitcnt lgkmcnt(0)
	v_mfma_f32_16x16x32_bf16 v[66:69], v[176:179], v[214:217], v[66:69]
	v_mfma_f32_16x16x32_bf16 v[66:69], v[180:183], v[218:221], v[66:69]
	v_mfma_f32_16x16x32_bf16 v[58:61], v[184:187], v[214:217], v[58:61]
	v_mfma_f32_16x16x32_bf16 v[58:61], v[188:191], v[218:221], v[58:61]
	v_mfma_f32_16x16x32_bf16 v[42:45], v[184:187], v[222:225], v[42:45]
	v_mfma_f32_16x16x32_bf16 v[42:45], v[188:191], v[226:229], v[42:45]
	v_mfma_f32_16x16x32_bf16 v[50:53], v[176:179], v[222:225], v[50:53]
	v_mfma_f32_16x16x32_bf16 v[50:53], v[180:183], v[226:229], v[50:53]
	v_mfma_f32_16x16x32_bf16 v[34:37], v[176:179], v[230:233], v[34:37]
	v_mfma_f32_16x16x32_bf16 v[34:37], v[180:183], v[234:237], v[34:37]
	v_mfma_f32_16x16x32_bf16 v[26:29], v[184:187], v[230:233], v[26:29]
	v_mfma_f32_16x16x32_bf16 v[26:29], v[188:191], v[234:237], v[26:29]
	v_mfma_f32_16x16x32_bf16 v[8:11], v[184:187], v[238:241], v[10:13]
	v_mfma_f32_16x16x32_bf16 v[10:13], v[188:191], v[242:245], v[8:11]
	v_mfma_f32_16x16x32_bf16 v[18:21], v[176:179], v[238:241], v[18:21]
	v_mfma_f32_16x16x32_bf16 v[18:21], v[180:183], v[242:245], v[18:21]
	v_mfma_f32_16x16x32_bf16 v[62:65], v[192:195], v[214:217], v[62:65]
	v_mfma_f32_16x16x32_bf16 v[62:65], v[196:199], v[218:221], v[62:65]
	v_mfma_f32_16x16x32_bf16 v[54:57], v[200:203], v[214:217], v[54:57]
	v_mfma_f32_16x16x32_bf16 v[54:57], v[210:213], v[218:221], v[54:57]
	v_mfma_f32_16x16x32_bf16 v[38:41], v[200:203], v[222:225], v[38:41]
	v_mfma_f32_16x16x32_bf16 v[38:41], v[210:213], v[226:229], v[38:41]
	v_mfma_f32_16x16x32_bf16 v[46:49], v[192:195], v[222:225], v[46:49]
	v_mfma_f32_16x16x32_bf16 v[46:49], v[196:199], v[226:229], v[46:49]
	v_mfma_f32_16x16x32_bf16 v[30:33], v[192:195], v[230:233], v[30:33]
	v_mfma_f32_16x16x32_bf16 v[30:33], v[196:199], v[234:237], v[30:33]
	v_mfma_f32_16x16x32_bf16 v[22:25], v[200:203], v[230:233], v[22:25]
	v_mfma_f32_16x16x32_bf16 v[22:25], v[210:213], v[234:237], v[22:25]
	v_mfma_f32_16x16x32_bf16 v[4:7], v[200:203], v[238:241], v[4:7]
	v_mfma_f32_16x16x32_bf16 v[6:9], v[210:213], v[242:245], v[4:7]
	v_mfma_f32_16x16x32_bf16 v[14:17], v[192:195], v[238:241], v[14:17]
	v_mfma_f32_16x16x32_bf16 v[14:17], v[196:199], v[242:245], v[14:17]
	s_setprio 0
	s_barrier
	s_add_u32 s56, s56, 0x100
	s_addc_u32 s57, s57, 0
	s_add_u32 s93, s93, 0x100
	s_addc_u32 s82, s82, 0
	s_cmp_ge_i32 s14, s39
	s_cbranch_scc1 .LBB0_1288
	s_mov_b32 s58, s14
	s_branch .LBB0_1283

.LBB0_1461:
	ds_read_b128 v[146:149], v157
	ds_read_b128 v[162:165], v157 offset:1024
	ds_read_b128 v[166:169], v157 offset:2048
	ds_read_b128 v[170:173], v157 offset:3072
	ds_read_b128 v[174:177], v158
	ds_read_b128 v[178:181], v158 offset:1024
	ds_read_b128 v[182:185], v158 offset:2048
	ds_read_b128 v[186:189], v158 offset:3072
	s_add_i32 s89, s52, 2
	s_add_u32 s53, s50, 0xfff00080
	s_addc_u32 s54, s51, -1
	s_cmp_eq_u32 s39, s52
	s_cselect_b32 s52, s46, s41
	s_cselect_b32 s55, s45, s54
	s_cselect_b32 s54, s44, s53
	s_cselect_b32 s53, s47, s43
	v_lshl_add_u64 v[150:151], s[50:51], 0, v[142:143]
	s_add_i32 m0, s64, 0xc000
	ds_read_b128 v[190:193], v159
	ds_read_b128 v[194:197], v159 offset:1024
	ds_read_b128 v[198:201], v159 offset:2048
	ds_read_b128 v[206:209], v159 offset:3072
	ds_read_b128 v[210:213], v159 offset:4096
	ds_read_b128 v[214:217], v159 offset:5120
	ds_read_b128 v[218:221], v159 offset:6144
	ds_read_b128 v[222:225], v159 offset:7168
	global_load_lds_dwordx4 v[150:151], off
	v_lshl_add_u64 v[150:151], s[50:51], 0, v[144:145]
	s_add_i32 m0, s64, 0xe000
	s_nop 0
	global_load_lds_dwordx4 v[150:151], off
	s_waitcnt vmcnt(8)
	s_waitcnt lgkmcnt(0)
	s_barrier
	s_setprio 1
	s_waitcnt lgkmcnt(0)
	v_mfma_f32_16x16x32_bf16 v[126:129], v[146:149], v[190:193], v[126:129]
	v_mfma_f32_16x16x32_bf16 v[126:129], v[162:165], v[194:197], v[126:129]
	v_mfma_f32_16x16x32_bf16 v[122:125], v[166:169], v[190:193], v[122:125]
	v_mfma_f32_16x16x32_bf16 v[122:125], v[170:173], v[194:197], v[122:125]
	v_mfma_f32_16x16x32_bf16 v[114:117], v[166:169], v[198:201], v[114:117]
	v_mfma_f32_16x16x32_bf16 v[114:117], v[170:173], v[206:209], v[114:117]
	v_mfma_f32_16x16x32_bf16 v[118:121], v[146:149], v[198:201], v[118:121]
	v_mfma_f32_16x16x32_bf16 v[118:121], v[162:165], v[206:209], v[118:121]
	v_mfma_f32_16x16x32_bf16 v[110:113], v[146:149], v[210:213], v[110:113]
	v_mfma_f32_16x16x32_bf16 v[110:113], v[162:165], v[214:217], v[110:113]
	v_mfma_f32_16x16x32_bf16 v[106:109], v[166:169], v[210:213], v[106:109]
	v_mfma_f32_16x16x32_bf16 v[106:109], v[170:173], v[214:217], v[106:109]
	v_mfma_f32_16x16x32_bf16 v[98:101], v[166:169], v[218:221], v[98:101]
	v_mfma_f32_16x16x32_bf16 v[98:101], v[170:173], v[222:225], v[98:101]
	v_mfma_f32_16x16x32_bf16 v[102:105], v[146:149], v[218:221], v[102:105]
	v_mfma_f32_16x16x32_bf16 v[102:105], v[162:165], v[222:225], v[102:105]
	v_mfma_f32_16x16x32_bf16 v[94:97], v[174:177], v[190:193], v[94:97]
	v_mfma_f32_16x16x32_bf16 v[94:97], v[178:181], v[194:197], v[94:97]
	v_mfma_f32_16x16x32_bf16 v[90:93], v[182:185], v[190:193], v[90:93]
	v_mfma_f32_16x16x32_bf16 v[90:93], v[186:189], v[194:197], v[90:93]
	v_mfma_f32_16x16x32_bf16 v[82:85], v[182:185], v[198:201], v[82:85]
	v_mfma_f32_16x16x32_bf16 v[82:85], v[186:189], v[206:209], v[82:85]
	v_mfma_f32_16x16x32_bf16 v[86:89], v[174:177], v[198:201], v[86:89]
	v_mfma_f32_16x16x32_bf16 v[86:89], v[178:181], v[206:209], v[86:89]
	v_mfma_f32_16x16x32_bf16 v[78:81], v[174:177], v[210:213], v[78:81]
	v_mfma_f32_16x16x32_bf16 v[78:81], v[178:181], v[214:217], v[78:81]
	v_mfma_f32_16x16x32_bf16 v[74:77], v[182:185], v[210:213], v[74:77]
	v_mfma_f32_16x16x32_bf16 v[74:77], v[186:189], v[214:217], v[74:77]
	v_mfma_f32_16x16x32_bf16 v[66:69], v[182:185], v[218:221], v[66:69]
	v_mfma_f32_16x16x32_bf16 v[66:69], v[186:189], v[222:225], v[66:69]
	v_mfma_f32_16x16x32_bf16 v[70:73], v[174:177], v[218:221], v[70:73]
	v_mfma_f32_16x16x32_bf16 v[70:73], v[178:181], v[222:225], v[70:73]
	s_setprio 0
	s_barrier
	s_add_i32 s90, s82, s59
	v_lshl_add_u64 v[150:151], s[52:53], 0, v[132:133]
	s_mov_b32 m0, s90
	ds_read_b128 v[190:193], v159 offset:16384
	ds_read_b128 v[194:197], v159 offset:17408
	ds_read_b128 v[198:201], v159 offset:18432
	ds_read_b128 v[206:209], v159 offset:19456
	ds_read_b128 v[210:213], v159 offset:20480
	ds_read_b128 v[214:217], v159 offset:21504
	ds_read_b128 v[218:221], v159 offset:22528
	ds_read_b128 v[222:225], v159 offset:23552
	global_load_lds_dwordx4 v[150:151], off
	s_add_i32 m0, s90, 0x2000
	s_add_u32 s90, s52, 0x100000
	v_lshl_add_u64 v[202:203], s[52:53], 0, v[136:137]
	s_addc_u32 s91, s53, 0
	s_add_i32 s92, s83, s59
	global_load_lds_dwordx4 v[202:203], off
	v_lshl_add_u64 v[226:227], s[90:91], 0, v[132:133]
	s_mov_b32 m0, s92
	v_lshl_add_u64 v[228:229], s[54:55], 0, v[134:135]
	global_load_lds_dwordx4 v[226:227], off
	v_lshl_add_u64 v[226:227], s[90:91], 0, v[136:137]
	s_add_i32 m0, s92, 0x2000
	s_nop 0
	global_load_lds_dwordx4 v[226:227], off
	v_lshl_add_u64 v[226:227], s[54:55], 0, v[130:131]
	s_mov_b32 m0, s64
	s_nop 0
	global_load_lds_dwordx4 v[226:227], off
	s_mov_b32 m0, s66
	s_nop 0
	global_load_lds_dwordx4 v[228:229], off
	s_waitcnt vmcnt(8)
	s_waitcnt lgkmcnt(0)
	s_barrier
	s_setprio 1
	s_waitcnt lgkmcnt(0)
	v_mfma_f32_16x16x32_bf16 v[62:65], v[146:149], v[190:193], v[62:65]
	v_mfma_f32_16x16x32_bf16 v[62:65], v[162:165], v[194:197], v[62:65]
	v_mfma_f32_16x16x32_bf16 v[58:61], v[166:169], v[190:193], v[58:61]
	v_mfma_f32_16x16x32_bf16 v[58:61], v[170:173], v[194:197], v[58:61]
	v_mfma_f32_16x16x32_bf16 v[50:53], v[166:169], v[198:201], v[50:53]
	v_mfma_f32_16x16x32_bf16 v[50:53], v[170:173], v[206:209], v[50:53]
	v_mfma_f32_16x16x32_bf16 v[54:57], v[146:149], v[198:201], v[54:57]
	v_mfma_f32_16x16x32_bf16 v[54:57], v[162:165], v[206:209], v[54:57]
	v_mfma_f32_16x16x32_bf16 v[46:49], v[146:149], v[210:213], v[46:49]
	v_mfma_f32_16x16x32_bf16 v[46:49], v[162:165], v[214:217], v[46:49]
	v_mfma_f32_16x16x32_bf16 v[42:45], v[166:169], v[210:213], v[42:45]
	v_mfma_f32_16x16x32_bf16 v[42:45], v[170:173], v[214:217], v[42:45]
	v_mfma_f32_16x16x32_bf16 v[34:37], v[166:169], v[218:221], v[34:37]
	v_mfma_f32_16x16x32_bf16 v[34:37], v[170:173], v[222:225], v[34:37]
	v_mfma_f32_16x16x32_bf16 v[38:41], v[146:149], v[218:221], v[38:41]
	v_mfma_f32_16x16x32_bf16 v[38:41], v[162:165], v[222:225], v[38:41]
	v_mfma_f32_16x16x32_bf16 v[30:33], v[174:177], v[190:193], v[30:33]
	v_mfma_f32_16x16x32_bf16 v[30:33], v[178:181], v[194:197], v[30:33]
	v_mfma_f32_16x16x32_bf16 v[26:29], v[182:185], v[190:193], v[26:29]
	v_mfma_f32_16x16x32_bf16 v[26:29], v[186:189], v[194:197], v[26:29]
	v_mfma_f32_16x16x32_bf16 v[18:21], v[182:185], v[198:201], v[18:21]
	v_mfma_f32_16x16x32_bf16 v[18:21], v[186:189], v[206:209], v[18:21]
	v_mfma_f32_16x16x32_bf16 v[22:25], v[174:177], v[198:201], v[22:25]
	v_mfma_f32_16x16x32_bf16 v[22:25], v[178:181], v[206:209], v[22:25]
	v_mfma_f32_16x16x32_bf16 v[14:17], v[174:177], v[210:213], v[14:17]
	v_mfma_f32_16x16x32_bf16 v[14:17], v[178:181], v[214:217], v[14:17]
	v_mfma_f32_16x16x32_bf16 v[10:13], v[182:185], v[210:213], v[10:13]
	v_mfma_f32_16x16x32_bf16 v[10:13], v[186:189], v[214:217], v[10:13]
	v_mfma_f32_16x16x32_bf16 v[2:5], v[182:185], v[218:221], v[2:5]
	v_mfma_f32_16x16x32_bf16 v[2:5], v[186:189], v[222:225], v[2:5]
	v_mfma_f32_16x16x32_bf16 v[6:9], v[174:177], v[218:221], v[6:9]
	v_mfma_f32_16x16x32_bf16 v[6:9], v[178:181], v[222:225], v[6:9]
	s_setprio 0
	s_barrier
	s_add_i32 s90, 0, 0x18000
	v_add_u32_e32 v161, s90, v155
	s_add_i32 s91, 0, 0x1c000
	ds_read_b128 v[146:149], v161
	ds_read_b128 v[162:165], v161 offset:1024
	ds_read_b128 v[166:169], v161 offset:2048
	ds_read_b128 v[170:173], v161 offset:3072
	v_add_u32_e32 v161, s91, v155
	ds_read_b128 v[174:177], v161
	ds_read_b128 v[178:181], v161 offset:1024
	ds_read_b128 v[182:185], v161 offset:2048
	ds_read_b128 v[186:189], v161 offset:3072
	s_add_u32 s54, s54, 0x100000
	s_addc_u32 s55, s55, 0
	s_mov_b32 m0, s67
	v_lshl_add_u64 v[230:231], s[54:55], 0, v[130:131]
	ds_read_b128 v[190:193], v159 offset:32768
	ds_read_b128 v[194:197], v159 offset:33792
	ds_read_b128 v[198:201], v159 offset:34816
	ds_read_b128 v[206:209], v159 offset:35840
	ds_read_b128 v[210:213], v159 offset:36864
	ds_read_b128 v[214:217], v159 offset:37888
	ds_read_b128 v[218:221], v159 offset:38912
	ds_read_b128 v[222:225], v159 offset:39936
	global_load_lds_dwordx4 v[230:231], off
	v_lshl_add_u64 v[230:231], s[54:55], 0, v[134:135]
	s_mov_b32 m0, s68
	s_nop 0
	global_load_lds_dwordx4 v[230:231], off
	s_waitcnt vmcnt(8)
	s_waitcnt lgkmcnt(0)
	s_barrier
	s_setprio 1
	s_waitcnt lgkmcnt(0)
	v_mfma_f32_16x16x32_bf16 v[126:129], v[146:149], v[190:193], v[126:129]
	v_mfma_f32_16x16x32_bf16 v[126:129], v[162:165], v[194:197], v[126:129]
	v_mfma_f32_16x16x32_bf16 v[122:125], v[166:169], v[190:193], v[122:125]
	v_mfma_f32_16x16x32_bf16 v[122:125], v[170:173], v[194:197], v[122:125]
	v_mfma_f32_16x16x32_bf16 v[114:117], v[166:169], v[198:201], v[114:117]
	v_mfma_f32_16x16x32_bf16 v[114:117], v[170:173], v[206:209], v[114:117]
	v_mfma_f32_16x16x32_bf16 v[118:121], v[146:149], v[198:201], v[118:121]
	v_mfma_f32_16x16x32_bf16 v[118:121], v[162:165], v[206:209], v[118:121]
	v_mfma_f32_16x16x32_bf16 v[110:113], v[146:149], v[210:213], v[110:113]
	v_mfma_f32_16x16x32_bf16 v[110:113], v[162:165], v[214:217], v[110:113]
	v_mfma_f32_16x16x32_bf16 v[106:109], v[166:169], v[210:213], v[106:109]
	v_mfma_f32_16x16x32_bf16 v[106:109], v[170:173], v[214:217], v[106:109]
	v_mfma_f32_16x16x32_bf16 v[98:101], v[166:169], v[218:221], v[98:101]
	v_mfma_f32_16x16x32_bf16 v[98:101], v[170:173], v[222:225], v[98:101]
	v_mfma_f32_16x16x32_bf16 v[102:105], v[146:149], v[218:221], v[102:105]
	v_mfma_f32_16x16x32_bf16 v[102:105], v[162:165], v[222:225], v[102:105]
	v_mfma_f32_16x16x32_bf16 v[94:97], v[174:177], v[190:193], v[94:97]
	v_mfma_f32_16x16x32_bf16 v[94:97], v[178:181], v[194:197], v[94:97]
	v_mfma_f32_16x16x32_bf16 v[90:93], v[182:185], v[190:193], v[90:93]
	v_mfma_f32_16x16x32_bf16 v[90:93], v[186:189], v[194:197], v[90:93]
	v_mfma_f32_16x16x32_bf16 v[82:85], v[182:185], v[198:201], v[82:85]
	v_mfma_f32_16x16x32_bf16 v[82:85], v[186:189], v[206:209], v[82:85]
	v_mfma_f32_16x16x32_bf16 v[86:89], v[174:177], v[198:201], v[86:89]
	v_mfma_f32_16x16x32_bf16 v[86:89], v[178:181], v[206:209], v[86:89]
	v_mfma_f32_16x16x32_bf16 v[78:81], v[174:177], v[210:213], v[78:81]
	v_mfma_f32_16x16x32_bf16 v[78:81], v[178:181], v[214:217], v[78:81]
	v_mfma_f32_16x16x32_bf16 v[74:77], v[182:185], v[210:213], v[74:77]
	v_mfma_f32_16x16x32_bf16 v[74:77], v[186:189], v[214:217], v[74:77]
	v_mfma_f32_16x16x32_bf16 v[66:69], v[182:185], v[218:221], v[66:69]
	v_mfma_f32_16x16x32_bf16 v[66:69], v[186:189], v[222:225], v[66:69]
	v_mfma_f32_16x16x32_bf16 v[70:73], v[174:177], v[218:221], v[70:73]
	v_mfma_f32_16x16x32_bf16 v[70:73], v[178:181], v[222:225], v[70:73]
	s_setprio 0
	s_barrier
	s_add_i32 s54, s90, s59
	v_lshl_add_u64 v[150:151], v[150:151], 0, s[22:23]
	s_mov_b32 m0, s54
	ds_read_b128 v[190:193], v159 offset:49152
	ds_read_b128 v[194:197], v159 offset:50176
	ds_read_b128 v[198:201], v159 offset:51200
	ds_read_b128 v[206:209], v159 offset:52224
	ds_read_b128 v[210:213], v159 offset:53248
	ds_read_b128 v[214:217], v159 offset:54272
	ds_read_b128 v[218:221], v159 offset:55296
	ds_read_b128 v[222:225], v159 offset:56320
	global_load_lds_dwordx4 v[150:151], off
	s_add_i32 m0, s54, 0x2000
	s_add_u32 s52, s52, 0x100080
	v_lshl_add_u64 v[150:151], v[202:203], 0, s[22:23]
	s_addc_u32 s53, s53, 0
	s_add_i32 s54, s91, s59
	global_load_lds_dwordx4 v[150:151], off
	v_lshl_add_u64 v[150:151], s[52:53], 0, v[132:133]
	s_mov_b32 m0, s54
	s_nop 0
	global_load_lds_dwordx4 v[150:151], off
	v_lshl_add_u64 v[150:151], s[52:53], 0, v[136:137]
	s_add_i32 m0, s54, 0x2000
	s_nop 0
	global_load_lds_dwordx4 v[150:151], off
	v_lshl_add_u64 v[150:151], v[226:227], 0, s[22:23]
	s_mov_b32 m0, s70
	s_nop 0
	global_load_lds_dwordx4 v[150:151], off
	v_lshl_add_u64 v[150:151], v[228:229], 0, s[22:23]
	s_mov_b32 m0, s71
	s_nop 0
	global_load_lds_dwordx4 v[150:151], off
	s_waitcnt vmcnt(8)
	s_waitcnt lgkmcnt(0)
	s_barrier
	s_setprio 1
	s_waitcnt lgkmcnt(0)
	v_mfma_f32_16x16x32_bf16 v[62:65], v[146:149], v[190:193], v[62:65]
	v_mfma_f32_16x16x32_bf16 v[62:65], v[162:165], v[194:197], v[62:65]
	v_mfma_f32_16x16x32_bf16 v[58:61], v[166:169], v[190:193], v[58:61]
	v_mfma_f32_16x16x32_bf16 v[58:61], v[170:173], v[194:197], v[58:61]
	v_mfma_f32_16x16x32_bf16 v[50:53], v[166:169], v[198:201], v[50:53]
	v_mfma_f32_16x16x32_bf16 v[50:53], v[170:173], v[206:209], v[50:53]
	v_mfma_f32_16x16x32_bf16 v[54:57], v[146:149], v[198:201], v[54:57]
	v_mfma_f32_16x16x32_bf16 v[54:57], v[162:165], v[206:209], v[54:57]
	v_mfma_f32_16x16x32_bf16 v[46:49], v[146:149], v[210:213], v[46:49]
	v_mfma_f32_16x16x32_bf16 v[46:49], v[162:165], v[214:217], v[46:49]
	v_mfma_f32_16x16x32_bf16 v[42:45], v[166:169], v[210:213], v[42:45]
	v_mfma_f32_16x16x32_bf16 v[42:45], v[170:173], v[214:217], v[42:45]
	v_mfma_f32_16x16x32_bf16 v[34:37], v[166:169], v[218:221], v[34:37]
	v_mfma_f32_16x16x32_bf16 v[34:37], v[170:173], v[222:225], v[34:37]
	v_mfma_f32_16x16x32_bf16 v[38:41], v[146:149], v[218:221], v[38:41]
	v_mfma_f32_16x16x32_bf16 v[38:41], v[162:165], v[222:225], v[38:41]
	v_mfma_f32_16x16x32_bf16 v[30:33], v[174:177], v[190:193], v[30:33]
	v_mfma_f32_16x16x32_bf16 v[30:33], v[178:181], v[194:197], v[30:33]
	v_mfma_f32_16x16x32_bf16 v[26:29], v[182:185], v[190:193], v[26:29]
	v_mfma_f32_16x16x32_bf16 v[26:29], v[186:189], v[194:197], v[26:29]
	v_mfma_f32_16x16x32_bf16 v[18:21], v[182:185], v[198:201], v[18:21]
	v_mfma_f32_16x16x32_bf16 v[18:21], v[186:189], v[206:209], v[18:21]
	v_mfma_f32_16x16x32_bf16 v[22:25], v[174:177], v[198:201], v[22:25]
	v_mfma_f32_16x16x32_bf16 v[22:25], v[178:181], v[206:209], v[22:25]
	v_mfma_f32_16x16x32_bf16 v[14:17], v[174:177], v[210:213], v[14:17]
	v_mfma_f32_16x16x32_bf16 v[14:17], v[178:181], v[214:217], v[14:17]
	v_mfma_f32_16x16x32_bf16 v[10:13], v[182:185], v[210:213], v[10:13]
	v_mfma_f32_16x16x32_bf16 v[10:13], v[186:189], v[214:217], v[10:13]
	v_mfma_f32_16x16x32_bf16 v[2:5], v[182:185], v[218:221], v[2:5]
	v_mfma_f32_16x16x32_bf16 v[2:5], v[186:189], v[222:225], v[2:5]
	v_mfma_f32_16x16x32_bf16 v[6:9], v[174:177], v[218:221], v[6:9]
	v_mfma_f32_16x16x32_bf16 v[6:9], v[178:181], v[222:225], v[6:9]
	s_setprio 0
	s_barrier
	s_add_u32 s50, s50, 0x100
	s_addc_u32 s51, s51, 0
	s_add_u32 s41, s41, 0x100
	s_addc_u32 s43, s43, 0
	s_cmp_ge_i32 s89, s49
	s_mov_b32 s52, s89
	s_cbranch_scc0 .LBB0_1461
	s_and_b64 vcc, exec, s[24:25]
	s_cbranch_vccz .LBB0_1464

.LBB0_1644:
	ds_read_b128 v[152:155], v149
	ds_read_b128 v[156:159], v149 offset:1024
	ds_read_b128 v[160:163], v149 offset:2048
	ds_read_b128 v[164:167], v149 offset:3072
	ds_read_b128 v[168:171], v150
	ds_read_b128 v[172:175], v150 offset:1024
	ds_read_b128 v[176:179], v150 offset:2048
	ds_read_b128 v[180:183], v150 offset:3072
	s_add_u32 s28, s26, 0xfff00080
	s_addc_u32 s29, s27, -1
	s_cmp_eq_u32 s55, 60
	s_cselect_b32 s31, s17, s29
	s_cselect_b32 s30, s51, s28
	s_cselect_b32 s29, s15, s54
	s_cselect_b32 s28, s52, s53
	v_lshl_add_u64 v[144:145], s[26:27], 0, v[140:141]
	s_add_i32 m0, s25, 0xc000
	ds_read_b128 v[184:187], v151
	ds_read_b128 v[188:191], v151 offset:1024
	ds_read_b128 v[192:195], v151 offset:2048
	ds_read_b128 v[196:199], v151 offset:3072
	ds_read_b128 v[200:203], v151 offset:4096
	ds_read_b128 v[206:209], v151 offset:5120
	ds_read_b128 v[210:213], v151 offset:6144
	ds_read_b128 v[214:217], v151 offset:7168
	global_load_lds_dwordx4 v[144:145], off
	v_lshl_add_u64 v[144:145], s[26:27], 0, v[142:143]
	s_add_i32 m0, s25, 0xe000
	s_nop 0
	global_load_lds_dwordx4 v[144:145], off
	s_waitcnt vmcnt(8)
	s_waitcnt lgkmcnt(0)
	s_barrier
	s_setprio 1
	s_waitcnt lgkmcnt(0)
	v_mfma_f32_16x16x32_bf16 v[126:129], v[152:155], v[184:187], v[126:129]
	v_mfma_f32_16x16x32_bf16 v[126:129], v[156:159], v[188:191], v[126:129]
	v_mfma_f32_16x16x32_bf16 v[122:125], v[160:163], v[184:187], v[122:125]
	v_mfma_f32_16x16x32_bf16 v[122:125], v[164:167], v[188:191], v[122:125]
	v_mfma_f32_16x16x32_bf16 v[106:109], v[160:163], v[192:195], v[106:109]
	v_mfma_f32_16x16x32_bf16 v[106:109], v[164:167], v[196:199], v[106:109]
	v_mfma_f32_16x16x32_bf16 v[110:113], v[152:155], v[192:195], v[110:113]
	v_mfma_f32_16x16x32_bf16 v[110:113], v[156:159], v[196:199], v[110:113]
	v_mfma_f32_16x16x32_bf16 v[98:101], v[152:155], v[200:203], v[98:101]
	v_mfma_f32_16x16x32_bf16 v[98:101], v[156:159], v[206:209], v[98:101]
	v_mfma_f32_16x16x32_bf16 v[90:93], v[160:163], v[200:203], v[90:93]
	v_mfma_f32_16x16x32_bf16 v[90:93], v[164:167], v[206:209], v[90:93]
	v_mfma_f32_16x16x32_bf16 v[74:77], v[160:163], v[210:213], v[74:77]
	v_mfma_f32_16x16x32_bf16 v[74:77], v[164:167], v[214:217], v[74:77]
	v_mfma_f32_16x16x32_bf16 v[82:85], v[152:155], v[210:213], v[82:85]
	v_mfma_f32_16x16x32_bf16 v[82:85], v[156:159], v[214:217], v[82:85]
	v_mfma_f32_16x16x32_bf16 v[118:121], v[168:171], v[184:187], v[118:121]
	v_mfma_f32_16x16x32_bf16 v[118:121], v[172:175], v[188:191], v[118:121]
	v_mfma_f32_16x16x32_bf16 v[114:117], v[176:179], v[184:187], v[114:117]
	v_mfma_f32_16x16x32_bf16 v[114:117], v[180:183], v[188:191], v[114:117]
	v_mfma_f32_16x16x32_bf16 v[94:97], v[176:179], v[192:195], v[94:97]
	v_mfma_f32_16x16x32_bf16 v[94:97], v[180:183], v[196:199], v[94:97]
	v_mfma_f32_16x16x32_bf16 v[102:105], v[168:171], v[192:195], v[102:105]
	v_mfma_f32_16x16x32_bf16 v[102:105], v[172:175], v[196:199], v[102:105]
	v_mfma_f32_16x16x32_bf16 v[86:89], v[168:171], v[200:203], v[86:89]
	v_mfma_f32_16x16x32_bf16 v[86:89], v[172:175], v[206:209], v[86:89]
	v_mfma_f32_16x16x32_bf16 v[78:81], v[176:179], v[200:203], v[78:81]
	v_mfma_f32_16x16x32_bf16 v[78:81], v[180:183], v[206:209], v[78:81]
	v_mfma_f32_16x16x32_bf16 v[66:69], v[176:179], v[210:213], v[66:69]
	v_mfma_f32_16x16x32_bf16 v[66:69], v[180:183], v[214:217], v[66:69]
	v_mfma_f32_16x16x32_bf16 v[70:73], v[168:171], v[210:213], v[70:73]
	v_mfma_f32_16x16x32_bf16 v[70:73], v[172:175], v[214:217], v[70:73]
	s_setprio 0
	s_barrier
	s_add_i32 s56, s48, s13
	v_lshl_add_u64 v[144:145], s[28:29], 0, v[132:133]
	s_mov_b32 m0, s56
	ds_read_b128 v[184:187], v151 offset:16384
	ds_read_b128 v[188:191], v151 offset:17408
	ds_read_b128 v[192:195], v151 offset:18432
	ds_read_b128 v[196:199], v151 offset:19456
	ds_read_b128 v[200:203], v151 offset:20480
	ds_read_b128 v[206:209], v151 offset:21504
	ds_read_b128 v[210:213], v151 offset:22528
	ds_read_b128 v[214:217], v151 offset:23552
	global_load_lds_dwordx4 v[144:145], off
	s_add_i32 m0, s56, 0x2000
	s_add_u32 s56, s28, 0x100000
	v_lshl_add_u64 v[218:219], s[28:29], 0, v[136:137]
	s_addc_u32 s57, s29, 0
	s_add_i32 s58, s49, s13
	global_load_lds_dwordx4 v[218:219], off
	v_lshl_add_u64 v[220:221], s[56:57], 0, v[132:133]
	s_mov_b32 m0, s58
	v_lshl_add_u64 v[222:223], s[30:31], 0, v[134:135]
	global_load_lds_dwordx4 v[220:221], off
	v_lshl_add_u64 v[220:221], s[56:57], 0, v[136:137]
	s_add_i32 m0, s58, 0x2000
	s_nop 0
	global_load_lds_dwordx4 v[220:221], off
	v_lshl_add_u64 v[220:221], s[30:31], 0, v[130:131]
	s_mov_b32 m0, s25
	s_nop 0
	global_load_lds_dwordx4 v[220:221], off
	s_mov_b32 m0, s39
	s_nop 0
	global_load_lds_dwordx4 v[222:223], off
	s_waitcnt vmcnt(8)
	s_waitcnt lgkmcnt(0)
	s_barrier
	s_setprio 1
	s_waitcnt lgkmcnt(0)
	v_mfma_f32_16x16x32_bf16 v[62:65], v[152:155], v[184:187], v[62:65]
	v_mfma_f32_16x16x32_bf16 v[62:65], v[156:159], v[188:191], v[62:65]
	v_mfma_f32_16x16x32_bf16 v[58:61], v[160:163], v[184:187], v[58:61]
	v_mfma_f32_16x16x32_bf16 v[58:61], v[164:167], v[188:191], v[58:61]
	v_mfma_f32_16x16x32_bf16 v[42:45], v[160:163], v[192:195], v[42:45]
	v_mfma_f32_16x16x32_bf16 v[42:45], v[164:167], v[196:199], v[42:45]
	v_mfma_f32_16x16x32_bf16 v[50:53], v[152:155], v[192:195], v[50:53]
	v_mfma_f32_16x16x32_bf16 v[50:53], v[156:159], v[196:199], v[50:53]
	v_mfma_f32_16x16x32_bf16 v[34:37], v[152:155], v[200:203], v[34:37]
	v_mfma_f32_16x16x32_bf16 v[34:37], v[156:159], v[206:209], v[34:37]
	v_mfma_f32_16x16x32_bf16 v[26:29], v[160:163], v[200:203], v[26:29]
	v_mfma_f32_16x16x32_bf16 v[26:29], v[164:167], v[206:209], v[26:29]
	v_mfma_f32_16x16x32_bf16 v[10:13], v[160:163], v[210:213], v[10:13]
	v_mfma_f32_16x16x32_bf16 v[10:13], v[164:167], v[214:217], v[10:13]
	v_mfma_f32_16x16x32_bf16 v[14:17], v[152:155], v[210:213], v[14:17]
	v_mfma_f32_16x16x32_bf16 v[14:17], v[156:159], v[214:217], v[14:17]
	v_mfma_f32_16x16x32_bf16 v[54:57], v[168:171], v[184:187], v[54:57]
	v_mfma_f32_16x16x32_bf16 v[54:57], v[172:175], v[188:191], v[54:57]
	v_mfma_f32_16x16x32_bf16 v[46:49], v[176:179], v[184:187], v[46:49]
	v_mfma_f32_16x16x32_bf16 v[46:49], v[180:183], v[188:191], v[46:49]
	v_mfma_f32_16x16x32_bf16 v[30:33], v[176:179], v[192:195], v[30:33]
	v_mfma_f32_16x16x32_bf16 v[30:33], v[180:183], v[196:199], v[30:33]
	v_mfma_f32_16x16x32_bf16 v[38:41], v[168:171], v[192:195], v[38:41]
	v_mfma_f32_16x16x32_bf16 v[38:41], v[172:175], v[196:199], v[38:41]
	v_mfma_f32_16x16x32_bf16 v[22:25], v[168:171], v[200:203], v[22:25]
	v_mfma_f32_16x16x32_bf16 v[22:25], v[172:175], v[206:209], v[22:25]
	v_mfma_f32_16x16x32_bf16 v[18:21], v[176:179], v[200:203], v[18:21]
	v_mfma_f32_16x16x32_bf16 v[18:21], v[180:183], v[206:209], v[18:21]
	v_mfma_f32_16x16x32_bf16 v[2:5], v[176:179], v[210:213], v[2:5]
	v_mfma_f32_16x16x32_bf16 v[2:5], v[180:183], v[214:217], v[2:5]
	v_mfma_f32_16x16x32_bf16 v[6:9], v[168:171], v[210:213], v[6:9]
	v_mfma_f32_16x16x32_bf16 v[6:9], v[172:175], v[214:217], v[6:9]
	s_setprio 0
	s_barrier
	s_add_i32 s56, 0, 0x18000
	s_add_i32 s57, 0, 0x1c000
	v_add_u32_e32 v164, s56, v147
	v_add_u32_e32 v180, s57, v147
	ds_read_b128 v[152:155], v164
	ds_read_b128 v[156:159], v164 offset:1024
	ds_read_b128 v[160:163], v164 offset:2048
	ds_read_b128 v[164:167], v164 offset:3072
	ds_read_b128 v[168:171], v180
	ds_read_b128 v[172:175], v180 offset:1024
	ds_read_b128 v[176:179], v180 offset:2048
	ds_read_b128 v[180:183], v180 offset:3072
	s_add_u32 s30, s30, 0x100000
	s_addc_u32 s31, s31, 0
	s_mov_b32 m0, s40
	v_lshl_add_u64 v[224:225], s[30:31], 0, v[130:131]
	ds_read_b128 v[184:187], v151 offset:32768
	ds_read_b128 v[188:191], v151 offset:33792
	ds_read_b128 v[192:195], v151 offset:34816
	ds_read_b128 v[196:199], v151 offset:35840
	ds_read_b128 v[200:203], v151 offset:36864
	ds_read_b128 v[206:209], v151 offset:37888
	ds_read_b128 v[210:213], v151 offset:38912
	ds_read_b128 v[214:217], v151 offset:39936
	global_load_lds_dwordx4 v[224:225], off
	v_lshl_add_u64 v[224:225], s[30:31], 0, v[134:135]
	s_mov_b32 m0, s41
	s_nop 0
	global_load_lds_dwordx4 v[224:225], off
	s_waitcnt vmcnt(8)
	s_waitcnt lgkmcnt(0)
	s_barrier
	s_setprio 1
	s_waitcnt lgkmcnt(0)
	v_mfma_f32_16x16x32_bf16 v[126:129], v[152:155], v[184:187], v[126:129]
	v_mfma_f32_16x16x32_bf16 v[126:129], v[156:159], v[188:191], v[126:129]
	v_mfma_f32_16x16x32_bf16 v[122:125], v[160:163], v[184:187], v[122:125]
	v_mfma_f32_16x16x32_bf16 v[122:125], v[164:167], v[188:191], v[122:125]
	v_mfma_f32_16x16x32_bf16 v[106:109], v[160:163], v[192:195], v[106:109]
	v_mfma_f32_16x16x32_bf16 v[106:109], v[164:167], v[196:199], v[106:109]
	v_mfma_f32_16x16x32_bf16 v[110:113], v[152:155], v[192:195], v[110:113]
	v_mfma_f32_16x16x32_bf16 v[110:113], v[156:159], v[196:199], v[110:113]
	v_mfma_f32_16x16x32_bf16 v[98:101], v[152:155], v[200:203], v[98:101]
	v_mfma_f32_16x16x32_bf16 v[98:101], v[156:159], v[206:209], v[98:101]
	v_mfma_f32_16x16x32_bf16 v[90:93], v[160:163], v[200:203], v[90:93]
	v_mfma_f32_16x16x32_bf16 v[90:93], v[164:167], v[206:209], v[90:93]
	v_mfma_f32_16x16x32_bf16 v[74:77], v[160:163], v[210:213], v[74:77]
	v_mfma_f32_16x16x32_bf16 v[74:77], v[164:167], v[214:217], v[74:77]
	v_mfma_f32_16x16x32_bf16 v[82:85], v[152:155], v[210:213], v[82:85]
	v_mfma_f32_16x16x32_bf16 v[82:85], v[156:159], v[214:217], v[82:85]
	v_mfma_f32_16x16x32_bf16 v[118:121], v[168:171], v[184:187], v[118:121]
	v_mfma_f32_16x16x32_bf16 v[118:121], v[172:175], v[188:191], v[118:121]
	v_mfma_f32_16x16x32_bf16 v[114:117], v[176:179], v[184:187], v[114:117]
	v_mfma_f32_16x16x32_bf16 v[114:117], v[180:183], v[188:191], v[114:117]
	v_mfma_f32_16x16x32_bf16 v[94:97], v[176:179], v[192:195], v[94:97]
	v_mfma_f32_16x16x32_bf16 v[94:97], v[180:183], v[196:199], v[94:97]
	v_mfma_f32_16x16x32_bf16 v[102:105], v[168:171], v[192:195], v[102:105]
	v_mfma_f32_16x16x32_bf16 v[102:105], v[172:175], v[196:199], v[102:105]
	v_mfma_f32_16x16x32_bf16 v[86:89], v[168:171], v[200:203], v[86:89]
	v_mfma_f32_16x16x32_bf16 v[86:89], v[172:175], v[206:209], v[86:89]
	v_mfma_f32_16x16x32_bf16 v[78:81], v[176:179], v[200:203], v[78:81]
	v_mfma_f32_16x16x32_bf16 v[78:81], v[180:183], v[206:209], v[78:81]
	v_mfma_f32_16x16x32_bf16 v[66:69], v[176:179], v[210:213], v[66:69]
	v_mfma_f32_16x16x32_bf16 v[66:69], v[180:183], v[214:217], v[66:69]
	v_mfma_f32_16x16x32_bf16 v[70:73], v[168:171], v[210:213], v[70:73]
	v_mfma_f32_16x16x32_bf16 v[70:73], v[172:175], v[214:217], v[70:73]
	s_setprio 0
	s_barrier
	s_add_i32 s30, s56, s13
	v_lshl_add_u64 v[144:145], v[144:145], 0, s[8:9]
	s_mov_b32 m0, s30
	ds_read_b128 v[184:187], v151 offset:49152
	ds_read_b128 v[188:191], v151 offset:50176
	ds_read_b128 v[192:195], v151 offset:51200
	ds_read_b128 v[196:199], v151 offset:52224
	ds_read_b128 v[200:203], v151 offset:53248
	ds_read_b128 v[206:209], v151 offset:54272
	ds_read_b128 v[210:213], v151 offset:55296
	ds_read_b128 v[214:217], v151 offset:56320
	global_load_lds_dwordx4 v[144:145], off
	s_add_i32 m0, s30, 0x2000
	s_add_u32 s28, s28, 0x100080
	v_lshl_add_u64 v[144:145], v[218:219], 0, s[8:9]
	s_addc_u32 s29, s29, 0
	s_add_i32 s30, s57, s13
	global_load_lds_dwordx4 v[144:145], off
	v_lshl_add_u64 v[144:145], s[28:29], 0, v[132:133]
	s_mov_b32 m0, s30
	s_nop 0
	global_load_lds_dwordx4 v[144:145], off
	v_lshl_add_u64 v[144:145], s[28:29], 0, v[136:137]
	s_add_i32 m0, s30, 0x2000
	s_nop 0
	global_load_lds_dwordx4 v[144:145], off
	v_lshl_add_u64 v[144:145], v[220:221], 0, s[8:9]
	s_mov_b32 m0, s42
	s_nop 0
	global_load_lds_dwordx4 v[144:145], off
	v_lshl_add_u64 v[144:145], v[222:223], 0, s[8:9]
	s_mov_b32 m0, s43
	s_nop 0
	global_load_lds_dwordx4 v[144:145], off
	s_waitcnt vmcnt(8)
	s_waitcnt lgkmcnt(0)
	s_barrier
	s_setprio 1
	s_waitcnt lgkmcnt(0)
	v_mfma_f32_16x16x32_bf16 v[62:65], v[152:155], v[184:187], v[62:65]
	v_mfma_f32_16x16x32_bf16 v[62:65], v[156:159], v[188:191], v[62:65]
	v_mfma_f32_16x16x32_bf16 v[58:61], v[160:163], v[184:187], v[58:61]
	v_mfma_f32_16x16x32_bf16 v[58:61], v[164:167], v[188:191], v[58:61]
	v_mfma_f32_16x16x32_bf16 v[42:45], v[160:163], v[192:195], v[42:45]
	v_mfma_f32_16x16x32_bf16 v[42:45], v[164:167], v[196:199], v[42:45]
	v_mfma_f32_16x16x32_bf16 v[50:53], v[152:155], v[192:195], v[50:53]
	v_mfma_f32_16x16x32_bf16 v[50:53], v[156:159], v[196:199], v[50:53]
	v_mfma_f32_16x16x32_bf16 v[34:37], v[152:155], v[200:203], v[34:37]
	v_mfma_f32_16x16x32_bf16 v[34:37], v[156:159], v[206:209], v[34:37]
	v_mfma_f32_16x16x32_bf16 v[26:29], v[160:163], v[200:203], v[26:29]
	v_mfma_f32_16x16x32_bf16 v[26:29], v[164:167], v[206:209], v[26:29]
	v_mfma_f32_16x16x32_bf16 v[10:13], v[160:163], v[210:213], v[10:13]
	v_mfma_f32_16x16x32_bf16 v[10:13], v[164:167], v[214:217], v[10:13]
	v_mfma_f32_16x16x32_bf16 v[14:17], v[152:155], v[210:213], v[14:17]
	v_mfma_f32_16x16x32_bf16 v[14:17], v[156:159], v[214:217], v[14:17]
	v_mfma_f32_16x16x32_bf16 v[54:57], v[168:171], v[184:187], v[54:57]
	v_mfma_f32_16x16x32_bf16 v[54:57], v[172:175], v[188:191], v[54:57]
	v_mfma_f32_16x16x32_bf16 v[46:49], v[176:179], v[184:187], v[46:49]
	v_mfma_f32_16x16x32_bf16 v[46:49], v[180:183], v[188:191], v[46:49]
	v_mfma_f32_16x16x32_bf16 v[30:33], v[176:179], v[192:195], v[30:33]
	v_mfma_f32_16x16x32_bf16 v[30:33], v[180:183], v[196:199], v[30:33]
	v_mfma_f32_16x16x32_bf16 v[38:41], v[168:171], v[192:195], v[38:41]
	v_mfma_f32_16x16x32_bf16 v[38:41], v[172:175], v[196:199], v[38:41]
	v_mfma_f32_16x16x32_bf16 v[22:25], v[168:171], v[200:203], v[22:25]
	v_mfma_f32_16x16x32_bf16 v[22:25], v[172:175], v[206:209], v[22:25]
	v_mfma_f32_16x16x32_bf16 v[18:21], v[176:179], v[200:203], v[18:21]
	v_mfma_f32_16x16x32_bf16 v[18:21], v[180:183], v[206:209], v[18:21]
	v_mfma_f32_16x16x32_bf16 v[2:5], v[176:179], v[210:213], v[2:5]
	v_mfma_f32_16x16x32_bf16 v[2:5], v[180:183], v[214:217], v[2:5]
	v_mfma_f32_16x16x32_bf16 v[6:9], v[168:171], v[210:213], v[6:9]
	v_mfma_f32_16x16x32_bf16 v[6:9], v[172:175], v[214:217], v[6:9]
	s_setprio 0
	s_barrier
	s_add_i32 s55, s55, 2
	s_add_u32 s26, s26, 0x100
	s_addc_u32 s27, s27, 0
	s_add_u32 s53, s53, 0x100
	s_addc_u32 s54, s54, 0
	s_cmp_gt_u32 s55, 61
	s_cbranch_scc0 .LBB0_1644
	s_and_b64 vcc, exec, s[10:11]
	s_cbranch_vccz .LBB0_1647
	s_barrier

.LBB0_1749:
	s_waitcnt lgkmcnt(0)
	ds_read_b128 v[144:147], v154
	ds_read_b128 v[158:161], v154 offset:1024
	ds_read_b128 v[162:165], v154 offset:2048
	ds_read_b128 v[166:169], v154 offset:3072
	ds_read_b128 v[170:173], v155
	ds_read_b128 v[174:177], v155 offset:1024
	ds_read_b128 v[178:181], v155 offset:2048
	ds_read_b128 v[182:185], v155 offset:3072
	s_add_i32 s89, s46, 2
	s_add_u32 s47, s44, 0xffd50080
	s_addc_u32 s48, s45, -1
	s_cmp_eq_u32 s39, s46
	s_cselect_b32 s46, s42, s87
	s_cselect_b32 s49, s41, s48
	s_cselect_b32 s48, s40, s47
	s_cselect_b32 s47, s43, s88
	v_lshl_add_u64 v[148:149], s[44:45], 0, v[140:141]
	s_add_i32 m0, s58, 0xc000
	ds_read_b128 v[186:189], v156
	ds_read_b128 v[190:193], v156 offset:1024
	ds_read_b128 v[194:197], v156 offset:2048
	ds_read_b128 v[198:201], v156 offset:3072
	ds_read_b128 v[202:205], v156 offset:4096
	ds_read_b128 v[206:209], v156 offset:5120
	ds_read_b128 v[210:213], v156 offset:6144
	ds_read_b128 v[214:217], v156 offset:7168
	global_load_lds_dwordx4 v[148:149], off
	v_lshl_add_u64 v[148:149], s[44:45], 0, v[142:143]
	s_add_i32 m0, s58, 0xe000
	s_nop 0
	global_load_lds_dwordx4 v[148:149], off
	s_waitcnt vmcnt(8)
	s_waitcnt lgkmcnt(0)
	s_barrier
	s_setprio 1
	s_waitcnt lgkmcnt(0)
	v_mfma_f32_16x16x32_bf16 v[124:127], v[144:147], v[186:189], v[124:127]
	v_mfma_f32_16x16x32_bf16 v[124:127], v[158:161], v[190:193], v[124:127]
	v_mfma_f32_16x16x32_bf16 v[120:123], v[162:165], v[186:189], v[120:123]
	v_mfma_f32_16x16x32_bf16 v[120:123], v[166:169], v[190:193], v[120:123]
	v_mfma_f32_16x16x32_bf16 v[112:115], v[162:165], v[194:197], v[112:115]
	v_mfma_f32_16x16x32_bf16 v[112:115], v[166:169], v[198:201], v[112:115]
	v_mfma_f32_16x16x32_bf16 v[116:119], v[144:147], v[194:197], v[116:119]
	v_mfma_f32_16x16x32_bf16 v[116:119], v[158:161], v[198:201], v[116:119]
	v_mfma_f32_16x16x32_bf16 v[108:111], v[144:147], v[202:205], v[108:111]
	v_mfma_f32_16x16x32_bf16 v[108:111], v[158:161], v[206:209], v[108:111]
	v_mfma_f32_16x16x32_bf16 v[104:107], v[162:165], v[202:205], v[104:107]
	v_mfma_f32_16x16x32_bf16 v[104:107], v[166:169], v[206:209], v[104:107]
	v_mfma_f32_16x16x32_bf16 v[96:99], v[162:165], v[210:213], v[96:99]
	v_mfma_f32_16x16x32_bf16 v[96:99], v[166:169], v[214:217], v[96:99]
	v_mfma_f32_16x16x32_bf16 v[100:103], v[144:147], v[210:213], v[100:103]
	v_mfma_f32_16x16x32_bf16 v[100:103], v[158:161], v[214:217], v[100:103]
	v_mfma_f32_16x16x32_bf16 v[92:95], v[170:173], v[186:189], v[92:95]
	v_mfma_f32_16x16x32_bf16 v[92:95], v[174:177], v[190:193], v[92:95]
	v_mfma_f32_16x16x32_bf16 v[88:91], v[178:181], v[186:189], v[88:91]
	v_mfma_f32_16x16x32_bf16 v[88:91], v[182:185], v[190:193], v[88:91]
	v_mfma_f32_16x16x32_bf16 v[80:83], v[178:181], v[194:197], v[80:83]
	v_mfma_f32_16x16x32_bf16 v[80:83], v[182:185], v[198:201], v[80:83]
	v_mfma_f32_16x16x32_bf16 v[84:87], v[170:173], v[194:197], v[84:87]
	v_mfma_f32_16x16x32_bf16 v[84:87], v[174:177], v[198:201], v[84:87]
	v_mfma_f32_16x16x32_bf16 v[76:79], v[170:173], v[202:205], v[76:79]
	v_mfma_f32_16x16x32_bf16 v[76:79], v[174:177], v[206:209], v[76:79]
	v_mfma_f32_16x16x32_bf16 v[72:75], v[178:181], v[202:205], v[72:75]
	v_mfma_f32_16x16x32_bf16 v[72:75], v[182:185], v[206:209], v[72:75]
	v_mfma_f32_16x16x32_bf16 v[64:67], v[178:181], v[210:213], v[64:67]
	v_mfma_f32_16x16x32_bf16 v[64:67], v[182:185], v[214:217], v[64:67]
	v_mfma_f32_16x16x32_bf16 v[68:71], v[170:173], v[210:213], v[68:71]
	v_mfma_f32_16x16x32_bf16 v[68:71], v[174:177], v[214:217], v[68:71]
	s_setprio 0
	s_barrier
	s_add_i32 s90, s76, s53
	v_lshl_add_u64 v[148:149], s[46:47], 0, v[130:131]
	s_mov_b32 m0, s90
	ds_read_b128 v[186:189], v156 offset:16384
	ds_read_b128 v[190:193], v156 offset:17408
	ds_read_b128 v[194:197], v156 offset:18432
	ds_read_b128 v[198:201], v156 offset:19456
	ds_read_b128 v[202:205], v156 offset:20480
	ds_read_b128 v[206:209], v156 offset:21504
	ds_read_b128 v[210:213], v156 offset:22528
	ds_read_b128 v[214:217], v156 offset:23552
	global_load_lds_dwordx4 v[148:149], off
	s_add_i32 m0, s90, 0x2000
	s_add_u32 s90, s46, 0x2b0000
	v_lshl_add_u64 v[218:219], s[46:47], 0, v[134:135]
	s_addc_u32 s91, s47, 0
	s_add_i32 s92, s77, s53
	global_load_lds_dwordx4 v[218:219], off
	v_lshl_add_u64 v[220:221], s[90:91], 0, v[130:131]
	s_mov_b32 m0, s92
	v_lshl_add_u64 v[222:223], s[48:49], 0, v[132:133]
	global_load_lds_dwordx4 v[220:221], off
	v_lshl_add_u64 v[220:221], s[90:91], 0, v[134:135]
	s_add_i32 m0, s92, 0x2000
	s_nop 0
	global_load_lds_dwordx4 v[220:221], off
	v_lshl_add_u64 v[220:221], s[48:49], 0, v[128:129]
	s_mov_b32 m0, s58
	s_nop 0
	global_load_lds_dwordx4 v[220:221], off
	s_mov_b32 m0, s60
	s_nop 0
	global_load_lds_dwordx4 v[222:223], off
	s_waitcnt vmcnt(8)
	s_waitcnt lgkmcnt(0)
	s_barrier
	s_setprio 1
	s_waitcnt lgkmcnt(0)
	v_mfma_f32_16x16x32_bf16 v[60:63], v[144:147], v[186:189], v[60:63]
	v_mfma_f32_16x16x32_bf16 v[60:63], v[158:161], v[190:193], v[60:63]
	v_mfma_f32_16x16x32_bf16 v[56:59], v[162:165], v[186:189], v[56:59]
	v_mfma_f32_16x16x32_bf16 v[56:59], v[166:169], v[190:193], v[56:59]
	v_mfma_f32_16x16x32_bf16 v[48:51], v[162:165], v[194:197], v[48:51]
	v_mfma_f32_16x16x32_bf16 v[48:51], v[166:169], v[198:201], v[48:51]
	v_mfma_f32_16x16x32_bf16 v[52:55], v[144:147], v[194:197], v[52:55]
	v_mfma_f32_16x16x32_bf16 v[52:55], v[158:161], v[198:201], v[52:55]
	v_mfma_f32_16x16x32_bf16 v[44:47], v[144:147], v[202:205], v[44:47]
	v_mfma_f32_16x16x32_bf16 v[44:47], v[158:161], v[206:209], v[44:47]
	v_mfma_f32_16x16x32_bf16 v[40:43], v[162:165], v[202:205], v[40:43]
	v_mfma_f32_16x16x32_bf16 v[40:43], v[166:169], v[206:209], v[40:43]
	v_mfma_f32_16x16x32_bf16 v[32:35], v[162:165], v[210:213], v[32:35]
	v_mfma_f32_16x16x32_bf16 v[32:35], v[166:169], v[214:217], v[32:35]
	v_mfma_f32_16x16x32_bf16 v[36:39], v[144:147], v[210:213], v[36:39]
	v_mfma_f32_16x16x32_bf16 v[36:39], v[158:161], v[214:217], v[36:39]
	v_mfma_f32_16x16x32_bf16 v[28:31], v[170:173], v[186:189], v[28:31]
	v_mfma_f32_16x16x32_bf16 v[28:31], v[174:177], v[190:193], v[28:31]
	v_mfma_f32_16x16x32_bf16 v[24:27], v[178:181], v[186:189], v[24:27]
	v_mfma_f32_16x16x32_bf16 v[24:27], v[182:185], v[190:193], v[24:27]
	v_mfma_f32_16x16x32_bf16 v[16:19], v[178:181], v[194:197], v[16:19]
	v_mfma_f32_16x16x32_bf16 v[16:19], v[182:185], v[198:201], v[16:19]
	v_mfma_f32_16x16x32_bf16 v[20:23], v[170:173], v[194:197], v[20:23]
	v_mfma_f32_16x16x32_bf16 v[20:23], v[174:177], v[198:201], v[20:23]
	v_mfma_f32_16x16x32_bf16 v[12:15], v[170:173], v[202:205], v[12:15]
	v_mfma_f32_16x16x32_bf16 v[12:15], v[174:177], v[206:209], v[12:15]
	v_mfma_f32_16x16x32_bf16 v[8:11], v[178:181], v[202:205], v[8:11]
	v_mfma_f32_16x16x32_bf16 v[8:11], v[182:185], v[206:209], v[8:11]
	v_mfma_f32_16x16x32_bf16 v[0:3], v[178:181], v[210:213], v[0:3]
	v_mfma_f32_16x16x32_bf16 v[0:3], v[182:185], v[214:217], v[0:3]
	v_mfma_f32_16x16x32_bf16 v[4:7], v[170:173], v[210:213], v[4:7]
	v_mfma_f32_16x16x32_bf16 v[4:7], v[174:177], v[214:217], v[4:7]
	s_setprio 0
	s_barrier
	s_add_i32 s90, 0, 0x18000
	s_add_i32 s91, 0, 0x1c000
	v_add_u32_e32 v166, s90, v139
	v_add_u32_e32 v182, s91, v139
	ds_read_b128 v[144:147], v166
	ds_read_b128 v[158:161], v166 offset:1024
	ds_read_b128 v[162:165], v166 offset:2048
	ds_read_b128 v[166:169], v166 offset:3072
	ds_read_b128 v[170:173], v182
	ds_read_b128 v[174:177], v182 offset:1024
	ds_read_b128 v[178:181], v182 offset:2048
	ds_read_b128 v[182:185], v182 offset:3072
	s_add_u32 s48, s48, 0x2b0000
	s_addc_u32 s49, s49, 0
	s_mov_b32 m0, s61
	v_lshl_add_u64 v[224:225], s[48:49], 0, v[128:129]
	ds_read_b128 v[186:189], v156 offset:32768
	ds_read_b128 v[190:193], v156 offset:33792
	ds_read_b128 v[194:197], v156 offset:34816
	ds_read_b128 v[198:201], v156 offset:35840
	ds_read_b128 v[202:205], v156 offset:36864
	ds_read_b128 v[206:209], v156 offset:37888
	ds_read_b128 v[210:213], v156 offset:38912
	ds_read_b128 v[214:217], v156 offset:39936
	global_load_lds_dwordx4 v[224:225], off
	v_lshl_add_u64 v[224:225], s[48:49], 0, v[132:133]
	s_mov_b32 m0, s62
	s_nop 0
	global_load_lds_dwordx4 v[224:225], off
	s_waitcnt vmcnt(8)
	s_waitcnt lgkmcnt(0)
	s_barrier
	s_setprio 1
	s_waitcnt lgkmcnt(0)
	v_mfma_f32_16x16x32_bf16 v[124:127], v[144:147], v[186:189], v[124:127]
	v_mfma_f32_16x16x32_bf16 v[124:127], v[158:161], v[190:193], v[124:127]
	v_mfma_f32_16x16x32_bf16 v[120:123], v[162:165], v[186:189], v[120:123]
	v_mfma_f32_16x16x32_bf16 v[120:123], v[166:169], v[190:193], v[120:123]
	v_mfma_f32_16x16x32_bf16 v[112:115], v[162:165], v[194:197], v[112:115]
	v_mfma_f32_16x16x32_bf16 v[112:115], v[166:169], v[198:201], v[112:115]
	v_mfma_f32_16x16x32_bf16 v[116:119], v[144:147], v[194:197], v[116:119]
	v_mfma_f32_16x16x32_bf16 v[116:119], v[158:161], v[198:201], v[116:119]
	v_mfma_f32_16x16x32_bf16 v[108:111], v[144:147], v[202:205], v[108:111]
	v_mfma_f32_16x16x32_bf16 v[108:111], v[158:161], v[206:209], v[108:111]
	v_mfma_f32_16x16x32_bf16 v[104:107], v[162:165], v[202:205], v[104:107]
	v_mfma_f32_16x16x32_bf16 v[104:107], v[166:169], v[206:209], v[104:107]
	v_mfma_f32_16x16x32_bf16 v[96:99], v[162:165], v[210:213], v[96:99]
	v_mfma_f32_16x16x32_bf16 v[96:99], v[166:169], v[214:217], v[96:99]
	v_mfma_f32_16x16x32_bf16 v[100:103], v[144:147], v[210:213], v[100:103]
	v_mfma_f32_16x16x32_bf16 v[100:103], v[158:161], v[214:217], v[100:103]
	v_mfma_f32_16x16x32_bf16 v[92:95], v[170:173], v[186:189], v[92:95]
	v_mfma_f32_16x16x32_bf16 v[92:95], v[174:177], v[190:193], v[92:95]
	v_mfma_f32_16x16x32_bf16 v[88:91], v[178:181], v[186:189], v[88:91]
	v_mfma_f32_16x16x32_bf16 v[88:91], v[182:185], v[190:193], v[88:91]
	v_mfma_f32_16x16x32_bf16 v[80:83], v[178:181], v[194:197], v[80:83]
	v_mfma_f32_16x16x32_bf16 v[80:83], v[182:185], v[198:201], v[80:83]
	v_mfma_f32_16x16x32_bf16 v[84:87], v[170:173], v[194:197], v[84:87]
	v_mfma_f32_16x16x32_bf16 v[84:87], v[174:177], v[198:201], v[84:87]
	v_mfma_f32_16x16x32_bf16 v[76:79], v[170:173], v[202:205], v[76:79]
	v_mfma_f32_16x16x32_bf16 v[76:79], v[174:177], v[206:209], v[76:79]
	v_mfma_f32_16x16x32_bf16 v[72:75], v[178:181], v[202:205], v[72:75]
	v_mfma_f32_16x16x32_bf16 v[72:75], v[182:185], v[206:209], v[72:75]
	v_mfma_f32_16x16x32_bf16 v[64:67], v[178:181], v[210:213], v[64:67]
	v_mfma_f32_16x16x32_bf16 v[64:67], v[182:185], v[214:217], v[64:67]
	v_mfma_f32_16x16x32_bf16 v[68:71], v[170:173], v[210:213], v[68:71]
	v_mfma_f32_16x16x32_bf16 v[68:71], v[174:177], v[214:217], v[68:71]
	s_setprio 0
	s_barrier
	s_add_i32 s48, s90, s53
	v_lshl_add_u64 v[148:149], v[148:149], 0, s[22:23]
	s_mov_b32 m0, s48
	ds_read_b128 v[186:189], v156 offset:49152
	ds_read_b128 v[190:193], v156 offset:50176
	ds_read_b128 v[194:197], v156 offset:51200
	ds_read_b128 v[198:201], v156 offset:52224
	ds_read_b128 v[202:205], v156 offset:53248
	ds_read_b128 v[206:209], v156 offset:54272
	ds_read_b128 v[210:213], v156 offset:55296
	ds_read_b128 v[214:217], v156 offset:56320
	global_load_lds_dwordx4 v[148:149], off
	s_add_i32 m0, s48, 0x2000
	s_add_u32 s46, s46, 0x2b0080
	v_lshl_add_u64 v[148:149], v[218:219], 0, s[22:23]
	s_addc_u32 s47, s47, 0
	s_add_i32 s48, s91, s53
	global_load_lds_dwordx4 v[148:149], off
	v_lshl_add_u64 v[148:149], s[46:47], 0, v[130:131]
	s_mov_b32 m0, s48
	s_nop 0
	global_load_lds_dwordx4 v[148:149], off
	v_lshl_add_u64 v[148:149], s[46:47], 0, v[134:135]
	s_add_i32 m0, s48, 0x2000
	s_nop 0
	global_load_lds_dwordx4 v[148:149], off
	v_lshl_add_u64 v[148:149], v[220:221], 0, s[22:23]
	s_mov_b32 m0, s64
	s_nop 0
	global_load_lds_dwordx4 v[148:149], off
	v_lshl_add_u64 v[148:149], v[222:223], 0, s[22:23]
	s_mov_b32 m0, s65
	s_nop 0
	global_load_lds_dwordx4 v[148:149], off
	s_waitcnt vmcnt(8)
	s_waitcnt lgkmcnt(0)
	s_barrier
	s_setprio 1
	s_waitcnt lgkmcnt(0)
	v_mfma_f32_16x16x32_bf16 v[60:63], v[144:147], v[186:189], v[60:63]
	v_mfma_f32_16x16x32_bf16 v[60:63], v[158:161], v[190:193], v[60:63]
	v_mfma_f32_16x16x32_bf16 v[56:59], v[162:165], v[186:189], v[56:59]
	v_mfma_f32_16x16x32_bf16 v[56:59], v[166:169], v[190:193], v[56:59]
	v_mfma_f32_16x16x32_bf16 v[48:51], v[162:165], v[194:197], v[48:51]
	v_mfma_f32_16x16x32_bf16 v[48:51], v[166:169], v[198:201], v[48:51]
	v_mfma_f32_16x16x32_bf16 v[52:55], v[144:147], v[194:197], v[52:55]
	v_mfma_f32_16x16x32_bf16 v[52:55], v[158:161], v[198:201], v[52:55]
	v_mfma_f32_16x16x32_bf16 v[44:47], v[144:147], v[202:205], v[44:47]
	v_mfma_f32_16x16x32_bf16 v[44:47], v[158:161], v[206:209], v[44:47]
	v_mfma_f32_16x16x32_bf16 v[40:43], v[162:165], v[202:205], v[40:43]
	v_mfma_f32_16x16x32_bf16 v[40:43], v[166:169], v[206:209], v[40:43]
	v_mfma_f32_16x16x32_bf16 v[32:35], v[162:165], v[210:213], v[32:35]
	v_mfma_f32_16x16x32_bf16 v[32:35], v[166:169], v[214:217], v[32:35]
	v_mfma_f32_16x16x32_bf16 v[36:39], v[144:147], v[210:213], v[36:39]
	v_mfma_f32_16x16x32_bf16 v[36:39], v[158:161], v[214:217], v[36:39]
	v_mfma_f32_16x16x32_bf16 v[28:31], v[170:173], v[186:189], v[28:31]
	v_mfma_f32_16x16x32_bf16 v[28:31], v[174:177], v[190:193], v[28:31]
	v_mfma_f32_16x16x32_bf16 v[24:27], v[178:181], v[186:189], v[24:27]
	v_mfma_f32_16x16x32_bf16 v[24:27], v[182:185], v[190:193], v[24:27]
	v_mfma_f32_16x16x32_bf16 v[16:19], v[178:181], v[194:197], v[16:19]
	v_mfma_f32_16x16x32_bf16 v[16:19], v[182:185], v[198:201], v[16:19]
	v_mfma_f32_16x16x32_bf16 v[20:23], v[170:173], v[194:197], v[20:23]
	v_mfma_f32_16x16x32_bf16 v[20:23], v[174:177], v[198:201], v[20:23]
	v_mfma_f32_16x16x32_bf16 v[12:15], v[170:173], v[202:205], v[12:15]
	v_mfma_f32_16x16x32_bf16 v[12:15], v[174:177], v[206:209], v[12:15]
	v_mfma_f32_16x16x32_bf16 v[8:11], v[178:181], v[202:205], v[8:11]
	v_mfma_f32_16x16x32_bf16 v[8:11], v[182:185], v[206:209], v[8:11]
	v_mfma_f32_16x16x32_bf16 v[0:3], v[178:181], v[210:213], v[0:3]
	v_mfma_f32_16x16x32_bf16 v[0:3], v[182:185], v[214:217], v[0:3]
	v_mfma_f32_16x16x32_bf16 v[4:7], v[170:173], v[210:213], v[4:7]
	v_mfma_f32_16x16x32_bf16 v[4:7], v[174:177], v[214:217], v[4:7]
	s_setprio 0
	s_barrier
	s_add_u32 s44, s44, 0x100
	s_addc_u32 s45, s45, 0
	s_add_u32 s87, s87, 0x100
	s_addc_u32 s88, s88, 0
	s_cmp_ge_i32 s89, s86
	s_mov_b32 s46, s89
	s_cbranch_scc0 .LBB0_1749
	s_and_b64 vcc, exec, s[24:25]
	s_cbranch_vccz .LBB0_1752
